# removed the back-to-back s_setprio 0/1 flip between the two 16-MFMA groups of each compute segment (40 sites)
# speedup vs baseline: 1.0200x; 1.0026x over previous
; #define PG8_STAGE(bufoff, gbase, voff) do { _Pragma("unroll") for (int _i = 0; _i < 2; ++_i) \
;         __builtin_amdgcn_global_load_lds((const unsigned*)((const char*)(gbase) + (voff)[_i]), (PG8_LAS unsigned*)(lds + (bufoff) + ldsw + _i * 8192), 16, 0, 0); } while (0)
; #define PG8_LDA(dst, b, h) do { _Pragma("unroll") for (int m = 0; m < 4; ++m) _Pragma("unroll") for (int k = 0; k < 2; ++k) dst[m][k] = *(const PG8_LAS bf16x8*)(lds + PG8_SA(b, h) + aoff + m * 2048 + k * 1024); } while (0)
; #define PG8_LDB(dst, b, h) do { _Pragma("unroll") for (int n = 0; n < 2; ++n) _Pragma("unroll") for (int k = 0; k < 2; ++k) dst[n][k] = *(const PG8_LAS bf16x8*)(lds + PG8_SB(b, h) + boff + n * 2048 + k * 1024); } while (0)
; #define PG8_MMA(ai, bj, At, Bt) do { __builtin_amdgcn_s_setprio(1); _Pragma("unroll") for (int m = 0; m < 4; ++m) _Pragma("unroll") for (int n = 0; n < 2; ++n) _Pragma("unroll") for (int k = 0; k < 2; ++k) \
;         acc[ai][bj][m][n] = __builtin_amdgcn_mfma_f32_16x16x32_bf16(Bt[n][k], At[m][k], acc[ai][bj][m][n], 0, 0, 0); __builtin_amdgcn_s_setprio(0); } while (0)
; #define PG8_WAIT_V(n) asm volatile("s_waitcnt vmcnt(" #n ")" ::: "memory")
; #define PG8_WAIT_L(n) asm volatile("s_waitcnt lgkmcnt(" #n ")" ::: "memory")
; #define PG8_BAR __builtin_amdgcn_s_barrier()
; #define PG8_SCHED __builtin_amdgcn_sched_barrier(0)
; template <class Epi, class Sched, bool ALIGN_EPI = false, bool SP2 = false>
; __device__ __forceinline__ void gemm_phase(PG8_LAS unsigned char* lds, const Gemm g, const Sched& S, const Epi& E) {
;     ...
;             const bool last = (t == nt - 2);
;             const char* a1 = cA + (size_t)(t + 1) * kstep;
;             const char* a2 = last ? nA : cA + (size_t)(t + 2) * kstep; const char* b2 = last ? nB : cB + (size_t)(t + 2) * kstep;
;             const char* a3 = a2 + kstep; const char* b3 = b2 + kstep;
;     ...
;             PG8_LDB(B0, 0, 0); PG8_LDB(B1, 0, 1); PG8_SCHED; PG8_LDA(At, 0, 0); PG8_STAGE(PG8_SA(1, 1), a1 + hstepA, voffA);
;             PG8_WAIT_V(8); PG8_WAIT_L(0); PG8_BAR; PG8_MMA(0, 0, At, B0); PG8_MMA(0, 1, At, B1); PG8_BAR; PG8_SCHED;
;             PG8_LDA(At, 0, 1); PG8_STAGE(PG8_SB(0, 0), b2, voffB); PG8_STAGE(PG8_SB(0, 1), b2 + hstepB, voffB); PG8_STAGE(PG8_SA(0, 0), a2, voffA);
;             PG8_WAIT_V(8); PG8_WAIT_L(0); PG8_BAR; PG8_MMA(1, 0, At, B0); PG8_MMA(1, 1, At, B1); PG8_BAR; PG8_SCHED;
.LBB0_288:
	ds_read_b128 v[144:147], v159
	ds_read_b128 v[148:151], v159 offset:1024
	ds_read_b128 v[152:155], v159 offset:2048
	ds_read_b128 v[168:171], v159 offset:3072
	ds_read_b128 v[172:175], v160
	ds_read_b128 v[176:179], v160 offset:1024
	ds_read_b128 v[180:183], v160 offset:2048
	ds_read_b128 v[184:187], v160 offset:3072
	s_add_u32 s4, s36, 0xfff80080
	s_addc_u32 s5, s37, -1
	s_cmp_eq_u32 s59, 28
	s_cselect_b32 s41, s9, s5
	s_cselect_b32 s40, s11, s4
	s_cselect_b32 s39, s27, s51
	s_cselect_b32 s38, s29, s50
	v_lshl_add_u64 v[156:157], s[36:37], 0, v[136:137]
	s_add_i32 m0, s25, 0xc000
	ds_read_b128 v[188:191], v161
	ds_read_b128 v[192:195], v161 offset:1024
	ds_read_b128 v[196:199], v161 offset:2048
	ds_read_b128 v[200:203], v161 offset:3072
	ds_read_b128 v[204:207], v161 offset:4096
	ds_read_b128 v[208:211], v161 offset:5120
	ds_read_b128 v[212:215], v161 offset:6144
	ds_read_b128 v[216:219], v161 offset:7168
	global_load_lds_dwordx4 v[156:157], off
	v_lshl_add_u64 v[156:157], s[36:37], 0, v[138:139]
	s_add_i32 m0, s25, 0xe000
	s_nop 0
	global_load_lds_dwordx4 v[156:157], off
	s_waitcnt vmcnt(8)
	s_waitcnt lgkmcnt(0)
	s_barrier
	s_setprio 1
	s_waitcnt lgkmcnt(0)
	v_mfma_f32_16x16x32_bf16 v[124:127], v[144:147], v[188:191], v[124:127]
	v_mfma_f32_16x16x32_bf16 v[120:123], v[152:155], v[188:191], v[120:123]
	v_mfma_f32_16x16x32_bf16 v[108:111], v[144:147], v[196:199], v[108:111]
	v_mfma_f32_16x16x32_bf16 v[104:107], v[152:155], v[196:199], v[104:107]
	v_mfma_f32_16x16x32_bf16 v[92:95], v[144:147], v[204:207], v[92:95]
	v_mfma_f32_16x16x32_bf16 v[88:91], v[152:155], v[204:207], v[88:91]
	v_mfma_f32_16x16x32_bf16 v[76:79], v[144:147], v[212:215], v[76:79]
	v_mfma_f32_16x16x32_bf16 v[72:75], v[152:155], v[212:215], v[72:75]
	v_mfma_f32_16x16x32_bf16 v[124:127], v[148:151], v[192:195], v[124:127]
	v_mfma_f32_16x16x32_bf16 v[120:123], v[168:171], v[192:195], v[120:123]
	v_mfma_f32_16x16x32_bf16 v[108:111], v[148:151], v[200:203], v[108:111]
	v_mfma_f32_16x16x32_bf16 v[104:107], v[168:171], v[200:203], v[104:107]
	v_mfma_f32_16x16x32_bf16 v[92:95], v[148:151], v[208:211], v[92:95]
	v_mfma_f32_16x16x32_bf16 v[88:91], v[168:171], v[208:211], v[88:91]
	v_mfma_f32_16x16x32_bf16 v[76:79], v[148:151], v[216:219], v[76:79]
	v_mfma_f32_16x16x32_bf16 v[72:75], v[168:171], v[216:219], v[72:75]
	v_mfma_f32_16x16x32_bf16 v[116:119], v[172:175], v[188:191], v[116:119]
	v_mfma_f32_16x16x32_bf16 v[112:115], v[180:183], v[188:191], v[112:115]
	v_mfma_f32_16x16x32_bf16 v[100:103], v[172:175], v[196:199], v[100:103]
	v_mfma_f32_16x16x32_bf16 v[96:99], v[180:183], v[196:199], v[96:99]
	v_mfma_f32_16x16x32_bf16 v[84:87], v[172:175], v[204:207], v[84:87]
	v_mfma_f32_16x16x32_bf16 v[80:83], v[180:183], v[204:207], v[80:83]
	v_mfma_f32_16x16x32_bf16 v[68:71], v[172:175], v[212:215], v[68:71]
	v_mfma_f32_16x16x32_bf16 v[64:67], v[180:183], v[212:215], v[64:67]
	v_mfma_f32_16x16x32_bf16 v[116:119], v[176:179], v[192:195], v[116:119]
	v_mfma_f32_16x16x32_bf16 v[112:115], v[184:187], v[192:195], v[112:115]
	v_mfma_f32_16x16x32_bf16 v[100:103], v[176:179], v[200:203], v[100:103]
	v_mfma_f32_16x16x32_bf16 v[96:99], v[184:187], v[200:203], v[96:99]
	v_mfma_f32_16x16x32_bf16 v[84:87], v[176:179], v[208:211], v[84:87]
	v_mfma_f32_16x16x32_bf16 v[80:83], v[184:187], v[208:211], v[80:83]
	v_mfma_f32_16x16x32_bf16 v[68:71], v[176:179], v[216:219], v[68:71]
	v_mfma_f32_16x16x32_bf16 v[64:67], v[184:187], v[216:219], v[64:67]
	s_setprio 0
	s_barrier
	s_add_i32 s4, s55, s47
	v_lshl_add_u64 v[156:157], s[38:39], 0, v[130:131]
	s_mov_b32 m0, s4
	ds_read_b128 v[188:191], v161 offset:16384
	ds_read_b128 v[192:195], v161 offset:17408
	ds_read_b128 v[196:199], v161 offset:18432
	ds_read_b128 v[200:203], v161 offset:19456
	ds_read_b128 v[204:207], v161 offset:20480
	ds_read_b128 v[208:211], v161 offset:21504
	ds_read_b128 v[212:215], v161 offset:22528
	ds_read_b128 v[216:219], v161 offset:23552
	global_load_lds_dwordx4 v[156:157], off
	s_add_i32 m0, s4, 0x2000
	s_add_u32 s60, s38, 0x80000
	v_lshl_add_u64 v[164:165], s[38:39], 0, v[134:135]
	s_addc_u32 s61, s39, 0
	s_add_i32 s4, s56, s47
	global_load_lds_dwordx4 v[164:165], off
	v_lshl_add_u64 v[220:221], s[60:61], 0, v[130:131]
	s_mov_b32 m0, s4
	v_lshl_add_u64 v[222:223], s[40:41], 0, v[132:133]
	global_load_lds_dwordx4 v[220:221], off
	v_lshl_add_u64 v[220:221], s[60:61], 0, v[134:135]
	s_add_i32 m0, s4, 0x2000
	s_nop 0
	global_load_lds_dwordx4 v[220:221], off
	v_lshl_add_u64 v[220:221], s[40:41], 0, v[128:129]
	s_mov_b32 m0, s25
	s_nop 0
	global_load_lds_dwordx4 v[220:221], off
	s_mov_b32 m0, s33
	s_nop 0
	global_load_lds_dwordx4 v[222:223], off
	s_waitcnt vmcnt(8)
	s_waitcnt lgkmcnt(0)
	s_barrier
; #define PG8_STAGE(bufoff, gbase, voff) do { _Pragma("unroll") for (int _i = 0; _i < 2; ++_i) \
;         __builtin_amdgcn_global_load_lds((const unsigned*)((const char*)(gbase) + (voff)[_i]), (PG8_LAS unsigned*)(lds + (bufoff) + ldsw + _i * 8192), 16, 0, 0); } while (0)
; #define PG8_LDA(dst, b, h) do { _Pragma("unroll") for (int m = 0; m < 4; ++m) _Pragma("unroll") for (int k = 0; k < 2; ++k) dst[m][k] = *(const PG8_LAS bf16x8*)(lds + PG8_SA(b, h) + aoff + m * 2048 + k * 1024); } while (0)
; #define PG8_LDB(dst, b, h) do { _Pragma("unroll") for (int n = 0; n < 2; ++n) _Pragma("unroll") for (int k = 0; k < 2; ++k) dst[n][k] = *(const PG8_LAS bf16x8*)(lds + PG8_SB(b, h) + boff + n * 2048 + k * 1024); } while (0)
; #define PG8_MMA(ai, bj, At, Bt) do { __builtin_amdgcn_s_setprio(1); _Pragma("unroll") for (int m = 0; m < 4; ++m) _Pragma("unroll") for (int n = 0; n < 2; ++n) _Pragma("unroll") for (int k = 0; k < 2; ++k) \
;         acc[ai][bj][m][n] = __builtin_amdgcn_mfma_f32_16x16x32_bf16(Bt[n][k], At[m][k], acc[ai][bj][m][n], 0, 0, 0); __builtin_amdgcn_s_setprio(0); } while (0)
; #define PG8_WAIT_V(n) asm volatile("s_waitcnt vmcnt(" #n ")" ::: "memory")
; #define PG8_WAIT_L(n) asm volatile("s_waitcnt lgkmcnt(" #n ")" ::: "memory")
; #define PG8_BAR __builtin_amdgcn_s_barrier()
; #define PG8_SCHED __builtin_amdgcn_sched_barrier(0)
; template <class Epi, class Sched, bool ALIGN_EPI = false, bool SP2 = false>
; __device__ __forceinline__ void gemm_phase(PG8_LAS unsigned char* lds, const Gemm g, const Sched& S, const Epi& E) {
;     ...
;             PG8_WAIT_V(8); PG8_WAIT_L(0); PG8_BAR; PG8_MMA(1, 0, At, B0); PG8_MMA(1, 1, At, B1); PG8_BAR; PG8_SCHED;
;             PG8_LDB(B0, 1, 0); PG8_LDB(B1, 1, 1); PG8_SCHED; PG8_LDA(At, 1, 0); PG8_STAGE(PG8_SA(0, 1), a2 + hstepA, voffA);
;             PG8_WAIT_V(8); PG8_WAIT_L(0); PG8_BAR; PG8_MMA(0, 0, At, B0); PG8_MMA(0, 1, At, B1); PG8_BAR; PG8_SCHED;
	s_setprio 1
	s_waitcnt lgkmcnt(0)
	v_mfma_f32_16x16x32_bf16 v[60:63], v[144:147], v[188:191], v[60:63]
	v_mfma_f32_16x16x32_bf16 v[56:59], v[152:155], v[188:191], v[56:59]
	v_mfma_f32_16x16x32_bf16 v[44:47], v[144:147], v[196:199], v[44:47]
	v_mfma_f32_16x16x32_bf16 v[40:43], v[152:155], v[196:199], v[40:43]
	v_mfma_f32_16x16x32_bf16 v[28:31], v[144:147], v[204:207], v[28:31]
	v_mfma_f32_16x16x32_bf16 v[24:27], v[152:155], v[204:207], v[24:27]
	v_mfma_f32_16x16x32_bf16 v[12:15], v[144:147], v[212:215], v[12:15]
	v_mfma_f32_16x16x32_bf16 v[8:11], v[152:155], v[212:215], v[8:11]
	v_mfma_f32_16x16x32_bf16 v[60:63], v[148:151], v[192:195], v[60:63]
	v_mfma_f32_16x16x32_bf16 v[56:59], v[168:171], v[192:195], v[56:59]
	v_mfma_f32_16x16x32_bf16 v[44:47], v[148:151], v[200:203], v[44:47]
	v_mfma_f32_16x16x32_bf16 v[40:43], v[168:171], v[200:203], v[40:43]
	v_mfma_f32_16x16x32_bf16 v[28:31], v[148:151], v[208:211], v[28:31]
	v_mfma_f32_16x16x32_bf16 v[24:27], v[168:171], v[208:211], v[24:27]
	v_mfma_f32_16x16x32_bf16 v[12:15], v[148:151], v[216:219], v[12:15]
	v_mfma_f32_16x16x32_bf16 v[8:11], v[168:171], v[216:219], v[8:11]
	v_mfma_f32_16x16x32_bf16 v[52:55], v[172:175], v[188:191], v[52:55]
	v_mfma_f32_16x16x32_bf16 v[48:51], v[180:183], v[188:191], v[48:51]
	v_mfma_f32_16x16x32_bf16 v[36:39], v[172:175], v[196:199], v[36:39]
	v_mfma_f32_16x16x32_bf16 v[32:35], v[180:183], v[196:199], v[32:35]
	v_mfma_f32_16x16x32_bf16 v[20:23], v[172:175], v[204:207], v[20:23]
	v_mfma_f32_16x16x32_bf16 v[16:19], v[180:183], v[204:207], v[16:19]
	v_mfma_f32_16x16x32_bf16 v[4:7], v[172:175], v[212:215], v[4:7]
	v_mfma_f32_16x16x32_bf16 v[0:3], v[180:183], v[212:215], v[0:3]
	v_mfma_f32_16x16x32_bf16 v[52:55], v[176:179], v[192:195], v[52:55]
	v_mfma_f32_16x16x32_bf16 v[48:51], v[184:187], v[192:195], v[48:51]
	v_mfma_f32_16x16x32_bf16 v[36:39], v[176:179], v[200:203], v[36:39]
	v_mfma_f32_16x16x32_bf16 v[32:35], v[184:187], v[200:203], v[32:35]
	v_mfma_f32_16x16x32_bf16 v[20:23], v[176:179], v[208:211], v[20:23]
	v_mfma_f32_16x16x32_bf16 v[16:19], v[184:187], v[208:211], v[16:19]
	v_mfma_f32_16x16x32_bf16 v[4:7], v[176:179], v[216:219], v[4:7]
	v_mfma_f32_16x16x32_bf16 v[0:3], v[184:187], v[216:219], v[0:3]
	s_setprio 0
	s_barrier
	s_add_i32 s4, 0, 0x18000
	v_add_u32_e32 v163, s4, v158
	s_add_i32 s5, 0, 0x1c000
	ds_read_b128 v[144:147], v163
	ds_read_b128 v[148:151], v163 offset:1024
	ds_read_b128 v[152:155], v163 offset:2048
	ds_read_b128 v[168:171], v163 offset:3072
	v_add_u32_e32 v163, s5, v158
	ds_read_b128 v[172:175], v163
	ds_read_b128 v[176:179], v163 offset:1024
	ds_read_b128 v[180:183], v163 offset:2048
	ds_read_b128 v[184:187], v163 offset:3072
	s_add_u32 s40, s40, 0x80000
	s_addc_u32 s41, s41, 0
	s_mov_b32 m0, s44
	v_lshl_add_u64 v[224:225], s[40:41], 0, v[128:129]
	ds_read_b128 v[188:191], v161 offset:32768
	ds_read_b128 v[192:195], v161 offset:33792
	ds_read_b128 v[196:199], v161 offset:34816
	ds_read_b128 v[200:203], v161 offset:35840
	ds_read_b128 v[204:207], v161 offset:36864
	ds_read_b128 v[208:211], v161 offset:37888
	ds_read_b128 v[212:215], v161 offset:38912
	ds_read_b128 v[216:219], v161 offset:39936
	global_load_lds_dwordx4 v[224:225], off
	v_lshl_add_u64 v[224:225], s[40:41], 0, v[132:133]
	s_mov_b32 m0, s45
	s_nop 0
	global_load_lds_dwordx4 v[224:225], off
	s_waitcnt vmcnt(8)
	s_waitcnt lgkmcnt(0)
	s_barrier
	s_setprio 1
	s_waitcnt lgkmcnt(0)
	v_mfma_f32_16x16x32_bf16 v[124:127], v[144:147], v[188:191], v[124:127]
	v_mfma_f32_16x16x32_bf16 v[120:123], v[152:155], v[188:191], v[120:123]
	v_mfma_f32_16x16x32_bf16 v[108:111], v[144:147], v[196:199], v[108:111]
	v_mfma_f32_16x16x32_bf16 v[104:107], v[152:155], v[196:199], v[104:107]
	v_mfma_f32_16x16x32_bf16 v[92:95], v[144:147], v[204:207], v[92:95]
	v_mfma_f32_16x16x32_bf16 v[88:91], v[152:155], v[204:207], v[88:91]
	v_mfma_f32_16x16x32_bf16 v[76:79], v[144:147], v[212:215], v[76:79]
	v_mfma_f32_16x16x32_bf16 v[72:75], v[152:155], v[212:215], v[72:75]
	v_mfma_f32_16x16x32_bf16 v[124:127], v[148:151], v[192:195], v[124:127]
	v_mfma_f32_16x16x32_bf16 v[120:123], v[168:171], v[192:195], v[120:123]
	v_mfma_f32_16x16x32_bf16 v[108:111], v[148:151], v[200:203], v[108:111]
	v_mfma_f32_16x16x32_bf16 v[104:107], v[168:171], v[200:203], v[104:107]
	v_mfma_f32_16x16x32_bf16 v[92:95], v[148:151], v[208:211], v[92:95]
	v_mfma_f32_16x16x32_bf16 v[88:91], v[168:171], v[208:211], v[88:91]
	v_mfma_f32_16x16x32_bf16 v[76:79], v[148:151], v[216:219], v[76:79]
	v_mfma_f32_16x16x32_bf16 v[72:75], v[168:171], v[216:219], v[72:75]
	v_mfma_f32_16x16x32_bf16 v[116:119], v[172:175], v[188:191], v[116:119]
	v_mfma_f32_16x16x32_bf16 v[112:115], v[180:183], v[188:191], v[112:115]
	v_mfma_f32_16x16x32_bf16 v[100:103], v[172:175], v[196:199], v[100:103]
	v_mfma_f32_16x16x32_bf16 v[96:99], v[180:183], v[196:199], v[96:99]
	v_mfma_f32_16x16x32_bf16 v[84:87], v[172:175], v[204:207], v[84:87]
	v_mfma_f32_16x16x32_bf16 v[80:83], v[180:183], v[204:207], v[80:83]
	v_mfma_f32_16x16x32_bf16 v[68:71], v[172:175], v[212:215], v[68:71]
	v_mfma_f32_16x16x32_bf16 v[64:67], v[180:183], v[212:215], v[64:67]
	v_mfma_f32_16x16x32_bf16 v[116:119], v[176:179], v[192:195], v[116:119]
	v_mfma_f32_16x16x32_bf16 v[112:115], v[184:187], v[192:195], v[112:115]
	v_mfma_f32_16x16x32_bf16 v[100:103], v[176:179], v[200:203], v[100:103]
	v_mfma_f32_16x16x32_bf16 v[96:99], v[184:187], v[200:203], v[96:99]
	v_mfma_f32_16x16x32_bf16 v[84:87], v[176:179], v[208:211], v[84:87]
	v_mfma_f32_16x16x32_bf16 v[80:83], v[184:187], v[208:211], v[80:83]
	v_mfma_f32_16x16x32_bf16 v[68:71], v[176:179], v[216:219], v[68:71]
	v_mfma_f32_16x16x32_bf16 v[64:67], v[184:187], v[216:219], v[64:67]
	s_setprio 0
	s_barrier
; #define PG8_STAGE(bufoff, gbase, voff) do { _Pragma("unroll") for (int _i = 0; _i < 2; ++_i) \
;         __builtin_amdgcn_global_load_lds((const unsigned*)((const char*)(gbase) + (voff)[_i]), (PG8_LAS unsigned*)(lds + (bufoff) + ldsw + _i * 8192), 16, 0, 0); } while (0)
; #define PG8_LDA(dst, b, h) do { _Pragma("unroll") for (int m = 0; m < 4; ++m) _Pragma("unroll") for (int k = 0; k < 2; ++k) dst[m][k] = *(const PG8_LAS bf16x8*)(lds + PG8_SA(b, h) + aoff + m * 2048 + k * 1024); } while (0)
; #define PG8_MMA(ai, bj, At, Bt) do { __builtin_amdgcn_s_setprio(1); _Pragma("unroll") for (int m = 0; m < 4; ++m) _Pragma("unroll") for (int n = 0; n < 2; ++n) _Pragma("unroll") for (int k = 0; k < 2; ++k) \
;         acc[ai][bj][m][n] = __builtin_amdgcn_mfma_f32_16x16x32_bf16(Bt[n][k], At[m][k], acc[ai][bj][m][n], 0, 0, 0); __builtin_amdgcn_s_setprio(0); } while (0)
; #define PG8_WAIT_V(n) asm volatile("s_waitcnt vmcnt(" #n ")" ::: "memory")
; #define PG8_WAIT_L(n) asm volatile("s_waitcnt lgkmcnt(" #n ")" ::: "memory")
; #define PG8_BAR __builtin_amdgcn_s_barrier()
; #define PG8_SCHED __builtin_amdgcn_sched_barrier(0)
; template <class Epi, class Sched, bool ALIGN_EPI = false, bool SP2 = false>
; __device__ __forceinline__ void gemm_phase(PG8_LAS unsigned char* lds, const Gemm g, const Sched& S, const Epi& E) {
;     ...
;         for (int t = 0; t < nt; t += 2) {
;             const bool last = (t == nt - 2);
;     ...
;             PG8_LDA(At, 1, 1); PG8_STAGE(PG8_SB(1, 0), b3, voffB); PG8_STAGE(PG8_SB(1, 1), b3 + hstepB, voffB); PG8_STAGE(PG8_SA(1, 0), a3, voffA);
;             PG8_WAIT_V(8); PG8_WAIT_L(0); PG8_BAR; PG8_MMA(1, 0, At, B0); PG8_MMA(1, 1, At, B1); PG8_BAR; PG8_SCHED;
	s_add_i32 s4, s4, s47
	v_lshl_add_u64 v[156:157], v[156:157], 0, s[22:23]
	s_mov_b32 m0, s4
	ds_read_b128 v[188:191], v161 offset:49152
	ds_read_b128 v[192:195], v161 offset:50176
	ds_read_b128 v[196:199], v161 offset:51200
	ds_read_b128 v[200:203], v161 offset:52224
	ds_read_b128 v[204:207], v161 offset:53248
	ds_read_b128 v[208:211], v161 offset:54272
	ds_read_b128 v[212:215], v161 offset:55296
	ds_read_b128 v[216:219], v161 offset:56320
	global_load_lds_dwordx4 v[156:157], off
	s_add_i32 m0, s4, 0x2000
	s_add_u32 s38, s38, 0x80080
	v_lshl_add_u64 v[156:157], v[164:165], 0, s[22:23]
	s_addc_u32 s39, s39, 0
	s_add_i32 s4, s5, s47
	global_load_lds_dwordx4 v[156:157], off
	v_lshl_add_u64 v[156:157], s[38:39], 0, v[130:131]
	s_mov_b32 m0, s4
	s_nop 0
	global_load_lds_dwordx4 v[156:157], off
	v_lshl_add_u64 v[156:157], s[38:39], 0, v[134:135]
	s_add_i32 m0, s4, 0x2000
	s_nop 0
	global_load_lds_dwordx4 v[156:157], off
	v_lshl_add_u64 v[156:157], v[220:221], 0, s[22:23]
	s_mov_b32 m0, s46
	s_nop 0
	global_load_lds_dwordx4 v[156:157], off
	v_lshl_add_u64 v[156:157], v[222:223], 0, s[22:23]
	s_mov_b32 m0, s53
	s_nop 0
	global_load_lds_dwordx4 v[156:157], off
	s_waitcnt vmcnt(8)
	s_waitcnt lgkmcnt(0)
	s_barrier
	s_setprio 1
	s_waitcnt lgkmcnt(0)
	v_mfma_f32_16x16x32_bf16 v[60:63], v[144:147], v[188:191], v[60:63]
	v_mfma_f32_16x16x32_bf16 v[56:59], v[152:155], v[188:191], v[56:59]
	v_mfma_f32_16x16x32_bf16 v[44:47], v[144:147], v[196:199], v[44:47]
	v_mfma_f32_16x16x32_bf16 v[40:43], v[152:155], v[196:199], v[40:43]
	v_mfma_f32_16x16x32_bf16 v[28:31], v[144:147], v[204:207], v[28:31]
	v_mfma_f32_16x16x32_bf16 v[24:27], v[152:155], v[204:207], v[24:27]
	v_mfma_f32_16x16x32_bf16 v[12:15], v[144:147], v[212:215], v[12:15]
	v_mfma_f32_16x16x32_bf16 v[8:11], v[152:155], v[212:215], v[8:11]
	v_mfma_f32_16x16x32_bf16 v[60:63], v[148:151], v[192:195], v[60:63]
	v_mfma_f32_16x16x32_bf16 v[56:59], v[168:171], v[192:195], v[56:59]
	v_mfma_f32_16x16x32_bf16 v[44:47], v[148:151], v[200:203], v[44:47]
	v_mfma_f32_16x16x32_bf16 v[40:43], v[168:171], v[200:203], v[40:43]
	v_mfma_f32_16x16x32_bf16 v[28:31], v[148:151], v[208:211], v[28:31]
	v_mfma_f32_16x16x32_bf16 v[24:27], v[168:171], v[208:211], v[24:27]
	v_mfma_f32_16x16x32_bf16 v[12:15], v[148:151], v[216:219], v[12:15]
	v_mfma_f32_16x16x32_bf16 v[8:11], v[168:171], v[216:219], v[8:11]
	v_mfma_f32_16x16x32_bf16 v[52:55], v[172:175], v[188:191], v[52:55]
	v_mfma_f32_16x16x32_bf16 v[48:51], v[180:183], v[188:191], v[48:51]
	v_mfma_f32_16x16x32_bf16 v[36:39], v[172:175], v[196:199], v[36:39]
	v_mfma_f32_16x16x32_bf16 v[32:35], v[180:183], v[196:199], v[32:35]
	v_mfma_f32_16x16x32_bf16 v[20:23], v[172:175], v[204:207], v[20:23]
	v_mfma_f32_16x16x32_bf16 v[16:19], v[180:183], v[204:207], v[16:19]
	v_mfma_f32_16x16x32_bf16 v[4:7], v[172:175], v[212:215], v[4:7]
	v_mfma_f32_16x16x32_bf16 v[0:3], v[180:183], v[212:215], v[0:3]
	v_mfma_f32_16x16x32_bf16 v[52:55], v[176:179], v[192:195], v[52:55]
	v_mfma_f32_16x16x32_bf16 v[48:51], v[184:187], v[192:195], v[48:51]
	v_mfma_f32_16x16x32_bf16 v[36:39], v[176:179], v[200:203], v[36:39]
	v_mfma_f32_16x16x32_bf16 v[32:35], v[184:187], v[200:203], v[32:35]
	v_mfma_f32_16x16x32_bf16 v[20:23], v[176:179], v[208:211], v[20:23]
	v_mfma_f32_16x16x32_bf16 v[16:19], v[184:187], v[208:211], v[16:19]
	v_mfma_f32_16x16x32_bf16 v[4:7], v[176:179], v[216:219], v[4:7]
	v_mfma_f32_16x16x32_bf16 v[0:3], v[184:187], v[216:219], v[0:3]
	s_setprio 0
	s_barrier
	s_add_i32 s59, s59, 2
	s_add_u32 s36, s36, 0x100
	s_addc_u32 s37, s37, 0
	s_add_u32 s50, s50, 0x100
	s_addc_u32 s51, s51, 0
	s_cmp_gt_u32 s59, 29
	s_cbranch_scc0 .LBB0_288
	s_and_b64 vcc, exec, s[48:49]
	s_cbranch_vccz .LBB0_291
	s_barrier

; #define PG8_STAGE(bufoff, gbase, voff) do { _Pragma("unroll") for (int _i = 0; _i < 2; ++_i) \
;         __builtin_amdgcn_global_load_lds((const unsigned*)((const char*)(gbase) + (voff)[_i]), (PG8_LAS unsigned*)(lds + (bufoff) + ldsw + _i * 8192), 16, 0, 0); } while (0)
; #define PG8_LDA(dst, b, h) do { _Pragma("unroll") for (int m = 0; m < 4; ++m) _Pragma("unroll") for (int k = 0; k < 2; ++k) dst[m][k] = *(const PG8_LAS bf16x8*)(lds + PG8_SA(b, h) + aoff + m * 2048 + k * 1024); } while (0)
; #define PG8_LDB(dst, b, h) do { _Pragma("unroll") for (int n = 0; n < 2; ++n) _Pragma("unroll") for (int k = 0; k < 2; ++k) dst[n][k] = *(const PG8_LAS bf16x8*)(lds + PG8_SB(b, h) + boff + n * 2048 + k * 1024); } while (0)
; #define PG8_MMA(ai, bj, At, Bt) do { __builtin_amdgcn_s_setprio(1); _Pragma("unroll") for (int m = 0; m < 4; ++m) _Pragma("unroll") for (int n = 0; n < 2; ++n) _Pragma("unroll") for (int k = 0; k < 2; ++k) \
;         acc[ai][bj][m][n] = __builtin_amdgcn_mfma_f32_16x16x32_bf16(Bt[n][k], At[m][k], acc[ai][bj][m][n], 0, 0, 0); __builtin_amdgcn_s_setprio(0); } while (0)
; #define PG8_WAIT_V(n) asm volatile("s_waitcnt vmcnt(" #n ")" ::: "memory")
; #define PG8_WAIT_L(n) asm volatile("s_waitcnt lgkmcnt(" #n ")" ::: "memory")
; #define PG8_BAR __builtin_amdgcn_s_barrier()
; #define PG8_SCHED __builtin_amdgcn_sched_barrier(0)
; template <class Epi, class Sched, bool ALIGN_EPI = false, bool SP2 = false>
; __device__ __forceinline__ void gemm_phase(PG8_LAS unsigned char* lds, const Gemm g, const Sched& S, const Epi& E) {
;     ...
;             const bool last = (t == nt - 2);
;             const char* a1 = cA + (size_t)(t + 1) * kstep;
;             const char* a2 = last ? nA : cA + (size_t)(t + 2) * kstep; const char* b2 = last ? nB : cB + (size_t)(t + 2) * kstep;
;             const char* a3 = a2 + kstep; const char* b3 = b2 + kstep;
;     ...
;             PG8_LDB(B0, 0, 0); PG8_LDB(B1, 0, 1); PG8_SCHED; PG8_LDA(At, 0, 0); PG8_STAGE(PG8_SA(1, 1), a1 + hstepA, voffA);
;             PG8_WAIT_V(8); PG8_WAIT_L(0); PG8_BAR; PG8_MMA(0, 0, At, B0); PG8_MMA(0, 1, At, B1); PG8_BAR; PG8_SCHED;
;             PG8_LDA(At, 0, 1); PG8_STAGE(PG8_SB(0, 0), b2, voffB); PG8_STAGE(PG8_SB(0, 1), b2 + hstepB, voffB); PG8_STAGE(PG8_SA(0, 0), a2, voffA);
;             PG8_WAIT_V(8); PG8_WAIT_L(0); PG8_BAR; PG8_MMA(1, 0, At, B0); PG8_MMA(1, 1, At, B1); PG8_BAR; PG8_SCHED;
.LBB0_660:
	ds_read_b128 v[144:147], v149
	ds_read_b128 v[152:155], v149 offset:1024
	ds_read_b128 v[156:159], v149 offset:2048
	ds_read_b128 v[160:163], v149 offset:3072
	ds_read_b128 v[168:171], v150
	ds_read_b128 v[172:175], v150 offset:1024
	ds_read_b128 v[176:179], v150 offset:2048
	ds_read_b128 v[180:183], v150 offset:3072
	s_add_u32 s4, s30, 0xfff80080
	s_addc_u32 s5, s31, -1
	s_cmp_eq_u32 s56, 28
	s_cselect_b32 s37, s21, s5
	s_cselect_b32 s36, s29, s4
	s_cselect_b32 s35, s19, s55
	s_cselect_b32 s34, s53, s54
	v_lshl_add_u64 v[164:165], s[30:31], 0, v[136:137]
	s_add_i32 m0, s25, 0xc000
	ds_read_b128 v[184:187], v151
	ds_read_b128 v[188:191], v151 offset:1024
	ds_read_b128 v[192:195], v151 offset:2048
	ds_read_b128 v[196:199], v151 offset:3072
	ds_read_b128 v[200:203], v151 offset:4096
	ds_read_b128 v[204:207], v151 offset:5120
	ds_read_b128 v[208:211], v151 offset:6144
	ds_read_b128 v[212:215], v151 offset:7168
	global_load_lds_dwordx4 v[164:165], off
	v_lshl_add_u64 v[164:165], s[30:31], 0, v[138:139]
	s_add_i32 m0, s25, 0xe000
	s_nop 0
	global_load_lds_dwordx4 v[164:165], off
	s_waitcnt vmcnt(8)
	s_waitcnt lgkmcnt(0)
	s_barrier
	s_setprio 1
	s_waitcnt lgkmcnt(0)
	v_mfma_f32_16x16x32_bf16 v[124:127], v[144:147], v[184:187], v[124:127]
	v_mfma_f32_16x16x32_bf16 v[120:123], v[156:159], v[184:187], v[120:123]
	v_mfma_f32_16x16x32_bf16 v[108:111], v[144:147], v[192:195], v[108:111]
	v_mfma_f32_16x16x32_bf16 v[104:107], v[156:159], v[192:195], v[104:107]
	v_mfma_f32_16x16x32_bf16 v[92:95], v[144:147], v[200:203], v[92:95]
	v_mfma_f32_16x16x32_bf16 v[88:91], v[156:159], v[200:203], v[88:91]
	v_mfma_f32_16x16x32_bf16 v[76:79], v[144:147], v[208:211], v[76:79]
	v_mfma_f32_16x16x32_bf16 v[72:75], v[156:159], v[208:211], v[72:75]
	v_mfma_f32_16x16x32_bf16 v[124:127], v[152:155], v[188:191], v[124:127]
	v_mfma_f32_16x16x32_bf16 v[120:123], v[160:163], v[188:191], v[120:123]
	v_mfma_f32_16x16x32_bf16 v[108:111], v[152:155], v[196:199], v[108:111]
	v_mfma_f32_16x16x32_bf16 v[104:107], v[160:163], v[196:199], v[104:107]
	v_mfma_f32_16x16x32_bf16 v[92:95], v[152:155], v[204:207], v[92:95]
	v_mfma_f32_16x16x32_bf16 v[88:91], v[160:163], v[204:207], v[88:91]
	v_mfma_f32_16x16x32_bf16 v[76:79], v[152:155], v[212:215], v[76:79]
	v_mfma_f32_16x16x32_bf16 v[72:75], v[160:163], v[212:215], v[72:75]
	v_mfma_f32_16x16x32_bf16 v[116:119], v[168:171], v[184:187], v[116:119]
	v_mfma_f32_16x16x32_bf16 v[112:115], v[176:179], v[184:187], v[112:115]
	v_mfma_f32_16x16x32_bf16 v[100:103], v[168:171], v[192:195], v[100:103]
	v_mfma_f32_16x16x32_bf16 v[96:99], v[176:179], v[192:195], v[96:99]
	v_mfma_f32_16x16x32_bf16 v[84:87], v[168:171], v[200:203], v[84:87]
	v_mfma_f32_16x16x32_bf16 v[80:83], v[176:179], v[200:203], v[80:83]
	v_mfma_f32_16x16x32_bf16 v[68:71], v[168:171], v[208:211], v[68:71]
	v_mfma_f32_16x16x32_bf16 v[64:67], v[176:179], v[208:211], v[64:67]
	v_mfma_f32_16x16x32_bf16 v[116:119], v[172:175], v[188:191], v[116:119]
	v_mfma_f32_16x16x32_bf16 v[112:115], v[180:183], v[188:191], v[112:115]
	v_mfma_f32_16x16x32_bf16 v[100:103], v[172:175], v[196:199], v[100:103]
	v_mfma_f32_16x16x32_bf16 v[96:99], v[180:183], v[196:199], v[96:99]
	v_mfma_f32_16x16x32_bf16 v[84:87], v[172:175], v[204:207], v[84:87]
	v_mfma_f32_16x16x32_bf16 v[80:83], v[180:183], v[204:207], v[80:83]
	v_mfma_f32_16x16x32_bf16 v[68:71], v[172:175], v[212:215], v[68:71]
	v_mfma_f32_16x16x32_bf16 v[64:67], v[180:183], v[212:215], v[64:67]
	s_setprio 0
	s_barrier
	s_add_i32 s4, s44, s47
	v_lshl_add_u64 v[164:165], s[34:35], 0, v[130:131]
	s_mov_b32 m0, s4
	ds_read_b128 v[184:187], v151 offset:16384
	ds_read_b128 v[188:191], v151 offset:17408
	ds_read_b128 v[192:195], v151 offset:18432
	ds_read_b128 v[196:199], v151 offset:19456
	ds_read_b128 v[200:203], v151 offset:20480
	ds_read_b128 v[204:207], v151 offset:21504
	ds_read_b128 v[208:211], v151 offset:22528
	ds_read_b128 v[212:215], v151 offset:23552
	global_load_lds_dwordx4 v[164:165], off
	s_add_i32 m0, s4, 0x2000
	s_add_u32 s58, s34, 0x80000
	v_lshl_add_u64 v[216:217], s[34:35], 0, v[134:135]
	s_addc_u32 s59, s35, 0
	s_add_i32 s4, s45, s47
	global_load_lds_dwordx4 v[216:217], off
	v_lshl_add_u64 v[218:219], s[58:59], 0, v[130:131]
	s_mov_b32 m0, s4
	v_lshl_add_u64 v[220:221], s[36:37], 0, v[132:133]
	global_load_lds_dwordx4 v[218:219], off
	v_lshl_add_u64 v[218:219], s[58:59], 0, v[134:135]
	s_add_i32 m0, s4, 0x2000
	s_nop 0
	global_load_lds_dwordx4 v[218:219], off
	v_lshl_add_u64 v[218:219], s[36:37], 0, v[128:129]
	s_mov_b32 m0, s25
	s_nop 0
	global_load_lds_dwordx4 v[218:219], off
	s_mov_b32 m0, s33
	s_nop 0
	global_load_lds_dwordx4 v[220:221], off
	s_waitcnt vmcnt(8)
	s_waitcnt lgkmcnt(0)
	s_barrier
; #define PG8_STAGE(bufoff, gbase, voff) do { _Pragma("unroll") for (int _i = 0; _i < 2; ++_i) \
;         __builtin_amdgcn_global_load_lds((const unsigned*)((const char*)(gbase) + (voff)[_i]), (PG8_LAS unsigned*)(lds + (bufoff) + ldsw + _i * 8192), 16, 0, 0); } while (0)
; #define PG8_LDA(dst, b, h) do { _Pragma("unroll") for (int m = 0; m < 4; ++m) _Pragma("unroll") for (int k = 0; k < 2; ++k) dst[m][k] = *(const PG8_LAS bf16x8*)(lds + PG8_SA(b, h) + aoff + m * 2048 + k * 1024); } while (0)
; #define PG8_LDB(dst, b, h) do { _Pragma("unroll") for (int n = 0; n < 2; ++n) _Pragma("unroll") for (int k = 0; k < 2; ++k) dst[n][k] = *(const PG8_LAS bf16x8*)(lds + PG8_SB(b, h) + boff + n * 2048 + k * 1024); } while (0)
; #define PG8_MMA(ai, bj, At, Bt) do { __builtin_amdgcn_s_setprio(1); _Pragma("unroll") for (int m = 0; m < 4; ++m) _Pragma("unroll") for (int n = 0; n < 2; ++n) _Pragma("unroll") for (int k = 0; k < 2; ++k) \
;         acc[ai][bj][m][n] = __builtin_amdgcn_mfma_f32_16x16x32_bf16(Bt[n][k], At[m][k], acc[ai][bj][m][n], 0, 0, 0); __builtin_amdgcn_s_setprio(0); } while (0)
; #define PG8_WAIT_V(n) asm volatile("s_waitcnt vmcnt(" #n ")" ::: "memory")
; #define PG8_WAIT_L(n) asm volatile("s_waitcnt lgkmcnt(" #n ")" ::: "memory")
; #define PG8_BAR __builtin_amdgcn_s_barrier()
; #define PG8_SCHED __builtin_amdgcn_sched_barrier(0)
; template <class Epi, class Sched, bool ALIGN_EPI = false, bool SP2 = false>
; __device__ __forceinline__ void gemm_phase(PG8_LAS unsigned char* lds, const Gemm g, const Sched& S, const Epi& E) {
;     ...
;             PG8_WAIT_V(8); PG8_WAIT_L(0); PG8_BAR; PG8_MMA(1, 0, At, B0); PG8_MMA(1, 1, At, B1); PG8_BAR; PG8_SCHED;
;             PG8_LDB(B0, 1, 0); PG8_LDB(B1, 1, 1); PG8_SCHED; PG8_LDA(At, 1, 0); PG8_STAGE(PG8_SA(0, 1), a2 + hstepA, voffA);
;             PG8_WAIT_V(8); PG8_WAIT_L(0); PG8_BAR; PG8_MMA(0, 0, At, B0); PG8_MMA(0, 1, At, B1); PG8_BAR; PG8_SCHED;
	s_setprio 1
	s_waitcnt lgkmcnt(0)
	v_mfma_f32_16x16x32_bf16 v[60:63], v[144:147], v[184:187], v[60:63]
	v_mfma_f32_16x16x32_bf16 v[56:59], v[156:159], v[184:187], v[56:59]
	v_mfma_f32_16x16x32_bf16 v[44:47], v[144:147], v[192:195], v[44:47]
	v_mfma_f32_16x16x32_bf16 v[40:43], v[156:159], v[192:195], v[40:43]
	v_mfma_f32_16x16x32_bf16 v[28:31], v[144:147], v[200:203], v[28:31]
	v_mfma_f32_16x16x32_bf16 v[24:27], v[156:159], v[200:203], v[24:27]
	v_mfma_f32_16x16x32_bf16 v[12:15], v[144:147], v[208:211], v[12:15]
	v_mfma_f32_16x16x32_bf16 v[8:11], v[156:159], v[208:211], v[8:11]
	v_mfma_f32_16x16x32_bf16 v[60:63], v[152:155], v[188:191], v[60:63]
	v_mfma_f32_16x16x32_bf16 v[56:59], v[160:163], v[188:191], v[56:59]
	v_mfma_f32_16x16x32_bf16 v[44:47], v[152:155], v[196:199], v[44:47]
	v_mfma_f32_16x16x32_bf16 v[40:43], v[160:163], v[196:199], v[40:43]
	v_mfma_f32_16x16x32_bf16 v[28:31], v[152:155], v[204:207], v[28:31]
	v_mfma_f32_16x16x32_bf16 v[24:27], v[160:163], v[204:207], v[24:27]
	v_mfma_f32_16x16x32_bf16 v[12:15], v[152:155], v[212:215], v[12:15]
	v_mfma_f32_16x16x32_bf16 v[8:11], v[160:163], v[212:215], v[8:11]
	v_mfma_f32_16x16x32_bf16 v[52:55], v[168:171], v[184:187], v[52:55]
	v_mfma_f32_16x16x32_bf16 v[48:51], v[176:179], v[184:187], v[48:51]
	v_mfma_f32_16x16x32_bf16 v[36:39], v[168:171], v[192:195], v[36:39]
	v_mfma_f32_16x16x32_bf16 v[32:35], v[176:179], v[192:195], v[32:35]
	v_mfma_f32_16x16x32_bf16 v[20:23], v[168:171], v[200:203], v[20:23]
	v_mfma_f32_16x16x32_bf16 v[16:19], v[176:179], v[200:203], v[16:19]
	v_mfma_f32_16x16x32_bf16 v[4:7], v[168:171], v[208:211], v[4:7]
	v_mfma_f32_16x16x32_bf16 v[0:3], v[176:179], v[208:211], v[0:3]
	v_mfma_f32_16x16x32_bf16 v[52:55], v[172:175], v[188:191], v[52:55]
	v_mfma_f32_16x16x32_bf16 v[48:51], v[180:183], v[188:191], v[48:51]
	v_mfma_f32_16x16x32_bf16 v[36:39], v[172:175], v[196:199], v[36:39]
	v_mfma_f32_16x16x32_bf16 v[32:35], v[180:183], v[196:199], v[32:35]
	v_mfma_f32_16x16x32_bf16 v[20:23], v[172:175], v[204:207], v[20:23]
	v_mfma_f32_16x16x32_bf16 v[16:19], v[180:183], v[204:207], v[16:19]
	v_mfma_f32_16x16x32_bf16 v[4:7], v[172:175], v[212:215], v[4:7]
	v_mfma_f32_16x16x32_bf16 v[0:3], v[180:183], v[212:215], v[0:3]
	s_setprio 0
	s_barrier
	s_add_i32 s4, 0, 0x18000
	s_add_i32 s5, 0, 0x1c000
	v_add_u32_e32 v160, s4, v148
	v_add_u32_e32 v166, s5, v148
	ds_read_b128 v[144:147], v160
	ds_read_b128 v[152:155], v160 offset:1024
	ds_read_b128 v[156:159], v160 offset:2048
	ds_read_b128 v[160:163], v160 offset:3072
	ds_read_b128 v[168:171], v166
	ds_read_b128 v[172:175], v166 offset:1024
	ds_read_b128 v[176:179], v166 offset:2048
	ds_read_b128 v[180:183], v166 offset:3072
	s_add_u32 s36, s36, 0x80000
	s_addc_u32 s37, s37, 0
	s_mov_b32 m0, s38
	v_lshl_add_u64 v[222:223], s[36:37], 0, v[128:129]
	ds_read_b128 v[184:187], v151 offset:32768
	ds_read_b128 v[188:191], v151 offset:33792
	ds_read_b128 v[192:195], v151 offset:34816
	ds_read_b128 v[196:199], v151 offset:35840
	ds_read_b128 v[200:203], v151 offset:36864
	ds_read_b128 v[204:207], v151 offset:37888
	ds_read_b128 v[208:211], v151 offset:38912
	ds_read_b128 v[212:215], v151 offset:39936
	global_load_lds_dwordx4 v[222:223], off
	v_lshl_add_u64 v[222:223], s[36:37], 0, v[132:133]
	s_mov_b32 m0, s39
	s_nop 0
	global_load_lds_dwordx4 v[222:223], off
	s_waitcnt vmcnt(8)
	s_waitcnt lgkmcnt(0)
	s_barrier
	s_setprio 1
	s_waitcnt lgkmcnt(0)
	v_mfma_f32_16x16x32_bf16 v[124:127], v[144:147], v[184:187], v[124:127]
	v_mfma_f32_16x16x32_bf16 v[120:123], v[156:159], v[184:187], v[120:123]
	v_mfma_f32_16x16x32_bf16 v[108:111], v[144:147], v[192:195], v[108:111]
	v_mfma_f32_16x16x32_bf16 v[104:107], v[156:159], v[192:195], v[104:107]
	v_mfma_f32_16x16x32_bf16 v[92:95], v[144:147], v[200:203], v[92:95]
	v_mfma_f32_16x16x32_bf16 v[88:91], v[156:159], v[200:203], v[88:91]
	v_mfma_f32_16x16x32_bf16 v[76:79], v[144:147], v[208:211], v[76:79]
	v_mfma_f32_16x16x32_bf16 v[72:75], v[156:159], v[208:211], v[72:75]
	v_mfma_f32_16x16x32_bf16 v[124:127], v[152:155], v[188:191], v[124:127]
	v_mfma_f32_16x16x32_bf16 v[120:123], v[160:163], v[188:191], v[120:123]
	v_mfma_f32_16x16x32_bf16 v[108:111], v[152:155], v[196:199], v[108:111]
	v_mfma_f32_16x16x32_bf16 v[104:107], v[160:163], v[196:199], v[104:107]
	v_mfma_f32_16x16x32_bf16 v[92:95], v[152:155], v[204:207], v[92:95]
	v_mfma_f32_16x16x32_bf16 v[88:91], v[160:163], v[204:207], v[88:91]
	v_mfma_f32_16x16x32_bf16 v[76:79], v[152:155], v[212:215], v[76:79]
	v_mfma_f32_16x16x32_bf16 v[72:75], v[160:163], v[212:215], v[72:75]
	v_mfma_f32_16x16x32_bf16 v[116:119], v[168:171], v[184:187], v[116:119]
	v_mfma_f32_16x16x32_bf16 v[112:115], v[176:179], v[184:187], v[112:115]
	v_mfma_f32_16x16x32_bf16 v[100:103], v[168:171], v[192:195], v[100:103]
	v_mfma_f32_16x16x32_bf16 v[96:99], v[176:179], v[192:195], v[96:99]
	v_mfma_f32_16x16x32_bf16 v[84:87], v[168:171], v[200:203], v[84:87]
	v_mfma_f32_16x16x32_bf16 v[80:83], v[176:179], v[200:203], v[80:83]
	v_mfma_f32_16x16x32_bf16 v[68:71], v[168:171], v[208:211], v[68:71]
	v_mfma_f32_16x16x32_bf16 v[64:67], v[176:179], v[208:211], v[64:67]
	v_mfma_f32_16x16x32_bf16 v[116:119], v[172:175], v[188:191], v[116:119]
	v_mfma_f32_16x16x32_bf16 v[112:115], v[180:183], v[188:191], v[112:115]
	v_mfma_f32_16x16x32_bf16 v[100:103], v[172:175], v[196:199], v[100:103]
	v_mfma_f32_16x16x32_bf16 v[96:99], v[180:183], v[196:199], v[96:99]
	v_mfma_f32_16x16x32_bf16 v[84:87], v[172:175], v[204:207], v[84:87]
	v_mfma_f32_16x16x32_bf16 v[80:83], v[180:183], v[204:207], v[80:83]
	v_mfma_f32_16x16x32_bf16 v[68:71], v[172:175], v[212:215], v[68:71]
	v_mfma_f32_16x16x32_bf16 v[64:67], v[180:183], v[212:215], v[64:67]
	s_setprio 0
	s_barrier
; #define PG8_STAGE(bufoff, gbase, voff) do { _Pragma("unroll") for (int _i = 0; _i < 2; ++_i) \
;         __builtin_amdgcn_global_load_lds((const unsigned*)((const char*)(gbase) + (voff)[_i]), (PG8_LAS unsigned*)(lds + (bufoff) + ldsw + _i * 8192), 16, 0, 0); } while (0)
; #define PG8_LDA(dst, b, h) do { _Pragma("unroll") for (int m = 0; m < 4; ++m) _Pragma("unroll") for (int k = 0; k < 2; ++k) dst[m][k] = *(const PG8_LAS bf16x8*)(lds + PG8_SA(b, h) + aoff + m * 2048 + k * 1024); } while (0)
; #define PG8_MMA(ai, bj, At, Bt) do { __builtin_amdgcn_s_setprio(1); _Pragma("unroll") for (int m = 0; m < 4; ++m) _Pragma("unroll") for (int n = 0; n < 2; ++n) _Pragma("unroll") for (int k = 0; k < 2; ++k) \
;         acc[ai][bj][m][n] = __builtin_amdgcn_mfma_f32_16x16x32_bf16(Bt[n][k], At[m][k], acc[ai][bj][m][n], 0, 0, 0); __builtin_amdgcn_s_setprio(0); } while (0)
; #define PG8_WAIT_V(n) asm volatile("s_waitcnt vmcnt(" #n ")" ::: "memory")
; #define PG8_WAIT_L(n) asm volatile("s_waitcnt lgkmcnt(" #n ")" ::: "memory")
; #define PG8_BAR __builtin_amdgcn_s_barrier()
; #define PG8_SCHED __builtin_amdgcn_sched_barrier(0)
; template <class Epi, class Sched, bool ALIGN_EPI = false, bool SP2 = false>
; __device__ __forceinline__ void gemm_phase(PG8_LAS unsigned char* lds, const Gemm g, const Sched& S, const Epi& E) {
;     ...
;         for (int t = 0; t < nt; t += 2) {
;             const bool last = (t == nt - 2);
;     ...
;             PG8_LDA(At, 1, 1); PG8_STAGE(PG8_SB(1, 0), b3, voffB); PG8_STAGE(PG8_SB(1, 1), b3 + hstepB, voffB); PG8_STAGE(PG8_SA(1, 0), a3, voffA);
;             PG8_WAIT_V(8); PG8_WAIT_L(0); PG8_BAR; PG8_MMA(1, 0, At, B0); PG8_MMA(1, 1, At, B1); PG8_BAR; PG8_SCHED;
	s_add_i32 s4, s4, s47
	v_lshl_add_u64 v[164:165], v[164:165], 0, s[16:17]
	s_mov_b32 m0, s4
	ds_read_b128 v[184:187], v151 offset:49152
	ds_read_b128 v[188:191], v151 offset:50176
	ds_read_b128 v[192:195], v151 offset:51200
	ds_read_b128 v[196:199], v151 offset:52224
	ds_read_b128 v[200:203], v151 offset:53248
	ds_read_b128 v[204:207], v151 offset:54272
	ds_read_b128 v[208:211], v151 offset:55296
	ds_read_b128 v[212:215], v151 offset:56320
	global_load_lds_dwordx4 v[164:165], off
	s_add_i32 m0, s4, 0x2000
	s_add_u32 s34, s34, 0x80080
	v_lshl_add_u64 v[164:165], v[216:217], 0, s[16:17]
	s_addc_u32 s35, s35, 0
	s_add_i32 s4, s5, s47
	global_load_lds_dwordx4 v[164:165], off
	v_lshl_add_u64 v[164:165], s[34:35], 0, v[130:131]
	s_mov_b32 m0, s4
	s_nop 0
	global_load_lds_dwordx4 v[164:165], off
	v_lshl_add_u64 v[164:165], s[34:35], 0, v[134:135]
	s_add_i32 m0, s4, 0x2000
	s_nop 0
	global_load_lds_dwordx4 v[164:165], off
	v_lshl_add_u64 v[164:165], v[218:219], 0, s[16:17]
	s_mov_b32 m0, s40
	s_nop 0
	global_load_lds_dwordx4 v[164:165], off
	v_lshl_add_u64 v[164:165], v[220:221], 0, s[16:17]
	s_mov_b32 m0, s41
	s_nop 0
	global_load_lds_dwordx4 v[164:165], off
	s_waitcnt vmcnt(8)
	s_waitcnt lgkmcnt(0)
	s_barrier
	s_setprio 1
	s_waitcnt lgkmcnt(0)
	v_mfma_f32_16x16x32_bf16 v[60:63], v[144:147], v[184:187], v[60:63]
	v_mfma_f32_16x16x32_bf16 v[56:59], v[156:159], v[184:187], v[56:59]
	v_mfma_f32_16x16x32_bf16 v[44:47], v[144:147], v[192:195], v[44:47]
	v_mfma_f32_16x16x32_bf16 v[40:43], v[156:159], v[192:195], v[40:43]
	v_mfma_f32_16x16x32_bf16 v[28:31], v[144:147], v[200:203], v[28:31]
	v_mfma_f32_16x16x32_bf16 v[24:27], v[156:159], v[200:203], v[24:27]
	v_mfma_f32_16x16x32_bf16 v[12:15], v[144:147], v[208:211], v[12:15]
	v_mfma_f32_16x16x32_bf16 v[8:11], v[156:159], v[208:211], v[8:11]
	v_mfma_f32_16x16x32_bf16 v[60:63], v[152:155], v[188:191], v[60:63]
	v_mfma_f32_16x16x32_bf16 v[56:59], v[160:163], v[188:191], v[56:59]
	v_mfma_f32_16x16x32_bf16 v[44:47], v[152:155], v[196:199], v[44:47]
	v_mfma_f32_16x16x32_bf16 v[40:43], v[160:163], v[196:199], v[40:43]
	v_mfma_f32_16x16x32_bf16 v[28:31], v[152:155], v[204:207], v[28:31]
	v_mfma_f32_16x16x32_bf16 v[24:27], v[160:163], v[204:207], v[24:27]
	v_mfma_f32_16x16x32_bf16 v[12:15], v[152:155], v[212:215], v[12:15]
	v_mfma_f32_16x16x32_bf16 v[8:11], v[160:163], v[212:215], v[8:11]
	v_mfma_f32_16x16x32_bf16 v[52:55], v[168:171], v[184:187], v[52:55]
	v_mfma_f32_16x16x32_bf16 v[48:51], v[176:179], v[184:187], v[48:51]
	v_mfma_f32_16x16x32_bf16 v[36:39], v[168:171], v[192:195], v[36:39]
	v_mfma_f32_16x16x32_bf16 v[32:35], v[176:179], v[192:195], v[32:35]
	v_mfma_f32_16x16x32_bf16 v[20:23], v[168:171], v[200:203], v[20:23]
	v_mfma_f32_16x16x32_bf16 v[16:19], v[176:179], v[200:203], v[16:19]
	v_mfma_f32_16x16x32_bf16 v[4:7], v[168:171], v[208:211], v[4:7]
	v_mfma_f32_16x16x32_bf16 v[0:3], v[176:179], v[208:211], v[0:3]
	v_mfma_f32_16x16x32_bf16 v[52:55], v[172:175], v[188:191], v[52:55]
	v_mfma_f32_16x16x32_bf16 v[48:51], v[180:183], v[188:191], v[48:51]
	v_mfma_f32_16x16x32_bf16 v[36:39], v[172:175], v[196:199], v[36:39]
	v_mfma_f32_16x16x32_bf16 v[32:35], v[180:183], v[196:199], v[32:35]
	v_mfma_f32_16x16x32_bf16 v[20:23], v[172:175], v[204:207], v[20:23]
	v_mfma_f32_16x16x32_bf16 v[16:19], v[180:183], v[204:207], v[16:19]
	v_mfma_f32_16x16x32_bf16 v[4:7], v[172:175], v[212:215], v[4:7]
	v_mfma_f32_16x16x32_bf16 v[0:3], v[180:183], v[212:215], v[0:3]
	s_setprio 0
	s_barrier
	s_add_i32 s56, s56, 2
	s_add_u32 s30, s30, 0x100
	s_addc_u32 s31, s31, 0
	s_add_u32 s54, s54, 0x100
	s_addc_u32 s55, s55, 0
	s_cmp_gt_u32 s56, 29
	s_cbranch_scc0 .LBB0_660
	s_and_b64 vcc, exec, s[48:49]
	s_cbranch_vccz .LBB0_663
	s_barrier

; #define PG8_STAGE(bufoff, gbase, voff) do { _Pragma("unroll") for (int _i = 0; _i < 2; ++_i) \
;         __builtin_amdgcn_global_load_lds((const unsigned*)((const char*)(gbase) + (voff)[_i]), (PG8_LAS unsigned*)(lds + (bufoff) + ldsw + _i * 8192), 16, 0, 0); } while (0)
; #define PG8_LDA(dst, b, h) do { _Pragma("unroll") for (int m = 0; m < 4; ++m) _Pragma("unroll") for (int k = 0; k < 2; ++k) dst[m][k] = *(const PG8_LAS bf16x8*)(lds + PG8_SA(b, h) + aoff + m * 2048 + k * 1024); } while (0)
; #define PG8_LDB(dst, b, h) do { _Pragma("unroll") for (int n = 0; n < 2; ++n) _Pragma("unroll") for (int k = 0; k < 2; ++k) dst[n][k] = *(const PG8_LAS bf16x8*)(lds + PG8_SB(b, h) + boff + n * 2048 + k * 1024); } while (0)
; #define PG8_MMA(ai, bj, At, Bt) do { __builtin_amdgcn_s_setprio(1); _Pragma("unroll") for (int m = 0; m < 4; ++m) _Pragma("unroll") for (int n = 0; n < 2; ++n) _Pragma("unroll") for (int k = 0; k < 2; ++k) \
;         acc[ai][bj][m][n] = __builtin_amdgcn_mfma_f32_16x16x32_bf16(Bt[n][k], At[m][k], acc[ai][bj][m][n], 0, 0, 0); __builtin_amdgcn_s_setprio(0); } while (0)
; #define PG8_WAIT_V(n) asm volatile("s_waitcnt vmcnt(" #n ")" ::: "memory")
; #define PG8_WAIT_L(n) asm volatile("s_waitcnt lgkmcnt(" #n ")" ::: "memory")
; #define PG8_BAR __builtin_amdgcn_s_barrier()
; #define PG8_SCHED __builtin_amdgcn_sched_barrier(0)
; template <class Epi, class Sched, bool ALIGN_EPI = false, bool SP2 = false>
; __device__ __forceinline__ void gemm_phase(PG8_LAS unsigned char* lds, const Gemm g, const Sched& S, const Epi& E) {
;     ...
;             const bool last = (t == nt - 2);
;             const char* a1 = cA + (size_t)(t + 1) * kstep;
;             const char* a2 = last ? nA : cA + (size_t)(t + 2) * kstep; const char* b2 = last ? nB : cB + (size_t)(t + 2) * kstep;
;             const char* a3 = a2 + kstep; const char* b3 = b2 + kstep;
;     ...
;             PG8_LDB(B0, 0, 0); PG8_LDB(B1, 0, 1); PG8_SCHED; PG8_LDA(At, 0, 0); PG8_STAGE(PG8_SA(1, 1), a1 + hstepA, voffA);
;             PG8_WAIT_V(8); PG8_WAIT_L(0); PG8_BAR; PG8_MMA(0, 0, At, B0); PG8_MMA(0, 1, At, B1); PG8_BAR; PG8_SCHED;
;             PG8_LDA(At, 0, 1); PG8_STAGE(PG8_SB(0, 0), b2, voffB); PG8_STAGE(PG8_SB(0, 1), b2 + hstepB, voffB); PG8_STAGE(PG8_SA(0, 0), a2, voffA);
;             PG8_WAIT_V(8); PG8_WAIT_L(0); PG8_BAR; PG8_MMA(1, 0, At, B0); PG8_MMA(1, 1, At, B1); PG8_BAR; PG8_SCHED;
.LBB0_736:
	ds_read_b128 v[144:147], v149
	ds_read_b128 v[154:157], v149 offset:1024
	ds_read_b128 v[158:161], v149 offset:2048
	ds_read_b128 v[162:165], v149 offset:3072
	ds_read_b128 v[168:171], v150
	ds_read_b128 v[172:175], v150 offset:1024
	ds_read_b128 v[176:179], v150 offset:2048
	ds_read_b128 v[180:183], v150 offset:3072
	s_add_u32 s4, s28, 0xfff80080
	s_addc_u32 s5, s29, -1
	s_cmp_eq_u32 s60, 28
	s_cselect_b32 s35, s19, s5
	s_cselect_b32 s34, s56, s4
	s_cselect_b32 s31, s17, s59
	s_cselect_b32 s30, s57, s58
	v_lshl_add_u64 v[216:217], s[28:29], 0, v[136:137]
	s_add_i32 m0, s27, 0xc000
	ds_read_b128 v[184:187], v151
	ds_read_b128 v[188:191], v151 offset:1024
	ds_read_b128 v[192:195], v151 offset:2048
	ds_read_b128 v[196:199], v151 offset:3072
	ds_read_b128 v[200:203], v151 offset:4096
	ds_read_b128 v[204:207], v151 offset:5120
	ds_read_b128 v[208:211], v151 offset:6144
	ds_read_b128 v[212:215], v151 offset:7168
	global_load_lds_dwordx4 v[216:217], off
	v_lshl_add_u64 v[216:217], s[28:29], 0, v[138:139]
	s_add_i32 m0, s27, 0xe000
	s_nop 0
	global_load_lds_dwordx4 v[216:217], off
	s_waitcnt vmcnt(8)
	s_waitcnt lgkmcnt(0)
	s_barrier
	s_setprio 1
	s_waitcnt lgkmcnt(0)
	v_mfma_f32_16x16x32_bf16 v[116:119], v[144:147], v[184:187], v[116:119]
	v_mfma_f32_16x16x32_bf16 v[112:115], v[158:161], v[184:187], v[112:115]
	v_mfma_f32_16x16x32_bf16 v[100:103], v[144:147], v[192:195], v[100:103]
	v_mfma_f32_16x16x32_bf16 v[96:99], v[158:161], v[192:195], v[96:99]
	v_mfma_f32_16x16x32_bf16 v[84:87], v[144:147], v[200:203], v[84:87]
	v_mfma_f32_16x16x32_bf16 v[80:83], v[158:161], v[200:203], v[80:83]
	v_mfma_f32_16x16x32_bf16 v[68:71], v[144:147], v[208:211], v[68:71]
	v_mfma_f32_16x16x32_bf16 v[64:67], v[158:161], v[208:211], v[64:67]
	v_mfma_f32_16x16x32_bf16 v[116:119], v[154:157], v[188:191], v[116:119]
	v_mfma_f32_16x16x32_bf16 v[112:115], v[162:165], v[188:191], v[112:115]
	v_mfma_f32_16x16x32_bf16 v[100:103], v[154:157], v[196:199], v[100:103]
	v_mfma_f32_16x16x32_bf16 v[96:99], v[162:165], v[196:199], v[96:99]
	v_mfma_f32_16x16x32_bf16 v[84:87], v[154:157], v[204:207], v[84:87]
	v_mfma_f32_16x16x32_bf16 v[80:83], v[162:165], v[204:207], v[80:83]
	v_mfma_f32_16x16x32_bf16 v[68:71], v[154:157], v[212:215], v[68:71]
	v_mfma_f32_16x16x32_bf16 v[64:67], v[162:165], v[212:215], v[64:67]
	v_mfma_f32_16x16x32_bf16 v[124:127], v[168:171], v[184:187], v[124:127]
	v_mfma_f32_16x16x32_bf16 v[120:123], v[176:179], v[184:187], v[120:123]
	v_mfma_f32_16x16x32_bf16 v[108:111], v[168:171], v[192:195], v[108:111]
	v_mfma_f32_16x16x32_bf16 v[104:107], v[176:179], v[192:195], v[104:107]
	v_mfma_f32_16x16x32_bf16 v[92:95], v[168:171], v[200:203], v[92:95]
	v_mfma_f32_16x16x32_bf16 v[88:91], v[176:179], v[200:203], v[88:91]
	v_mfma_f32_16x16x32_bf16 v[76:79], v[168:171], v[208:211], v[76:79]
	v_mfma_f32_16x16x32_bf16 v[72:75], v[176:179], v[208:211], v[72:75]
	v_mfma_f32_16x16x32_bf16 v[124:127], v[172:175], v[188:191], v[124:127]
	v_mfma_f32_16x16x32_bf16 v[120:123], v[180:183], v[188:191], v[120:123]
	v_mfma_f32_16x16x32_bf16 v[108:111], v[172:175], v[196:199], v[108:111]
	v_mfma_f32_16x16x32_bf16 v[104:107], v[180:183], v[196:199], v[104:107]
	v_mfma_f32_16x16x32_bf16 v[92:95], v[172:175], v[204:207], v[92:95]
	v_mfma_f32_16x16x32_bf16 v[88:91], v[180:183], v[204:207], v[88:91]
	v_mfma_f32_16x16x32_bf16 v[76:79], v[172:175], v[212:215], v[76:79]
	v_mfma_f32_16x16x32_bf16 v[72:75], v[180:183], v[212:215], v[72:75]
	s_setprio 0
	s_barrier
	s_add_i32 s4, s41, s47
	v_lshl_add_u64 v[216:217], s[30:31], 0, v[132:133]
	s_mov_b32 m0, s4
	ds_read_b128 v[184:187], v151 offset:16384
	ds_read_b128 v[188:191], v151 offset:17408
	ds_read_b128 v[192:195], v151 offset:18432
	ds_read_b128 v[196:199], v151 offset:19456
	ds_read_b128 v[200:203], v151 offset:20480
	ds_read_b128 v[204:207], v151 offset:21504
	ds_read_b128 v[208:211], v151 offset:22528
	ds_read_b128 v[212:215], v151 offset:23552
	global_load_lds_dwordx4 v[216:217], off
	s_add_i32 m0, s4, 0x2000
	s_add_u32 s4, s30, 0x80000
	v_lshl_add_u64 v[218:219], s[30:31], 0, v[128:129]
	s_addc_u32 s5, s31, 0
	s_add_i32 s61, s44, s47
	global_load_lds_dwordx4 v[218:219], off
	v_lshl_add_u64 v[220:221], s[4:5], 0, v[132:133]
	s_mov_b32 m0, s61
	v_lshl_add_u64 v[222:223], s[34:35], 0, v[130:131]
	global_load_lds_dwordx4 v[220:221], off
	v_lshl_add_u64 v[220:221], s[4:5], 0, v[128:129]
	s_add_i32 m0, s61, 0x2000
	s_nop 0
	global_load_lds_dwordx4 v[220:221], off
	v_lshl_add_u64 v[220:221], s[34:35], 0, v[134:135]
	s_mov_b32 m0, s27
	s_nop 0
	global_load_lds_dwordx4 v[220:221], off
	s_mov_b32 m0, s33
	s_nop 0
	global_load_lds_dwordx4 v[222:223], off
	s_waitcnt vmcnt(8)
	s_waitcnt lgkmcnt(0)
	s_barrier
; #define PG8_STAGE(bufoff, gbase, voff) do { _Pragma("unroll") for (int _i = 0; _i < 2; ++_i) \
;         __builtin_amdgcn_global_load_lds((const unsigned*)((const char*)(gbase) + (voff)[_i]), (PG8_LAS unsigned*)(lds + (bufoff) + ldsw + _i * 8192), 16, 0, 0); } while (0)
; #define PG8_LDA(dst, b, h) do { _Pragma("unroll") for (int m = 0; m < 4; ++m) _Pragma("unroll") for (int k = 0; k < 2; ++k) dst[m][k] = *(const PG8_LAS bf16x8*)(lds + PG8_SA(b, h) + aoff + m * 2048 + k * 1024); } while (0)
; #define PG8_LDB(dst, b, h) do { _Pragma("unroll") for (int n = 0; n < 2; ++n) _Pragma("unroll") for (int k = 0; k < 2; ++k) dst[n][k] = *(const PG8_LAS bf16x8*)(lds + PG8_SB(b, h) + boff + n * 2048 + k * 1024); } while (0)
; #define PG8_MMA(ai, bj, At, Bt) do { __builtin_amdgcn_s_setprio(1); _Pragma("unroll") for (int m = 0; m < 4; ++m) _Pragma("unroll") for (int n = 0; n < 2; ++n) _Pragma("unroll") for (int k = 0; k < 2; ++k) \
;         acc[ai][bj][m][n] = __builtin_amdgcn_mfma_f32_16x16x32_bf16(Bt[n][k], At[m][k], acc[ai][bj][m][n], 0, 0, 0); __builtin_amdgcn_s_setprio(0); } while (0)
; #define PG8_WAIT_V(n) asm volatile("s_waitcnt vmcnt(" #n ")" ::: "memory")
; #define PG8_WAIT_L(n) asm volatile("s_waitcnt lgkmcnt(" #n ")" ::: "memory")
; #define PG8_BAR __builtin_amdgcn_s_barrier()
; #define PG8_SCHED __builtin_amdgcn_sched_barrier(0)
; template <class Epi, class Sched, bool ALIGN_EPI = false, bool SP2 = false>
; __device__ __forceinline__ void gemm_phase(PG8_LAS unsigned char* lds, const Gemm g, const Sched& S, const Epi& E) {
;     ...
;             PG8_WAIT_V(8); PG8_WAIT_L(0); PG8_BAR; PG8_MMA(1, 0, At, B0); PG8_MMA(1, 1, At, B1); PG8_BAR; PG8_SCHED;
;             PG8_LDB(B0, 1, 0); PG8_LDB(B1, 1, 1); PG8_SCHED; PG8_LDA(At, 1, 0); PG8_STAGE(PG8_SA(0, 1), a2 + hstepA, voffA);
;             PG8_WAIT_V(8); PG8_WAIT_L(0); PG8_BAR; PG8_MMA(0, 0, At, B0); PG8_MMA(0, 1, At, B1); PG8_BAR; PG8_SCHED;
	s_setprio 1
	s_waitcnt lgkmcnt(0)
	v_mfma_f32_16x16x32_bf16 v[52:55], v[144:147], v[184:187], v[52:55]
	v_mfma_f32_16x16x32_bf16 v[48:51], v[158:161], v[184:187], v[48:51]
	v_mfma_f32_16x16x32_bf16 v[36:39], v[144:147], v[192:195], v[36:39]
	v_mfma_f32_16x16x32_bf16 v[32:35], v[158:161], v[192:195], v[32:35]
	v_mfma_f32_16x16x32_bf16 v[20:23], v[144:147], v[200:203], v[20:23]
	v_mfma_f32_16x16x32_bf16 v[16:19], v[158:161], v[200:203], v[16:19]
	v_mfma_f32_16x16x32_bf16 v[8:11], v[144:147], v[208:211], v[8:11]
	v_mfma_f32_16x16x32_bf16 v[4:7], v[158:161], v[208:211], v[4:7]
	v_mfma_f32_16x16x32_bf16 v[52:55], v[154:157], v[188:191], v[52:55]
	v_mfma_f32_16x16x32_bf16 v[48:51], v[162:165], v[188:191], v[48:51]
	v_mfma_f32_16x16x32_bf16 v[36:39], v[154:157], v[196:199], v[36:39]
	v_mfma_f32_16x16x32_bf16 v[32:35], v[162:165], v[196:199], v[32:35]
	v_mfma_f32_16x16x32_bf16 v[20:23], v[154:157], v[204:207], v[20:23]
	v_mfma_f32_16x16x32_bf16 v[16:19], v[162:165], v[204:207], v[16:19]
	v_mfma_f32_16x16x32_bf16 v[8:11], v[154:157], v[212:215], v[8:11]
	v_mfma_f32_16x16x32_bf16 v[4:7], v[162:165], v[212:215], v[4:7]
	v_mfma_f32_16x16x32_bf16 v[60:63], v[168:171], v[184:187], v[60:63]
	v_mfma_f32_16x16x32_bf16 v[56:59], v[176:179], v[184:187], v[56:59]
	v_mfma_f32_16x16x32_bf16 v[44:47], v[168:171], v[192:195], v[44:47]
	v_mfma_f32_16x16x32_bf16 v[40:43], v[176:179], v[192:195], v[40:43]
	v_mfma_f32_16x16x32_bf16 v[28:31], v[168:171], v[200:203], v[28:31]
	v_mfma_f32_16x16x32_bf16 v[24:27], v[176:179], v[200:203], v[24:27]
	v_mfma_f32_16x16x32_bf16 v[12:15], v[168:171], v[208:211], v[12:15]
	v_mfma_f32_16x16x32_bf16 v[0:3], v[176:179], v[208:211], v[0:3]
	v_mfma_f32_16x16x32_bf16 v[60:63], v[172:175], v[188:191], v[60:63]
	v_mfma_f32_16x16x32_bf16 v[56:59], v[180:183], v[188:191], v[56:59]
	v_mfma_f32_16x16x32_bf16 v[44:47], v[172:175], v[196:199], v[44:47]
	v_mfma_f32_16x16x32_bf16 v[40:43], v[180:183], v[196:199], v[40:43]
	v_mfma_f32_16x16x32_bf16 v[28:31], v[172:175], v[204:207], v[28:31]
	v_mfma_f32_16x16x32_bf16 v[24:27], v[180:183], v[204:207], v[24:27]
	v_mfma_f32_16x16x32_bf16 v[12:15], v[172:175], v[212:215], v[12:15]
	v_mfma_f32_16x16x32_bf16 v[0:3], v[180:183], v[212:215], v[0:3]
	s_setprio 0
	s_barrier
	s_add_i32 s61, 0, 0x18000
	v_add_u32_e32 v153, s61, v148
	s_add_i32 s62, 0, 0x1c000
	ds_read_b128 v[144:147], v153
	ds_read_b128 v[154:157], v153 offset:1024
	ds_read_b128 v[158:161], v153 offset:2048
	ds_read_b128 v[162:165], v153 offset:3072
	v_add_u32_e32 v153, s62, v148
	ds_read_b128 v[168:171], v153
	ds_read_b128 v[172:175], v153 offset:1024
	ds_read_b128 v[176:179], v153 offset:2048
	ds_read_b128 v[180:183], v153 offset:3072
	s_add_u32 s4, s34, 0x80000
	s_addc_u32 s5, s35, 0
	s_mov_b32 m0, s36
	v_lshl_add_u64 v[224:225], s[4:5], 0, v[134:135]
	ds_read_b128 v[184:187], v151 offset:32768
	ds_read_b128 v[188:191], v151 offset:33792
	ds_read_b128 v[192:195], v151 offset:34816
	ds_read_b128 v[196:199], v151 offset:35840
	ds_read_b128 v[200:203], v151 offset:36864
	ds_read_b128 v[204:207], v151 offset:37888
	ds_read_b128 v[208:211], v151 offset:38912
	ds_read_b128 v[212:215], v151 offset:39936
	global_load_lds_dwordx4 v[224:225], off
	v_lshl_add_u64 v[224:225], s[4:5], 0, v[130:131]
	s_mov_b32 m0, s37
	s_nop 0
	global_load_lds_dwordx4 v[224:225], off
	s_waitcnt vmcnt(8)
	s_waitcnt lgkmcnt(0)
	s_barrier
	s_setprio 1
	s_waitcnt lgkmcnt(0)
	v_mfma_f32_16x16x32_bf16 v[116:119], v[144:147], v[184:187], v[116:119]
	v_mfma_f32_16x16x32_bf16 v[112:115], v[158:161], v[184:187], v[112:115]
	v_mfma_f32_16x16x32_bf16 v[100:103], v[144:147], v[192:195], v[100:103]
	v_mfma_f32_16x16x32_bf16 v[96:99], v[158:161], v[192:195], v[96:99]
	v_mfma_f32_16x16x32_bf16 v[84:87], v[144:147], v[200:203], v[84:87]
	v_mfma_f32_16x16x32_bf16 v[80:83], v[158:161], v[200:203], v[80:83]
	v_mfma_f32_16x16x32_bf16 v[68:71], v[144:147], v[208:211], v[68:71]
	v_mfma_f32_16x16x32_bf16 v[64:67], v[158:161], v[208:211], v[64:67]
	v_mfma_f32_16x16x32_bf16 v[116:119], v[154:157], v[188:191], v[116:119]
	v_mfma_f32_16x16x32_bf16 v[112:115], v[162:165], v[188:191], v[112:115]
	v_mfma_f32_16x16x32_bf16 v[100:103], v[154:157], v[196:199], v[100:103]
	v_mfma_f32_16x16x32_bf16 v[96:99], v[162:165], v[196:199], v[96:99]
	v_mfma_f32_16x16x32_bf16 v[84:87], v[154:157], v[204:207], v[84:87]
	v_mfma_f32_16x16x32_bf16 v[80:83], v[162:165], v[204:207], v[80:83]
	v_mfma_f32_16x16x32_bf16 v[68:71], v[154:157], v[212:215], v[68:71]
	v_mfma_f32_16x16x32_bf16 v[64:67], v[162:165], v[212:215], v[64:67]
	v_mfma_f32_16x16x32_bf16 v[124:127], v[168:171], v[184:187], v[124:127]
	v_mfma_f32_16x16x32_bf16 v[120:123], v[176:179], v[184:187], v[120:123]
	v_mfma_f32_16x16x32_bf16 v[108:111], v[168:171], v[192:195], v[108:111]
	v_mfma_f32_16x16x32_bf16 v[104:107], v[176:179], v[192:195], v[104:107]
	v_mfma_f32_16x16x32_bf16 v[92:95], v[168:171], v[200:203], v[92:95]
	v_mfma_f32_16x16x32_bf16 v[88:91], v[176:179], v[200:203], v[88:91]
	v_mfma_f32_16x16x32_bf16 v[76:79], v[168:171], v[208:211], v[76:79]
	v_mfma_f32_16x16x32_bf16 v[72:75], v[176:179], v[208:211], v[72:75]
	v_mfma_f32_16x16x32_bf16 v[124:127], v[172:175], v[188:191], v[124:127]
	v_mfma_f32_16x16x32_bf16 v[120:123], v[180:183], v[188:191], v[120:123]
	v_mfma_f32_16x16x32_bf16 v[108:111], v[172:175], v[196:199], v[108:111]
	v_mfma_f32_16x16x32_bf16 v[104:107], v[180:183], v[196:199], v[104:107]
	v_mfma_f32_16x16x32_bf16 v[92:95], v[172:175], v[204:207], v[92:95]
	v_mfma_f32_16x16x32_bf16 v[88:91], v[180:183], v[204:207], v[88:91]
	v_mfma_f32_16x16x32_bf16 v[76:79], v[172:175], v[212:215], v[76:79]
	v_mfma_f32_16x16x32_bf16 v[72:75], v[180:183], v[212:215], v[72:75]
	s_setprio 0
	s_barrier
; #define PG8_STAGE(bufoff, gbase, voff) do { _Pragma("unroll") for (int _i = 0; _i < 2; ++_i) \
;         __builtin_amdgcn_global_load_lds((const unsigned*)((const char*)(gbase) + (voff)[_i]), (PG8_LAS unsigned*)(lds + (bufoff) + ldsw + _i * 8192), 16, 0, 0); } while (0)
; #define PG8_LDA(dst, b, h) do { _Pragma("unroll") for (int m = 0; m < 4; ++m) _Pragma("unroll") for (int k = 0; k < 2; ++k) dst[m][k] = *(const PG8_LAS bf16x8*)(lds + PG8_SA(b, h) + aoff + m * 2048 + k * 1024); } while (0)
; #define PG8_MMA(ai, bj, At, Bt) do { __builtin_amdgcn_s_setprio(1); _Pragma("unroll") for (int m = 0; m < 4; ++m) _Pragma("unroll") for (int n = 0; n < 2; ++n) _Pragma("unroll") for (int k = 0; k < 2; ++k) \
;         acc[ai][bj][m][n] = __builtin_amdgcn_mfma_f32_16x16x32_bf16(Bt[n][k], At[m][k], acc[ai][bj][m][n], 0, 0, 0); __builtin_amdgcn_s_setprio(0); } while (0)
; #define PG8_WAIT_V(n) asm volatile("s_waitcnt vmcnt(" #n ")" ::: "memory")
; #define PG8_WAIT_L(n) asm volatile("s_waitcnt lgkmcnt(" #n ")" ::: "memory")
; #define PG8_BAR __builtin_amdgcn_s_barrier()
; #define PG8_SCHED __builtin_amdgcn_sched_barrier(0)
; template <class Epi, class Sched, bool ALIGN_EPI = false, bool SP2 = false>
; __device__ __forceinline__ void gemm_phase(PG8_LAS unsigned char* lds, const Gemm g, const Sched& S, const Epi& E) {
;     ...
;         for (int t = 0; t < nt; t += 2) {
;             const bool last = (t == nt - 2);
;     ...
;             PG8_LDA(At, 1, 1); PG8_STAGE(PG8_SB(1, 0), b3, voffB); PG8_STAGE(PG8_SB(1, 1), b3 + hstepB, voffB); PG8_STAGE(PG8_SA(1, 0), a3, voffA);
;             PG8_WAIT_V(8); PG8_WAIT_L(0); PG8_BAR; PG8_MMA(1, 0, At, B0); PG8_MMA(1, 1, At, B1); PG8_BAR; PG8_SCHED;
	s_add_i32 s4, s61, s47
	v_lshl_add_u64 v[216:217], v[216:217], 0, s[14:15]
	s_mov_b32 m0, s4
	ds_read_b128 v[184:187], v151 offset:49152
	ds_read_b128 v[188:191], v151 offset:50176
	ds_read_b128 v[192:195], v151 offset:51200
	ds_read_b128 v[196:199], v151 offset:52224
	ds_read_b128 v[200:203], v151 offset:53248
	ds_read_b128 v[204:207], v151 offset:54272
	ds_read_b128 v[208:211], v151 offset:55296
	ds_read_b128 v[212:215], v151 offset:56320
	global_load_lds_dwordx4 v[216:217], off
	s_add_i32 m0, s4, 0x2000
	s_add_u32 s4, s30, 0x80080
	v_lshl_add_u64 v[216:217], v[218:219], 0, s[14:15]
	s_addc_u32 s5, s31, 0
	s_add_i32 s30, s62, s47
	global_load_lds_dwordx4 v[216:217], off
	v_lshl_add_u64 v[216:217], s[4:5], 0, v[132:133]
	s_mov_b32 m0, s30
	s_nop 0
	global_load_lds_dwordx4 v[216:217], off
	v_lshl_add_u64 v[216:217], s[4:5], 0, v[128:129]
	s_add_i32 m0, s30, 0x2000
	s_nop 0
	global_load_lds_dwordx4 v[216:217], off
	v_lshl_add_u64 v[216:217], v[220:221], 0, s[14:15]
	s_mov_b32 m0, s39
	s_nop 0
	global_load_lds_dwordx4 v[216:217], off
	v_lshl_add_u64 v[216:217], v[222:223], 0, s[14:15]
	s_mov_b32 m0, s40
	s_nop 0
	global_load_lds_dwordx4 v[216:217], off
	s_waitcnt vmcnt(8)
	s_waitcnt lgkmcnt(0)
	s_barrier
	s_setprio 1
	s_waitcnt lgkmcnt(0)
	v_mfma_f32_16x16x32_bf16 v[52:55], v[144:147], v[184:187], v[52:55]
	v_mfma_f32_16x16x32_bf16 v[48:51], v[158:161], v[184:187], v[48:51]
	v_mfma_f32_16x16x32_bf16 v[36:39], v[144:147], v[192:195], v[36:39]
	v_mfma_f32_16x16x32_bf16 v[32:35], v[158:161], v[192:195], v[32:35]
	v_mfma_f32_16x16x32_bf16 v[20:23], v[144:147], v[200:203], v[20:23]
	v_mfma_f32_16x16x32_bf16 v[16:19], v[158:161], v[200:203], v[16:19]
	v_mfma_f32_16x16x32_bf16 v[8:11], v[144:147], v[208:211], v[8:11]
	v_mfma_f32_16x16x32_bf16 v[4:7], v[158:161], v[208:211], v[4:7]
	v_mfma_f32_16x16x32_bf16 v[52:55], v[154:157], v[188:191], v[52:55]
	v_mfma_f32_16x16x32_bf16 v[48:51], v[162:165], v[188:191], v[48:51]
	v_mfma_f32_16x16x32_bf16 v[36:39], v[154:157], v[196:199], v[36:39]
	v_mfma_f32_16x16x32_bf16 v[32:35], v[162:165], v[196:199], v[32:35]
	v_mfma_f32_16x16x32_bf16 v[20:23], v[154:157], v[204:207], v[20:23]
	v_mfma_f32_16x16x32_bf16 v[16:19], v[162:165], v[204:207], v[16:19]
	v_mfma_f32_16x16x32_bf16 v[8:11], v[154:157], v[212:215], v[8:11]
	v_mfma_f32_16x16x32_bf16 v[4:7], v[162:165], v[212:215], v[4:7]
	v_mfma_f32_16x16x32_bf16 v[60:63], v[168:171], v[184:187], v[60:63]
	v_mfma_f32_16x16x32_bf16 v[56:59], v[176:179], v[184:187], v[56:59]
	v_mfma_f32_16x16x32_bf16 v[44:47], v[168:171], v[192:195], v[44:47]
	v_mfma_f32_16x16x32_bf16 v[40:43], v[176:179], v[192:195], v[40:43]
	v_mfma_f32_16x16x32_bf16 v[28:31], v[168:171], v[200:203], v[28:31]
	v_mfma_f32_16x16x32_bf16 v[24:27], v[176:179], v[200:203], v[24:27]
	v_mfma_f32_16x16x32_bf16 v[12:15], v[168:171], v[208:211], v[12:15]
	v_mfma_f32_16x16x32_bf16 v[0:3], v[176:179], v[208:211], v[0:3]
	v_mfma_f32_16x16x32_bf16 v[60:63], v[172:175], v[188:191], v[60:63]
	v_mfma_f32_16x16x32_bf16 v[56:59], v[180:183], v[188:191], v[56:59]
	v_mfma_f32_16x16x32_bf16 v[44:47], v[172:175], v[196:199], v[44:47]
	v_mfma_f32_16x16x32_bf16 v[40:43], v[180:183], v[196:199], v[40:43]
	v_mfma_f32_16x16x32_bf16 v[28:31], v[172:175], v[204:207], v[28:31]
	v_mfma_f32_16x16x32_bf16 v[24:27], v[180:183], v[204:207], v[24:27]
	v_mfma_f32_16x16x32_bf16 v[12:15], v[172:175], v[212:215], v[12:15]
	v_mfma_f32_16x16x32_bf16 v[0:3], v[180:183], v[212:215], v[0:3]
	s_setprio 0
	s_barrier
	s_add_i32 s60, s60, 2
	s_add_u32 s28, s28, 0x100
	s_addc_u32 s29, s29, 0
	s_add_u32 s58, s58, 0x100
	s_addc_u32 s59, s59, 0
	s_cmp_gt_u32 s60, 29
	s_cbranch_scc0 .LBB0_736
	s_and_b64 vcc, exec, s[48:49]
	s_cbranch_vccz .LBB0_739
	s_barrier

; #define PG8_STAGE(bufoff, gbase, voff) do { _Pragma("unroll") for (int _i = 0; _i < 2; ++_i) \
;         __builtin_amdgcn_global_load_lds((const unsigned*)((const char*)(gbase) + (voff)[_i]), (PG8_LAS unsigned*)(lds + (bufoff) + ldsw + _i * 8192), 16, 0, 0); } while (0)
; #define PG8_LDA(dst, b, h) do { _Pragma("unroll") for (int m = 0; m < 4; ++m) _Pragma("unroll") for (int k = 0; k < 2; ++k) dst[m][k] = *(const PG8_LAS bf16x8*)(lds + PG8_SA(b, h) + aoff + m * 2048 + k * 1024); } while (0)
; #define PG8_LDB(dst, b, h) do { _Pragma("unroll") for (int n = 0; n < 2; ++n) _Pragma("unroll") for (int k = 0; k < 2; ++k) dst[n][k] = *(const PG8_LAS bf16x8*)(lds + PG8_SB(b, h) + boff + n * 2048 + k * 1024); } while (0)
; #define PG8_MMA(ai, bj, At, Bt) do { __builtin_amdgcn_s_setprio(1); _Pragma("unroll") for (int m = 0; m < 4; ++m) _Pragma("unroll") for (int n = 0; n < 2; ++n) _Pragma("unroll") for (int k = 0; k < 2; ++k) \
;         acc[ai][bj][m][n] = __builtin_amdgcn_mfma_f32_16x16x32_bf16(Bt[n][k], At[m][k], acc[ai][bj][m][n], 0, 0, 0); __builtin_amdgcn_s_setprio(0); } while (0)
; #define PG8_WAIT_V(n) asm volatile("s_waitcnt vmcnt(" #n ")" ::: "memory")
; #define PG8_WAIT_L(n) asm volatile("s_waitcnt lgkmcnt(" #n ")" ::: "memory")
; #define PG8_BAR __builtin_amdgcn_s_barrier()
; #define PG8_SCHED __builtin_amdgcn_sched_barrier(0)
; template <class Epi, class Sched, bool ALIGN_EPI = false, bool SP2 = false>
; __device__ __forceinline__ void gemm_phase(PG8_LAS unsigned char* lds, const Gemm g, const Sched& S, const Epi& E) {
;     ...
;             const bool last = (t == nt - 2);
;             const char* a1 = cA + (size_t)(t + 1) * kstep;
;             const char* a2 = last ? nA : cA + (size_t)(t + 2) * kstep; const char* b2 = last ? nB : cB + (size_t)(t + 2) * kstep;
;             const char* a3 = a2 + kstep; const char* b3 = b2 + kstep;
;     ...
;             PG8_LDB(B0, 0, 0); PG8_LDB(B1, 0, 1); PG8_SCHED; PG8_LDA(At, 0, 0); PG8_STAGE(PG8_SA(1, 1), a1 + hstepA, voffA);
;             PG8_WAIT_V(8); PG8_WAIT_L(0); PG8_BAR; PG8_MMA(0, 0, At, B0); PG8_MMA(0, 1, At, B1); PG8_BAR; PG8_SCHED;
;             PG8_LDA(At, 0, 1); PG8_STAGE(PG8_SB(0, 0), b2, voffB); PG8_STAGE(PG8_SB(0, 1), b2 + hstepB, voffB); PG8_STAGE(PG8_SA(0, 0), a2, voffA);
;             PG8_WAIT_V(8); PG8_WAIT_L(0); PG8_BAR; PG8_MMA(1, 0, At, B0); PG8_MMA(1, 1, At, B1); PG8_BAR; PG8_SCHED;
.LBB0_810:
	ds_read_b128 v[144:147], v149
	ds_read_b128 v[152:155], v149 offset:1024
	ds_read_b128 v[156:159], v149 offset:2048
	ds_read_b128 v[160:163], v149 offset:3072
	ds_read_b128 v[168:171], v150
	ds_read_b128 v[172:175], v150 offset:1024
	ds_read_b128 v[176:179], v150 offset:2048
	ds_read_b128 v[180:183], v150 offset:3072
	s_add_u32 s26, s22, 0x100
	s_addc_u32 s27, s23, 0
	s_cmpk_eq_i32 s56, 0x54
	s_cselect_b32 s31, s11, s27
	s_cselect_b32 s30, s10, s26
	s_cselect_b32 s29, s21, s55
	s_cselect_b32 s28, s20, s54
	v_lshl_add_u64 v[164:165], s[22:23], 0, v[136:137]
	s_add_i32 m0, s25, 0xc000
	ds_read_b128 v[184:187], v151
	ds_read_b128 v[188:191], v151 offset:1024
	ds_read_b128 v[192:195], v151 offset:2048
	ds_read_b128 v[196:199], v151 offset:3072
	ds_read_b128 v[200:203], v151 offset:4096
	ds_read_b128 v[204:207], v151 offset:5120
	ds_read_b128 v[208:211], v151 offset:6144
	ds_read_b128 v[212:215], v151 offset:7168
	global_load_lds_dwordx4 v[164:165], off
	v_lshl_add_u64 v[164:165], s[22:23], 0, v[138:139]
	s_add_i32 m0, s25, 0xe000
	s_nop 0
	global_load_lds_dwordx4 v[164:165], off
	s_waitcnt vmcnt(8)
	s_waitcnt lgkmcnt(0)
	s_barrier
	s_setprio 1
	s_waitcnt lgkmcnt(0)
	v_mfma_f32_16x16x32_bf16 v[124:127], v[144:147], v[184:187], v[124:127]
	v_mfma_f32_16x16x32_bf16 v[120:123], v[156:159], v[184:187], v[120:123]
	v_mfma_f32_16x16x32_bf16 v[108:111], v[144:147], v[192:195], v[108:111]
	v_mfma_f32_16x16x32_bf16 v[104:107], v[156:159], v[192:195], v[104:107]
	v_mfma_f32_16x16x32_bf16 v[92:95], v[144:147], v[200:203], v[92:95]
	v_mfma_f32_16x16x32_bf16 v[88:91], v[156:159], v[200:203], v[88:91]
	v_mfma_f32_16x16x32_bf16 v[76:79], v[144:147], v[208:211], v[76:79]
	v_mfma_f32_16x16x32_bf16 v[72:75], v[156:159], v[208:211], v[72:75]
	v_mfma_f32_16x16x32_bf16 v[124:127], v[152:155], v[188:191], v[124:127]
	v_mfma_f32_16x16x32_bf16 v[120:123], v[160:163], v[188:191], v[120:123]
	v_mfma_f32_16x16x32_bf16 v[108:111], v[152:155], v[196:199], v[108:111]
	v_mfma_f32_16x16x32_bf16 v[104:107], v[160:163], v[196:199], v[104:107]
	v_mfma_f32_16x16x32_bf16 v[92:95], v[152:155], v[204:207], v[92:95]
	v_mfma_f32_16x16x32_bf16 v[88:91], v[160:163], v[204:207], v[88:91]
	v_mfma_f32_16x16x32_bf16 v[76:79], v[152:155], v[212:215], v[76:79]
	v_mfma_f32_16x16x32_bf16 v[72:75], v[160:163], v[212:215], v[72:75]
	v_mfma_f32_16x16x32_bf16 v[116:119], v[168:171], v[184:187], v[116:119]
	v_mfma_f32_16x16x32_bf16 v[112:115], v[176:179], v[184:187], v[112:115]
	v_mfma_f32_16x16x32_bf16 v[100:103], v[168:171], v[192:195], v[100:103]
	v_mfma_f32_16x16x32_bf16 v[96:99], v[176:179], v[192:195], v[96:99]
	v_mfma_f32_16x16x32_bf16 v[84:87], v[168:171], v[200:203], v[84:87]
	v_mfma_f32_16x16x32_bf16 v[80:83], v[176:179], v[200:203], v[80:83]
	v_mfma_f32_16x16x32_bf16 v[68:71], v[168:171], v[208:211], v[68:71]
	v_mfma_f32_16x16x32_bf16 v[64:67], v[176:179], v[208:211], v[64:67]
	v_mfma_f32_16x16x32_bf16 v[116:119], v[172:175], v[188:191], v[116:119]
	v_mfma_f32_16x16x32_bf16 v[112:115], v[180:183], v[188:191], v[112:115]
	v_mfma_f32_16x16x32_bf16 v[100:103], v[172:175], v[196:199], v[100:103]
	v_mfma_f32_16x16x32_bf16 v[96:99], v[180:183], v[196:199], v[96:99]
	v_mfma_f32_16x16x32_bf16 v[84:87], v[172:175], v[204:207], v[84:87]
	v_mfma_f32_16x16x32_bf16 v[80:83], v[180:183], v[204:207], v[80:83]
	v_mfma_f32_16x16x32_bf16 v[68:71], v[172:175], v[212:215], v[68:71]
	v_mfma_f32_16x16x32_bf16 v[64:67], v[180:183], v[212:215], v[64:67]
	s_setprio 0
	s_barrier
	s_add_i32 s4, s38, s47
	v_lshl_add_u64 v[164:165], s[28:29], 0, v[130:131]
	s_mov_b32 m0, s4
	ds_read_b128 v[184:187], v151 offset:16384
	ds_read_b128 v[188:191], v151 offset:17408
	ds_read_b128 v[192:195], v151 offset:18432
	ds_read_b128 v[196:199], v151 offset:19456
	ds_read_b128 v[200:203], v151 offset:20480
	ds_read_b128 v[204:207], v151 offset:21504
	ds_read_b128 v[208:211], v151 offset:22528
	ds_read_b128 v[212:215], v151 offset:23552
	global_load_lds_dwordx4 v[164:165], off
	s_add_i32 m0, s4, 0x2000
	s_add_u32 s4, s28, 0x160000
	v_lshl_add_u64 v[216:217], s[28:29], 0, v[134:135]
	s_addc_u32 s5, s29, 0
	s_add_i32 s22, s39, s47
	global_load_lds_dwordx4 v[216:217], off
	v_lshl_add_u64 v[218:219], s[4:5], 0, v[130:131]
	s_mov_b32 m0, s22
	v_lshl_add_u64 v[220:221], s[30:31], 0, v[132:133]
	global_load_lds_dwordx4 v[218:219], off
	v_lshl_add_u64 v[218:219], s[4:5], 0, v[134:135]
	s_add_i32 m0, s22, 0x2000
	s_nop 0
	global_load_lds_dwordx4 v[218:219], off
	v_lshl_add_u64 v[218:219], s[30:31], 0, v[128:129]
	s_mov_b32 m0, s25
	s_nop 0
	global_load_lds_dwordx4 v[218:219], off
	s_mov_b32 m0, s33
	s_nop 0
	global_load_lds_dwordx4 v[220:221], off
	s_waitcnt vmcnt(8)
	s_waitcnt lgkmcnt(0)
	s_barrier
; #define PG8_STAGE(bufoff, gbase, voff) do { _Pragma("unroll") for (int _i = 0; _i < 2; ++_i) \
;         __builtin_amdgcn_global_load_lds((const unsigned*)((const char*)(gbase) + (voff)[_i]), (PG8_LAS unsigned*)(lds + (bufoff) + ldsw + _i * 8192), 16, 0, 0); } while (0)
; #define PG8_LDA(dst, b, h) do { _Pragma("unroll") for (int m = 0; m < 4; ++m) _Pragma("unroll") for (int k = 0; k < 2; ++k) dst[m][k] = *(const PG8_LAS bf16x8*)(lds + PG8_SA(b, h) + aoff + m * 2048 + k * 1024); } while (0)
; #define PG8_LDB(dst, b, h) do { _Pragma("unroll") for (int n = 0; n < 2; ++n) _Pragma("unroll") for (int k = 0; k < 2; ++k) dst[n][k] = *(const PG8_LAS bf16x8*)(lds + PG8_SB(b, h) + boff + n * 2048 + k * 1024); } while (0)
; #define PG8_MMA(ai, bj, At, Bt) do { __builtin_amdgcn_s_setprio(1); _Pragma("unroll") for (int m = 0; m < 4; ++m) _Pragma("unroll") for (int n = 0; n < 2; ++n) _Pragma("unroll") for (int k = 0; k < 2; ++k) \
;         acc[ai][bj][m][n] = __builtin_amdgcn_mfma_f32_16x16x32_bf16(Bt[n][k], At[m][k], acc[ai][bj][m][n], 0, 0, 0); __builtin_amdgcn_s_setprio(0); } while (0)
; #define PG8_WAIT_V(n) asm volatile("s_waitcnt vmcnt(" #n ")" ::: "memory")
; #define PG8_WAIT_L(n) asm volatile("s_waitcnt lgkmcnt(" #n ")" ::: "memory")
; #define PG8_BAR __builtin_amdgcn_s_barrier()
; #define PG8_SCHED __builtin_amdgcn_sched_barrier(0)
; template <class Epi, class Sched, bool ALIGN_EPI = false, bool SP2 = false>
; __device__ __forceinline__ void gemm_phase(PG8_LAS unsigned char* lds, const Gemm g, const Sched& S, const Epi& E) {
;     ...
;             PG8_WAIT_V(8); PG8_WAIT_L(0); PG8_BAR; PG8_MMA(1, 0, At, B0); PG8_MMA(1, 1, At, B1); PG8_BAR; PG8_SCHED;
;             PG8_LDB(B0, 1, 0); PG8_LDB(B1, 1, 1); PG8_SCHED; PG8_LDA(At, 1, 0); PG8_STAGE(PG8_SA(0, 1), a2 + hstepA, voffA);
;             PG8_WAIT_V(8); PG8_WAIT_L(0); PG8_BAR; PG8_MMA(0, 0, At, B0); PG8_MMA(0, 1, At, B1); PG8_BAR; PG8_SCHED;
	s_setprio 1
	s_waitcnt lgkmcnt(0)
	v_mfma_f32_16x16x32_bf16 v[60:63], v[144:147], v[184:187], v[60:63]
	v_mfma_f32_16x16x32_bf16 v[56:59], v[156:159], v[184:187], v[56:59]
	v_mfma_f32_16x16x32_bf16 v[44:47], v[144:147], v[192:195], v[44:47]
	v_mfma_f32_16x16x32_bf16 v[40:43], v[156:159], v[192:195], v[40:43]
	v_mfma_f32_16x16x32_bf16 v[28:31], v[144:147], v[200:203], v[28:31]
	v_mfma_f32_16x16x32_bf16 v[24:27], v[156:159], v[200:203], v[24:27]
	v_mfma_f32_16x16x32_bf16 v[12:15], v[144:147], v[208:211], v[12:15]
	v_mfma_f32_16x16x32_bf16 v[8:11], v[156:159], v[208:211], v[8:11]
	v_mfma_f32_16x16x32_bf16 v[60:63], v[152:155], v[188:191], v[60:63]
	v_mfma_f32_16x16x32_bf16 v[56:59], v[160:163], v[188:191], v[56:59]
	v_mfma_f32_16x16x32_bf16 v[44:47], v[152:155], v[196:199], v[44:47]
	v_mfma_f32_16x16x32_bf16 v[40:43], v[160:163], v[196:199], v[40:43]
	v_mfma_f32_16x16x32_bf16 v[28:31], v[152:155], v[204:207], v[28:31]
	v_mfma_f32_16x16x32_bf16 v[24:27], v[160:163], v[204:207], v[24:27]
	v_mfma_f32_16x16x32_bf16 v[12:15], v[152:155], v[212:215], v[12:15]
	v_mfma_f32_16x16x32_bf16 v[8:11], v[160:163], v[212:215], v[8:11]
	v_mfma_f32_16x16x32_bf16 v[52:55], v[168:171], v[184:187], v[52:55]
	v_mfma_f32_16x16x32_bf16 v[48:51], v[176:179], v[184:187], v[48:51]
	v_mfma_f32_16x16x32_bf16 v[36:39], v[168:171], v[192:195], v[36:39]
	v_mfma_f32_16x16x32_bf16 v[32:35], v[176:179], v[192:195], v[32:35]
	v_mfma_f32_16x16x32_bf16 v[20:23], v[168:171], v[200:203], v[20:23]
	v_mfma_f32_16x16x32_bf16 v[16:19], v[176:179], v[200:203], v[16:19]
	v_mfma_f32_16x16x32_bf16 v[4:7], v[168:171], v[208:211], v[4:7]
	v_mfma_f32_16x16x32_bf16 v[0:3], v[176:179], v[208:211], v[0:3]
	v_mfma_f32_16x16x32_bf16 v[52:55], v[172:175], v[188:191], v[52:55]
	v_mfma_f32_16x16x32_bf16 v[48:51], v[180:183], v[188:191], v[48:51]
	v_mfma_f32_16x16x32_bf16 v[36:39], v[172:175], v[196:199], v[36:39]
	v_mfma_f32_16x16x32_bf16 v[32:35], v[180:183], v[196:199], v[32:35]
	v_mfma_f32_16x16x32_bf16 v[20:23], v[172:175], v[204:207], v[20:23]
	v_mfma_f32_16x16x32_bf16 v[16:19], v[180:183], v[204:207], v[16:19]
	v_mfma_f32_16x16x32_bf16 v[4:7], v[172:175], v[212:215], v[4:7]
	v_mfma_f32_16x16x32_bf16 v[0:3], v[180:183], v[212:215], v[0:3]
	s_setprio 0
	s_barrier
	s_add_i32 s22, 0, 0x18000
	s_add_i32 s23, 0, 0x1c000
	v_add_u32_e32 v160, s22, v148
	v_add_u32_e32 v166, s23, v148
	ds_read_b128 v[144:147], v160
	ds_read_b128 v[152:155], v160 offset:1024
	ds_read_b128 v[156:159], v160 offset:2048
	ds_read_b128 v[160:163], v160 offset:3072
	ds_read_b128 v[168:171], v166
	ds_read_b128 v[172:175], v166 offset:1024
	ds_read_b128 v[176:179], v166 offset:2048
	ds_read_b128 v[180:183], v166 offset:3072
	s_add_u32 s4, s30, 0x160000
	s_addc_u32 s5, s31, 0
	s_mov_b32 m0, s34
	v_lshl_add_u64 v[222:223], s[4:5], 0, v[128:129]
	ds_read_b128 v[184:187], v151 offset:32768
	ds_read_b128 v[188:191], v151 offset:33792
	ds_read_b128 v[192:195], v151 offset:34816
	ds_read_b128 v[196:199], v151 offset:35840
	ds_read_b128 v[200:203], v151 offset:36864
	ds_read_b128 v[204:207], v151 offset:37888
	ds_read_b128 v[208:211], v151 offset:38912
	ds_read_b128 v[212:215], v151 offset:39936
	global_load_lds_dwordx4 v[222:223], off
	v_lshl_add_u64 v[222:223], s[4:5], 0, v[132:133]
	s_mov_b32 m0, s35
	s_nop 0
	global_load_lds_dwordx4 v[222:223], off
	s_waitcnt vmcnt(8)
	s_waitcnt lgkmcnt(0)
	s_barrier
	s_setprio 1
	s_waitcnt lgkmcnt(0)
	v_mfma_f32_16x16x32_bf16 v[124:127], v[144:147], v[184:187], v[124:127]
	v_mfma_f32_16x16x32_bf16 v[120:123], v[156:159], v[184:187], v[120:123]
	v_mfma_f32_16x16x32_bf16 v[108:111], v[144:147], v[192:195], v[108:111]
	v_mfma_f32_16x16x32_bf16 v[104:107], v[156:159], v[192:195], v[104:107]
	v_mfma_f32_16x16x32_bf16 v[92:95], v[144:147], v[200:203], v[92:95]
	v_mfma_f32_16x16x32_bf16 v[88:91], v[156:159], v[200:203], v[88:91]
	v_mfma_f32_16x16x32_bf16 v[76:79], v[144:147], v[208:211], v[76:79]
	v_mfma_f32_16x16x32_bf16 v[72:75], v[156:159], v[208:211], v[72:75]
	v_mfma_f32_16x16x32_bf16 v[124:127], v[152:155], v[188:191], v[124:127]
	v_mfma_f32_16x16x32_bf16 v[120:123], v[160:163], v[188:191], v[120:123]
	v_mfma_f32_16x16x32_bf16 v[108:111], v[152:155], v[196:199], v[108:111]
	v_mfma_f32_16x16x32_bf16 v[104:107], v[160:163], v[196:199], v[104:107]
	v_mfma_f32_16x16x32_bf16 v[92:95], v[152:155], v[204:207], v[92:95]
	v_mfma_f32_16x16x32_bf16 v[88:91], v[160:163], v[204:207], v[88:91]
	v_mfma_f32_16x16x32_bf16 v[76:79], v[152:155], v[212:215], v[76:79]
	v_mfma_f32_16x16x32_bf16 v[72:75], v[160:163], v[212:215], v[72:75]
	v_mfma_f32_16x16x32_bf16 v[116:119], v[168:171], v[184:187], v[116:119]
	v_mfma_f32_16x16x32_bf16 v[112:115], v[176:179], v[184:187], v[112:115]
	v_mfma_f32_16x16x32_bf16 v[100:103], v[168:171], v[192:195], v[100:103]
	v_mfma_f32_16x16x32_bf16 v[96:99], v[176:179], v[192:195], v[96:99]
	v_mfma_f32_16x16x32_bf16 v[84:87], v[168:171], v[200:203], v[84:87]
	v_mfma_f32_16x16x32_bf16 v[80:83], v[176:179], v[200:203], v[80:83]
	v_mfma_f32_16x16x32_bf16 v[68:71], v[168:171], v[208:211], v[68:71]
	v_mfma_f32_16x16x32_bf16 v[64:67], v[176:179], v[208:211], v[64:67]
	v_mfma_f32_16x16x32_bf16 v[116:119], v[172:175], v[188:191], v[116:119]
	v_mfma_f32_16x16x32_bf16 v[112:115], v[180:183], v[188:191], v[112:115]
	v_mfma_f32_16x16x32_bf16 v[100:103], v[172:175], v[196:199], v[100:103]
	v_mfma_f32_16x16x32_bf16 v[96:99], v[180:183], v[196:199], v[96:99]
	v_mfma_f32_16x16x32_bf16 v[84:87], v[172:175], v[204:207], v[84:87]
	v_mfma_f32_16x16x32_bf16 v[80:83], v[180:183], v[204:207], v[80:83]
	v_mfma_f32_16x16x32_bf16 v[68:71], v[172:175], v[212:215], v[68:71]
	v_mfma_f32_16x16x32_bf16 v[64:67], v[180:183], v[212:215], v[64:67]
	s_setprio 0
	s_barrier
; #define PG8_STAGE(bufoff, gbase, voff) do { _Pragma("unroll") for (int _i = 0; _i < 2; ++_i) \
;         __builtin_amdgcn_global_load_lds((const unsigned*)((const char*)(gbase) + (voff)[_i]), (PG8_LAS unsigned*)(lds + (bufoff) + ldsw + _i * 8192), 16, 0, 0); } while (0)
; #define PG8_LDA(dst, b, h) do { _Pragma("unroll") for (int m = 0; m < 4; ++m) _Pragma("unroll") for (int k = 0; k < 2; ++k) dst[m][k] = *(const PG8_LAS bf16x8*)(lds + PG8_SA(b, h) + aoff + m * 2048 + k * 1024); } while (0)
; #define PG8_MMA(ai, bj, At, Bt) do { __builtin_amdgcn_s_setprio(1); _Pragma("unroll") for (int m = 0; m < 4; ++m) _Pragma("unroll") for (int n = 0; n < 2; ++n) _Pragma("unroll") for (int k = 0; k < 2; ++k) \
;         acc[ai][bj][m][n] = __builtin_amdgcn_mfma_f32_16x16x32_bf16(Bt[n][k], At[m][k], acc[ai][bj][m][n], 0, 0, 0); __builtin_amdgcn_s_setprio(0); } while (0)
; #define PG8_WAIT_V(n) asm volatile("s_waitcnt vmcnt(" #n ")" ::: "memory")
; #define PG8_WAIT_L(n) asm volatile("s_waitcnt lgkmcnt(" #n ")" ::: "memory")
; #define PG8_BAR __builtin_amdgcn_s_barrier()
; #define PG8_SCHED __builtin_amdgcn_sched_barrier(0)
; template <class Epi, class Sched, bool ALIGN_EPI = false, bool SP2 = false>
; __device__ __forceinline__ void gemm_phase(PG8_LAS unsigned char* lds, const Gemm g, const Sched& S, const Epi& E) {
;     ...
;         for (int t = 0; t < nt; t += 2) {
;             const bool last = (t == nt - 2);
;     ...
;             PG8_LDA(At, 1, 1); PG8_STAGE(PG8_SB(1, 0), b3, voffB); PG8_STAGE(PG8_SB(1, 1), b3 + hstepB, voffB); PG8_STAGE(PG8_SA(1, 0), a3, voffA);
;             PG8_WAIT_V(8); PG8_WAIT_L(0); PG8_BAR; PG8_MMA(1, 0, At, B0); PG8_MMA(1, 1, At, B1); PG8_BAR; PG8_SCHED;
	s_add_i32 s4, s22, s47
	v_lshl_add_u64 v[164:165], v[164:165], 0, s[18:19]
	s_mov_b32 m0, s4
	ds_read_b128 v[184:187], v151 offset:49152
	ds_read_b128 v[188:191], v151 offset:50176
	ds_read_b128 v[192:195], v151 offset:51200
	ds_read_b128 v[196:199], v151 offset:52224
	ds_read_b128 v[200:203], v151 offset:53248
	ds_read_b128 v[204:207], v151 offset:54272
	ds_read_b128 v[208:211], v151 offset:55296
	ds_read_b128 v[212:215], v151 offset:56320
	global_load_lds_dwordx4 v[164:165], off
	s_add_i32 m0, s4, 0x2000
	s_add_u32 s4, s28, 0x160080
	v_lshl_add_u64 v[164:165], v[216:217], 0, s[18:19]
	s_addc_u32 s5, s29, 0
	s_add_i32 s22, s23, s47
	global_load_lds_dwordx4 v[164:165], off
	v_lshl_add_u64 v[164:165], s[4:5], 0, v[130:131]
	s_mov_b32 m0, s22
	s_nop 0
	global_load_lds_dwordx4 v[164:165], off
	v_lshl_add_u64 v[164:165], s[4:5], 0, v[134:135]
	s_add_i32 m0, s22, 0x2000
	s_nop 0
	global_load_lds_dwordx4 v[164:165], off
	v_lshl_add_u64 v[164:165], v[218:219], 0, s[18:19]
	s_mov_b32 m0, s36
	s_nop 0
	global_load_lds_dwordx4 v[164:165], off
	v_lshl_add_u64 v[164:165], v[220:221], 0, s[18:19]
	s_mov_b32 m0, s37
	s_nop 0
	global_load_lds_dwordx4 v[164:165], off
	s_waitcnt vmcnt(8)
	s_waitcnt lgkmcnt(0)
	s_barrier
	s_setprio 1
	s_waitcnt lgkmcnt(0)
	v_mfma_f32_16x16x32_bf16 v[60:63], v[144:147], v[184:187], v[60:63]
	v_mfma_f32_16x16x32_bf16 v[56:59], v[156:159], v[184:187], v[56:59]
	v_mfma_f32_16x16x32_bf16 v[44:47], v[144:147], v[192:195], v[44:47]
	v_mfma_f32_16x16x32_bf16 v[40:43], v[156:159], v[192:195], v[40:43]
	v_mfma_f32_16x16x32_bf16 v[28:31], v[144:147], v[200:203], v[28:31]
	v_mfma_f32_16x16x32_bf16 v[24:27], v[156:159], v[200:203], v[24:27]
	v_mfma_f32_16x16x32_bf16 v[12:15], v[144:147], v[208:211], v[12:15]
	v_mfma_f32_16x16x32_bf16 v[8:11], v[156:159], v[208:211], v[8:11]
	v_mfma_f32_16x16x32_bf16 v[60:63], v[152:155], v[188:191], v[60:63]
	v_mfma_f32_16x16x32_bf16 v[56:59], v[160:163], v[188:191], v[56:59]
	v_mfma_f32_16x16x32_bf16 v[44:47], v[152:155], v[196:199], v[44:47]
	v_mfma_f32_16x16x32_bf16 v[40:43], v[160:163], v[196:199], v[40:43]
	v_mfma_f32_16x16x32_bf16 v[28:31], v[152:155], v[204:207], v[28:31]
	v_mfma_f32_16x16x32_bf16 v[24:27], v[160:163], v[204:207], v[24:27]
	v_mfma_f32_16x16x32_bf16 v[12:15], v[152:155], v[212:215], v[12:15]
	v_mfma_f32_16x16x32_bf16 v[8:11], v[160:163], v[212:215], v[8:11]
	v_mfma_f32_16x16x32_bf16 v[52:55], v[168:171], v[184:187], v[52:55]
	v_mfma_f32_16x16x32_bf16 v[48:51], v[176:179], v[184:187], v[48:51]
	v_mfma_f32_16x16x32_bf16 v[36:39], v[168:171], v[192:195], v[36:39]
	v_mfma_f32_16x16x32_bf16 v[32:35], v[176:179], v[192:195], v[32:35]
	v_mfma_f32_16x16x32_bf16 v[20:23], v[168:171], v[200:203], v[20:23]
	v_mfma_f32_16x16x32_bf16 v[16:19], v[176:179], v[200:203], v[16:19]
	v_mfma_f32_16x16x32_bf16 v[4:7], v[168:171], v[208:211], v[4:7]
	v_mfma_f32_16x16x32_bf16 v[0:3], v[176:179], v[208:211], v[0:3]
	v_mfma_f32_16x16x32_bf16 v[52:55], v[172:175], v[188:191], v[52:55]
	v_mfma_f32_16x16x32_bf16 v[48:51], v[180:183], v[188:191], v[48:51]
	v_mfma_f32_16x16x32_bf16 v[36:39], v[172:175], v[196:199], v[36:39]
	v_mfma_f32_16x16x32_bf16 v[32:35], v[180:183], v[196:199], v[32:35]
	v_mfma_f32_16x16x32_bf16 v[20:23], v[172:175], v[204:207], v[20:23]
	v_mfma_f32_16x16x32_bf16 v[16:19], v[180:183], v[204:207], v[16:19]
	v_mfma_f32_16x16x32_bf16 v[4:7], v[172:175], v[212:215], v[4:7]
	v_mfma_f32_16x16x32_bf16 v[0:3], v[180:183], v[212:215], v[0:3]
	s_setprio 0
	s_barrier
	s_add_i32 s56, s56, 2
	s_add_u32 s54, s54, 0x100
	s_addc_u32 s55, s55, 0
	s_cmpk_gt_u32 s56, 0x55
	s_mov_b64 s[22:23], s[26:27]
	s_cbranch_scc0 .LBB0_810
	s_and_b64 vcc, exec, s[48:49]
	s_cbranch_vccz .LBB0_813
	s_barrier

; #define PG8_STAGE(bufoff, gbase, voff) do { _Pragma("unroll") for (int _i = 0; _i < 2; ++_i) \
;         __builtin_amdgcn_global_load_lds((const unsigned*)((const char*)(gbase) + (voff)[_i]), (PG8_LAS unsigned*)(lds + (bufoff) + ldsw + _i * 8192), 16, 0, 0); } while (0)
; #define PG8_LDA(dst, b, h) do { _Pragma("unroll") for (int m = 0; m < 4; ++m) _Pragma("unroll") for (int k = 0; k < 2; ++k) dst[m][k] = *(const PG8_LAS bf16x8*)(lds + PG8_SA(b, h) + aoff + m * 2048 + k * 1024); } while (0)
; #define PG8_LDB(dst, b, h) do { _Pragma("unroll") for (int n = 0; n < 2; ++n) _Pragma("unroll") for (int k = 0; k < 2; ++k) dst[n][k] = *(const PG8_LAS bf16x8*)(lds + PG8_SB(b, h) + boff + n * 2048 + k * 1024); } while (0)
; #define PG8_MMA(ai, bj, At, Bt) do { __builtin_amdgcn_s_setprio(1); _Pragma("unroll") for (int m = 0; m < 4; ++m) _Pragma("unroll") for (int n = 0; n < 2; ++n) _Pragma("unroll") for (int k = 0; k < 2; ++k) \
;         acc[ai][bj][m][n] = __builtin_amdgcn_mfma_f32_16x16x32_bf16(Bt[n][k], At[m][k], acc[ai][bj][m][n], 0, 0, 0); __builtin_amdgcn_s_setprio(0); } while (0)
; #define PG8_WAIT_V(n) asm volatile("s_waitcnt vmcnt(" #n ")" ::: "memory")
; #define PG8_WAIT_L(n) asm volatile("s_waitcnt lgkmcnt(" #n ")" ::: "memory")
; #define PG8_BAR __builtin_amdgcn_s_barrier()
; #define PG8_SCHED __builtin_amdgcn_sched_barrier(0)
; template <class Epi, class Sched, bool ALIGN_EPI = false, bool SP2 = false>
; __device__ __forceinline__ void gemm_phase(PG8_LAS unsigned char* lds, const Gemm g, const Sched& S, const Epi& E) {
;     ...
;             const bool last = (t == nt - 2);
;             const char* a1 = cA + (size_t)(t + 1) * kstep;
;             const char* a2 = last ? nA : cA + (size_t)(t + 2) * kstep; const char* b2 = last ? nB : cB + (size_t)(t + 2) * kstep;
;             const char* a3 = a2 + kstep; const char* b3 = b2 + kstep;
;     ...
;             PG8_LDB(B0, 0, 0); PG8_LDB(B1, 0, 1); PG8_SCHED; PG8_LDA(At, 0, 0); PG8_STAGE(PG8_SA(1, 1), a1 + hstepA, voffA);
;             PG8_WAIT_V(8); PG8_WAIT_L(0); PG8_BAR; PG8_MMA(0, 0, At, B0); PG8_MMA(0, 1, At, B1); PG8_BAR; PG8_SCHED;
;             PG8_LDA(At, 0, 1); PG8_STAGE(PG8_SB(0, 0), b2, voffB); PG8_STAGE(PG8_SB(0, 1), b2 + hstepB, voffB); PG8_STAGE(PG8_SA(0, 0), a2, voffA);
;             PG8_WAIT_V(8); PG8_WAIT_L(0); PG8_BAR; PG8_MMA(1, 0, At, B0); PG8_MMA(1, 1, At, B1); PG8_BAR; PG8_SCHED;
.LBB0_892:
	ds_read_b128 v[144:147], v155
	ds_read_b128 v[148:151], v155 offset:1024
	ds_read_b128 v[160:163], v155 offset:2048
	ds_read_b128 v[168:171], v155 offset:3072
	ds_read_b128 v[172:175], v156
	ds_read_b128 v[176:179], v156 offset:1024
	ds_read_b128 v[180:183], v156 offset:2048
	ds_read_b128 v[184:187], v156 offset:3072
	s_add_u32 s4, s30, 0xfff80080
	s_addc_u32 s5, s31, -1
	s_cmp_eq_u32 s61, 28
	s_cselect_b32 s37, s11, s5
	s_cselect_b32 s36, s13, s4
	s_cselect_b32 s35, s21, s60
	s_cselect_b32 s34, s23, s59
	v_lshl_add_u64 v[152:153], s[30:31], 0, v[136:137]
	s_add_i32 m0, s25, 0xc000
	ds_read_b128 v[188:191], v157
	ds_read_b128 v[192:195], v157 offset:1024
	ds_read_b128 v[196:199], v157 offset:2048
	ds_read_b128 v[200:203], v157 offset:3072
	ds_read_b128 v[204:207], v157 offset:4096
	ds_read_b128 v[208:211], v157 offset:5120
	ds_read_b128 v[212:215], v157 offset:6144
	ds_read_b128 v[216:219], v157 offset:7168
	global_load_lds_dwordx4 v[152:153], off
	v_lshl_add_u64 v[152:153], s[30:31], 0, v[138:139]
	s_add_i32 m0, s25, 0xe000
	s_nop 0
	global_load_lds_dwordx4 v[152:153], off
	s_waitcnt vmcnt(8)
	s_waitcnt lgkmcnt(0)
	s_barrier
	s_setprio 1
	s_waitcnt lgkmcnt(0)
	v_mfma_f32_16x16x32_bf16 v[124:127], v[144:147], v[188:191], v[124:127]
	v_mfma_f32_16x16x32_bf16 v[120:123], v[160:163], v[188:191], v[120:123]
	v_mfma_f32_16x16x32_bf16 v[108:111], v[144:147], v[196:199], v[108:111]
	v_mfma_f32_16x16x32_bf16 v[104:107], v[160:163], v[196:199], v[104:107]
	v_mfma_f32_16x16x32_bf16 v[92:95], v[144:147], v[204:207], v[92:95]
	v_mfma_f32_16x16x32_bf16 v[88:91], v[160:163], v[204:207], v[88:91]
	v_mfma_f32_16x16x32_bf16 v[76:79], v[144:147], v[212:215], v[76:79]
	v_mfma_f32_16x16x32_bf16 v[72:75], v[160:163], v[212:215], v[72:75]
	v_mfma_f32_16x16x32_bf16 v[124:127], v[148:151], v[192:195], v[124:127]
	v_mfma_f32_16x16x32_bf16 v[120:123], v[168:171], v[192:195], v[120:123]
	v_mfma_f32_16x16x32_bf16 v[108:111], v[148:151], v[200:203], v[108:111]
	v_mfma_f32_16x16x32_bf16 v[104:107], v[168:171], v[200:203], v[104:107]
	v_mfma_f32_16x16x32_bf16 v[92:95], v[148:151], v[208:211], v[92:95]
	v_mfma_f32_16x16x32_bf16 v[88:91], v[168:171], v[208:211], v[88:91]
	v_mfma_f32_16x16x32_bf16 v[76:79], v[148:151], v[216:219], v[76:79]
	v_mfma_f32_16x16x32_bf16 v[72:75], v[168:171], v[216:219], v[72:75]
	v_mfma_f32_16x16x32_bf16 v[116:119], v[172:175], v[188:191], v[116:119]
	v_mfma_f32_16x16x32_bf16 v[112:115], v[180:183], v[188:191], v[112:115]
	v_mfma_f32_16x16x32_bf16 v[100:103], v[172:175], v[196:199], v[100:103]
	v_mfma_f32_16x16x32_bf16 v[96:99], v[180:183], v[196:199], v[96:99]
	v_mfma_f32_16x16x32_bf16 v[84:87], v[172:175], v[204:207], v[84:87]
	v_mfma_f32_16x16x32_bf16 v[80:83], v[180:183], v[204:207], v[80:83]
	v_mfma_f32_16x16x32_bf16 v[68:71], v[172:175], v[212:215], v[68:71]
	v_mfma_f32_16x16x32_bf16 v[64:67], v[180:183], v[212:215], v[64:67]
	v_mfma_f32_16x16x32_bf16 v[116:119], v[176:179], v[192:195], v[116:119]
	v_mfma_f32_16x16x32_bf16 v[112:115], v[184:187], v[192:195], v[112:115]
	v_mfma_f32_16x16x32_bf16 v[100:103], v[176:179], v[200:203], v[100:103]
	v_mfma_f32_16x16x32_bf16 v[96:99], v[184:187], v[200:203], v[96:99]
	v_mfma_f32_16x16x32_bf16 v[84:87], v[176:179], v[208:211], v[84:87]
	v_mfma_f32_16x16x32_bf16 v[80:83], v[184:187], v[208:211], v[80:83]
	v_mfma_f32_16x16x32_bf16 v[68:71], v[176:179], v[216:219], v[68:71]
	v_mfma_f32_16x16x32_bf16 v[64:67], v[184:187], v[216:219], v[64:67]
	s_setprio 0
	s_barrier
	s_add_i32 s4, s45, s47
	v_lshl_add_u64 v[152:153], s[34:35], 0, v[130:131]
	s_mov_b32 m0, s4
	ds_read_b128 v[188:191], v157 offset:16384
	ds_read_b128 v[192:195], v157 offset:17408
	ds_read_b128 v[196:199], v157 offset:18432
	ds_read_b128 v[200:203], v157 offset:19456
	ds_read_b128 v[204:207], v157 offset:20480
	ds_read_b128 v[208:211], v157 offset:21504
	ds_read_b128 v[212:215], v157 offset:22528
	ds_read_b128 v[216:219], v157 offset:23552
	global_load_lds_dwordx4 v[152:153], off
	s_add_i32 m0, s4, 0x2000
	s_add_u32 s4, s34, 0x80000
	v_lshl_add_u64 v[164:165], s[34:35], 0, v[134:135]
	s_addc_u32 s5, s35, 0
	s_add_i32 s62, s46, s47
	global_load_lds_dwordx4 v[164:165], off
	v_lshl_add_u64 v[220:221], s[4:5], 0, v[130:131]
	s_mov_b32 m0, s62
	v_lshl_add_u64 v[222:223], s[36:37], 0, v[132:133]
	global_load_lds_dwordx4 v[220:221], off
	v_lshl_add_u64 v[220:221], s[4:5], 0, v[134:135]
	s_add_i32 m0, s62, 0x2000
	s_nop 0
	global_load_lds_dwordx4 v[220:221], off
	v_lshl_add_u64 v[220:221], s[36:37], 0, v[128:129]
	s_mov_b32 m0, s25
	s_nop 0
	global_load_lds_dwordx4 v[220:221], off
	s_mov_b32 m0, s33
	s_nop 0
	global_load_lds_dwordx4 v[222:223], off
	s_waitcnt vmcnt(8)
	s_waitcnt lgkmcnt(0)
	s_barrier
; #define PG8_STAGE(bufoff, gbase, voff) do { _Pragma("unroll") for (int _i = 0; _i < 2; ++_i) \
;         __builtin_amdgcn_global_load_lds((const unsigned*)((const char*)(gbase) + (voff)[_i]), (PG8_LAS unsigned*)(lds + (bufoff) + ldsw + _i * 8192), 16, 0, 0); } while (0)
; #define PG8_LDA(dst, b, h) do { _Pragma("unroll") for (int m = 0; m < 4; ++m) _Pragma("unroll") for (int k = 0; k < 2; ++k) dst[m][k] = *(const PG8_LAS bf16x8*)(lds + PG8_SA(b, h) + aoff + m * 2048 + k * 1024); } while (0)
; #define PG8_LDB(dst, b, h) do { _Pragma("unroll") for (int n = 0; n < 2; ++n) _Pragma("unroll") for (int k = 0; k < 2; ++k) dst[n][k] = *(const PG8_LAS bf16x8*)(lds + PG8_SB(b, h) + boff + n * 2048 + k * 1024); } while (0)
; #define PG8_MMA(ai, bj, At, Bt) do { __builtin_amdgcn_s_setprio(1); _Pragma("unroll") for (int m = 0; m < 4; ++m) _Pragma("unroll") for (int n = 0; n < 2; ++n) _Pragma("unroll") for (int k = 0; k < 2; ++k) \
;         acc[ai][bj][m][n] = __builtin_amdgcn_mfma_f32_16x16x32_bf16(Bt[n][k], At[m][k], acc[ai][bj][m][n], 0, 0, 0); __builtin_amdgcn_s_setprio(0); } while (0)
; #define PG8_WAIT_V(n) asm volatile("s_waitcnt vmcnt(" #n ")" ::: "memory")
; #define PG8_WAIT_L(n) asm volatile("s_waitcnt lgkmcnt(" #n ")" ::: "memory")
; #define PG8_BAR __builtin_amdgcn_s_barrier()
; #define PG8_SCHED __builtin_amdgcn_sched_barrier(0)
; template <class Epi, class Sched, bool ALIGN_EPI = false, bool SP2 = false>
; __device__ __forceinline__ void gemm_phase(PG8_LAS unsigned char* lds, const Gemm g, const Sched& S, const Epi& E) {
;     ...
;             PG8_WAIT_V(8); PG8_WAIT_L(0); PG8_BAR; PG8_MMA(1, 0, At, B0); PG8_MMA(1, 1, At, B1); PG8_BAR; PG8_SCHED;
;             PG8_LDB(B0, 1, 0); PG8_LDB(B1, 1, 1); PG8_SCHED; PG8_LDA(At, 1, 0); PG8_STAGE(PG8_SA(0, 1), a2 + hstepA, voffA);
;             PG8_WAIT_V(8); PG8_WAIT_L(0); PG8_BAR; PG8_MMA(0, 0, At, B0); PG8_MMA(0, 1, At, B1); PG8_BAR; PG8_SCHED;
	s_setprio 1
	s_waitcnt lgkmcnt(0)
	v_mfma_f32_16x16x32_bf16 v[60:63], v[144:147], v[188:191], v[60:63]
	v_mfma_f32_16x16x32_bf16 v[56:59], v[160:163], v[188:191], v[56:59]
	v_mfma_f32_16x16x32_bf16 v[44:47], v[144:147], v[196:199], v[44:47]
	v_mfma_f32_16x16x32_bf16 v[40:43], v[160:163], v[196:199], v[40:43]
	v_mfma_f32_16x16x32_bf16 v[28:31], v[144:147], v[204:207], v[28:31]
	v_mfma_f32_16x16x32_bf16 v[24:27], v[160:163], v[204:207], v[24:27]
	v_mfma_f32_16x16x32_bf16 v[12:15], v[144:147], v[212:215], v[12:15]
	v_mfma_f32_16x16x32_bf16 v[8:11], v[160:163], v[212:215], v[8:11]
	v_mfma_f32_16x16x32_bf16 v[60:63], v[148:151], v[192:195], v[60:63]
	v_mfma_f32_16x16x32_bf16 v[56:59], v[168:171], v[192:195], v[56:59]
	v_mfma_f32_16x16x32_bf16 v[44:47], v[148:151], v[200:203], v[44:47]
	v_mfma_f32_16x16x32_bf16 v[40:43], v[168:171], v[200:203], v[40:43]
	v_mfma_f32_16x16x32_bf16 v[28:31], v[148:151], v[208:211], v[28:31]
	v_mfma_f32_16x16x32_bf16 v[24:27], v[168:171], v[208:211], v[24:27]
	v_mfma_f32_16x16x32_bf16 v[12:15], v[148:151], v[216:219], v[12:15]
	v_mfma_f32_16x16x32_bf16 v[8:11], v[168:171], v[216:219], v[8:11]
	v_mfma_f32_16x16x32_bf16 v[52:55], v[172:175], v[188:191], v[52:55]
	v_mfma_f32_16x16x32_bf16 v[48:51], v[180:183], v[188:191], v[48:51]
	v_mfma_f32_16x16x32_bf16 v[36:39], v[172:175], v[196:199], v[36:39]
	v_mfma_f32_16x16x32_bf16 v[32:35], v[180:183], v[196:199], v[32:35]
	v_mfma_f32_16x16x32_bf16 v[20:23], v[172:175], v[204:207], v[20:23]
	v_mfma_f32_16x16x32_bf16 v[16:19], v[180:183], v[204:207], v[16:19]
	v_mfma_f32_16x16x32_bf16 v[4:7], v[172:175], v[212:215], v[4:7]
	v_mfma_f32_16x16x32_bf16 v[0:3], v[180:183], v[212:215], v[0:3]
	v_mfma_f32_16x16x32_bf16 v[52:55], v[176:179], v[192:195], v[52:55]
	v_mfma_f32_16x16x32_bf16 v[48:51], v[184:187], v[192:195], v[48:51]
	v_mfma_f32_16x16x32_bf16 v[36:39], v[176:179], v[200:203], v[36:39]
	v_mfma_f32_16x16x32_bf16 v[32:35], v[184:187], v[200:203], v[32:35]
	v_mfma_f32_16x16x32_bf16 v[20:23], v[176:179], v[208:211], v[20:23]
	v_mfma_f32_16x16x32_bf16 v[16:19], v[184:187], v[208:211], v[16:19]
	v_mfma_f32_16x16x32_bf16 v[4:7], v[176:179], v[216:219], v[4:7]
	v_mfma_f32_16x16x32_bf16 v[0:3], v[184:187], v[216:219], v[0:3]
	s_setprio 0
	s_barrier
	s_add_i32 s62, 0, 0x18000
	v_add_u32_e32 v166, s62, v154
	s_add_i32 s63, 0, 0x1c000
	ds_read_b128 v[144:147], v166
	ds_read_b128 v[148:151], v166 offset:1024
	ds_read_b128 v[160:163], v166 offset:2048
	ds_read_b128 v[168:171], v166 offset:3072
	v_add_u32_e32 v166, s63, v154
	ds_read_b128 v[172:175], v166
	ds_read_b128 v[176:179], v166 offset:1024
	ds_read_b128 v[180:183], v166 offset:2048
	ds_read_b128 v[184:187], v166 offset:3072
	s_add_u32 s4, s36, 0x80000
	s_addc_u32 s5, s37, 0
	s_mov_b32 m0, s38
	v_lshl_add_u64 v[224:225], s[4:5], 0, v[128:129]
	ds_read_b128 v[188:191], v157 offset:32768
	ds_read_b128 v[192:195], v157 offset:33792
	ds_read_b128 v[196:199], v157 offset:34816
	ds_read_b128 v[200:203], v157 offset:35840
	ds_read_b128 v[204:207], v157 offset:36864
	ds_read_b128 v[208:211], v157 offset:37888
	ds_read_b128 v[212:215], v157 offset:38912
	ds_read_b128 v[216:219], v157 offset:39936
	global_load_lds_dwordx4 v[224:225], off
	v_lshl_add_u64 v[224:225], s[4:5], 0, v[132:133]
	s_mov_b32 m0, s39
	s_nop 0
	global_load_lds_dwordx4 v[224:225], off
	s_waitcnt vmcnt(8)
	s_waitcnt lgkmcnt(0)
	s_barrier
	s_setprio 1
	s_waitcnt lgkmcnt(0)
	v_mfma_f32_16x16x32_bf16 v[124:127], v[144:147], v[188:191], v[124:127]
	v_mfma_f32_16x16x32_bf16 v[120:123], v[160:163], v[188:191], v[120:123]
	v_mfma_f32_16x16x32_bf16 v[108:111], v[144:147], v[196:199], v[108:111]
	v_mfma_f32_16x16x32_bf16 v[104:107], v[160:163], v[196:199], v[104:107]
	v_mfma_f32_16x16x32_bf16 v[92:95], v[144:147], v[204:207], v[92:95]
	v_mfma_f32_16x16x32_bf16 v[88:91], v[160:163], v[204:207], v[88:91]
	v_mfma_f32_16x16x32_bf16 v[76:79], v[144:147], v[212:215], v[76:79]
	v_mfma_f32_16x16x32_bf16 v[72:75], v[160:163], v[212:215], v[72:75]
	v_mfma_f32_16x16x32_bf16 v[124:127], v[148:151], v[192:195], v[124:127]
	v_mfma_f32_16x16x32_bf16 v[120:123], v[168:171], v[192:195], v[120:123]
	v_mfma_f32_16x16x32_bf16 v[108:111], v[148:151], v[200:203], v[108:111]
	v_mfma_f32_16x16x32_bf16 v[104:107], v[168:171], v[200:203], v[104:107]
	v_mfma_f32_16x16x32_bf16 v[92:95], v[148:151], v[208:211], v[92:95]
	v_mfma_f32_16x16x32_bf16 v[88:91], v[168:171], v[208:211], v[88:91]
	v_mfma_f32_16x16x32_bf16 v[76:79], v[148:151], v[216:219], v[76:79]
	v_mfma_f32_16x16x32_bf16 v[72:75], v[168:171], v[216:219], v[72:75]
	v_mfma_f32_16x16x32_bf16 v[116:119], v[172:175], v[188:191], v[116:119]
	v_mfma_f32_16x16x32_bf16 v[112:115], v[180:183], v[188:191], v[112:115]
	v_mfma_f32_16x16x32_bf16 v[100:103], v[172:175], v[196:199], v[100:103]
	v_mfma_f32_16x16x32_bf16 v[96:99], v[180:183], v[196:199], v[96:99]
	v_mfma_f32_16x16x32_bf16 v[84:87], v[172:175], v[204:207], v[84:87]
	v_mfma_f32_16x16x32_bf16 v[80:83], v[180:183], v[204:207], v[80:83]
	v_mfma_f32_16x16x32_bf16 v[68:71], v[172:175], v[212:215], v[68:71]
	v_mfma_f32_16x16x32_bf16 v[64:67], v[180:183], v[212:215], v[64:67]
	v_mfma_f32_16x16x32_bf16 v[116:119], v[176:179], v[192:195], v[116:119]
	v_mfma_f32_16x16x32_bf16 v[112:115], v[184:187], v[192:195], v[112:115]
	v_mfma_f32_16x16x32_bf16 v[100:103], v[176:179], v[200:203], v[100:103]
	v_mfma_f32_16x16x32_bf16 v[96:99], v[184:187], v[200:203], v[96:99]
	v_mfma_f32_16x16x32_bf16 v[84:87], v[176:179], v[208:211], v[84:87]
	v_mfma_f32_16x16x32_bf16 v[80:83], v[184:187], v[208:211], v[80:83]
	v_mfma_f32_16x16x32_bf16 v[68:71], v[176:179], v[216:219], v[68:71]
	v_mfma_f32_16x16x32_bf16 v[64:67], v[184:187], v[216:219], v[64:67]
	s_setprio 0
	s_barrier
; #define PG8_STAGE(bufoff, gbase, voff) do { _Pragma("unroll") for (int _i = 0; _i < 2; ++_i) \
;         __builtin_amdgcn_global_load_lds((const unsigned*)((const char*)(gbase) + (voff)[_i]), (PG8_LAS unsigned*)(lds + (bufoff) + ldsw + _i * 8192), 16, 0, 0); } while (0)
; #define PG8_LDA(dst, b, h) do { _Pragma("unroll") for (int m = 0; m < 4; ++m) _Pragma("unroll") for (int k = 0; k < 2; ++k) dst[m][k] = *(const PG8_LAS bf16x8*)(lds + PG8_SA(b, h) + aoff + m * 2048 + k * 1024); } while (0)
; #define PG8_MMA(ai, bj, At, Bt) do { __builtin_amdgcn_s_setprio(1); _Pragma("unroll") for (int m = 0; m < 4; ++m) _Pragma("unroll") for (int n = 0; n < 2; ++n) _Pragma("unroll") for (int k = 0; k < 2; ++k) \
;         acc[ai][bj][m][n] = __builtin_amdgcn_mfma_f32_16x16x32_bf16(Bt[n][k], At[m][k], acc[ai][bj][m][n], 0, 0, 0); __builtin_amdgcn_s_setprio(0); } while (0)
; #define PG8_WAIT_V(n) asm volatile("s_waitcnt vmcnt(" #n ")" ::: "memory")
; #define PG8_WAIT_L(n) asm volatile("s_waitcnt lgkmcnt(" #n ")" ::: "memory")
; #define PG8_BAR __builtin_amdgcn_s_barrier()
; #define PG8_SCHED __builtin_amdgcn_sched_barrier(0)
; template <class Epi, class Sched, bool ALIGN_EPI = false, bool SP2 = false>
; __device__ __forceinline__ void gemm_phase(PG8_LAS unsigned char* lds, const Gemm g, const Sched& S, const Epi& E) {
;     ...
;         for (int t = 0; t < nt; t += 2) {
;             const bool last = (t == nt - 2);
;     ...
;             PG8_LDA(At, 1, 1); PG8_STAGE(PG8_SB(1, 0), b3, voffB); PG8_STAGE(PG8_SB(1, 1), b3 + hstepB, voffB); PG8_STAGE(PG8_SA(1, 0), a3, voffA);
;             PG8_WAIT_V(8); PG8_WAIT_L(0); PG8_BAR; PG8_MMA(1, 0, At, B0); PG8_MMA(1, 1, At, B1); PG8_BAR; PG8_SCHED;
	s_add_i32 s4, s62, s47
	v_lshl_add_u64 v[152:153], v[152:153], 0, s[18:19]
	s_mov_b32 m0, s4
	ds_read_b128 v[188:191], v157 offset:49152
	ds_read_b128 v[192:195], v157 offset:50176
	ds_read_b128 v[196:199], v157 offset:51200
	ds_read_b128 v[200:203], v157 offset:52224
	ds_read_b128 v[204:207], v157 offset:53248
	ds_read_b128 v[208:211], v157 offset:54272
	ds_read_b128 v[212:215], v157 offset:55296
	ds_read_b128 v[216:219], v157 offset:56320
	global_load_lds_dwordx4 v[152:153], off
	s_add_i32 m0, s4, 0x2000
	s_add_u32 s4, s34, 0x80080
	v_lshl_add_u64 v[152:153], v[164:165], 0, s[18:19]
	s_addc_u32 s5, s35, 0
	s_add_i32 s34, s63, s47
	global_load_lds_dwordx4 v[152:153], off
	v_lshl_add_u64 v[152:153], s[4:5], 0, v[130:131]
	s_mov_b32 m0, s34
	s_nop 0
	global_load_lds_dwordx4 v[152:153], off
	v_lshl_add_u64 v[152:153], s[4:5], 0, v[134:135]
	s_add_i32 m0, s34, 0x2000
	s_nop 0
	global_load_lds_dwordx4 v[152:153], off
	v_lshl_add_u64 v[152:153], v[220:221], 0, s[18:19]
	s_mov_b32 m0, s41
	s_nop 0
	global_load_lds_dwordx4 v[152:153], off
	v_lshl_add_u64 v[152:153], v[222:223], 0, s[18:19]
	s_mov_b32 m0, s44
	s_nop 0
	global_load_lds_dwordx4 v[152:153], off
	s_waitcnt vmcnt(8)
	s_waitcnt lgkmcnt(0)
	s_barrier
	s_setprio 1
	s_waitcnt lgkmcnt(0)
	v_mfma_f32_16x16x32_bf16 v[60:63], v[144:147], v[188:191], v[60:63]
	v_mfma_f32_16x16x32_bf16 v[56:59], v[160:163], v[188:191], v[56:59]
	v_mfma_f32_16x16x32_bf16 v[44:47], v[144:147], v[196:199], v[44:47]
	v_mfma_f32_16x16x32_bf16 v[40:43], v[160:163], v[196:199], v[40:43]
	v_mfma_f32_16x16x32_bf16 v[28:31], v[144:147], v[204:207], v[28:31]
	v_mfma_f32_16x16x32_bf16 v[24:27], v[160:163], v[204:207], v[24:27]
	v_mfma_f32_16x16x32_bf16 v[12:15], v[144:147], v[212:215], v[12:15]
	v_mfma_f32_16x16x32_bf16 v[8:11], v[160:163], v[212:215], v[8:11]
	v_mfma_f32_16x16x32_bf16 v[60:63], v[148:151], v[192:195], v[60:63]
	v_mfma_f32_16x16x32_bf16 v[56:59], v[168:171], v[192:195], v[56:59]
	v_mfma_f32_16x16x32_bf16 v[44:47], v[148:151], v[200:203], v[44:47]
	v_mfma_f32_16x16x32_bf16 v[40:43], v[168:171], v[200:203], v[40:43]
	v_mfma_f32_16x16x32_bf16 v[28:31], v[148:151], v[208:211], v[28:31]
	v_mfma_f32_16x16x32_bf16 v[24:27], v[168:171], v[208:211], v[24:27]
	v_mfma_f32_16x16x32_bf16 v[12:15], v[148:151], v[216:219], v[12:15]
	v_mfma_f32_16x16x32_bf16 v[8:11], v[168:171], v[216:219], v[8:11]
	v_mfma_f32_16x16x32_bf16 v[52:55], v[172:175], v[188:191], v[52:55]
	v_mfma_f32_16x16x32_bf16 v[48:51], v[180:183], v[188:191], v[48:51]
	v_mfma_f32_16x16x32_bf16 v[36:39], v[172:175], v[196:199], v[36:39]
	v_mfma_f32_16x16x32_bf16 v[32:35], v[180:183], v[196:199], v[32:35]
	v_mfma_f32_16x16x32_bf16 v[20:23], v[172:175], v[204:207], v[20:23]
	v_mfma_f32_16x16x32_bf16 v[16:19], v[180:183], v[204:207], v[16:19]
	v_mfma_f32_16x16x32_bf16 v[4:7], v[172:175], v[212:215], v[4:7]
	v_mfma_f32_16x16x32_bf16 v[0:3], v[180:183], v[212:215], v[0:3]
	v_mfma_f32_16x16x32_bf16 v[52:55], v[176:179], v[192:195], v[52:55]
	v_mfma_f32_16x16x32_bf16 v[48:51], v[184:187], v[192:195], v[48:51]
	v_mfma_f32_16x16x32_bf16 v[36:39], v[176:179], v[200:203], v[36:39]
	v_mfma_f32_16x16x32_bf16 v[32:35], v[184:187], v[200:203], v[32:35]
	v_mfma_f32_16x16x32_bf16 v[20:23], v[176:179], v[208:211], v[20:23]
	v_mfma_f32_16x16x32_bf16 v[16:19], v[184:187], v[208:211], v[16:19]
	v_mfma_f32_16x16x32_bf16 v[4:7], v[176:179], v[216:219], v[4:7]
	v_mfma_f32_16x16x32_bf16 v[0:3], v[184:187], v[216:219], v[0:3]
	s_setprio 0
	s_barrier
	s_add_i32 s61, s61, 2
	s_add_u32 s30, s30, 0x100
	s_addc_u32 s31, s31, 0
	s_add_u32 s59, s59, 0x100
	s_addc_u32 s60, s60, 0
	s_cmp_gt_u32 s61, 29
	s_cbranch_scc0 .LBB0_892
	s_and_b64 vcc, exec, s[48:49]
	s_cbranch_vccz .LBB0_895
	s_barrier

; #define PG8_STAGE(bufoff, gbase, voff) do { _Pragma("unroll") for (int _i = 0; _i < 2; ++_i) \
;         __builtin_amdgcn_global_load_lds((const unsigned*)((const char*)(gbase) + (voff)[_i]), (PG8_LAS unsigned*)(lds + (bufoff) + ldsw + _i * 8192), 16, 0, 0); } while (0)
; #define PG8_LDA(dst, b, h) do { _Pragma("unroll") for (int m = 0; m < 4; ++m) _Pragma("unroll") for (int k = 0; k < 2; ++k) dst[m][k] = *(const PG8_LAS bf16x8*)(lds + PG8_SA(b, h) + aoff + m * 2048 + k * 1024); } while (0)
; #define PG8_LDB(dst, b, h) do { _Pragma("unroll") for (int n = 0; n < 2; ++n) _Pragma("unroll") for (int k = 0; k < 2; ++k) dst[n][k] = *(const PG8_LAS bf16x8*)(lds + PG8_SB(b, h) + boff + n * 2048 + k * 1024); } while (0)
; #define PG8_MMA(ai, bj, At, Bt) do { __builtin_amdgcn_s_setprio(1); _Pragma("unroll") for (int m = 0; m < 4; ++m) _Pragma("unroll") for (int n = 0; n < 2; ++n) _Pragma("unroll") for (int k = 0; k < 2; ++k) \
;         acc[ai][bj][m][n] = __builtin_amdgcn_mfma_f32_16x16x32_bf16(Bt[n][k], At[m][k], acc[ai][bj][m][n], 0, 0, 0); __builtin_amdgcn_s_setprio(0); } while (0)
; #define PG8_WAIT_V(n) asm volatile("s_waitcnt vmcnt(" #n ")" ::: "memory")
; template <class Epi, class Sched, bool ALIGN_EPI = false, bool SP2 = false>
; __device__ __forceinline__ void gemm_phase(PG8_LAS unsigned char* lds, const Gemm g, const Sched& S, const Epi& E) {
;     ...
;         const bool has_next = S.next(ui + 1, nxt);
;         const char* nA = has_next ? (const char*)g.A + (size_t)nxt.pm * tstepA + nxt.aoff : cA; const char* nB = has_next ? (const char*)g.Bt + (size_t)nxt.pn * tstepB : cB;
;         for (int t = 0; t < nt; t += 2) {
;             const bool last = (t == nt - 2);
;             const char* a1 = cA + (size_t)(t + 1) * kstep;
;             const char* a2 = last ? nA : cA + (size_t)(t + 2) * kstep; const char* b2 = last ? nB : cB + (size_t)(t + 2) * kstep;
;     ...
;             PG8_LDB(B0, 0, 0); PG8_LDB(B1, 0, 1); PG8_SCHED; PG8_LDA(At, 0, 0); PG8_STAGE(PG8_SA(1, 1), a1 + hstepA, voffA);
;             PG8_WAIT_V(8); PG8_WAIT_L(0); PG8_BAR; PG8_MMA(0, 0, At, B0); PG8_MMA(0, 1, At, B1); PG8_BAR; PG8_SCHED;
;             PG8_LDA(At, 0, 1); PG8_STAGE(PG8_SB(0, 0), b2, voffB); PG8_STAGE(PG8_SB(0, 1), b2 + hstepB, voffB); PG8_STAGE(PG8_SA(0, 0), a2, voffA);
;             PG8_WAIT_V(8); PG8_WAIT_L(0); PG8_BAR; PG8_MMA(1, 0, At, B0); PG8_MMA(1, 1, At, B1); PG8_BAR; PG8_SCHED;
.LBB0_1041:
	s_ashr_i32 s63, s62, 31
	s_lshl_b64 s[4:5], s[62:63], 20
	ds_read_b128 v[0:3], v168
	ds_read_b128 v[4:7], v168 offset:1024
	ds_read_b128 v[8:11], v168 offset:2048
	ds_read_b128 v[12:15], v168 offset:3072
	ds_read_b128 v[16:19], v169
	ds_read_b128 v[20:23], v169 offset:1024
	ds_read_b128 v[24:27], v169 offset:2048
	ds_read_b128 v[28:31], v169 offset:3072
	s_add_u32 s4, s20, s4
	s_addc_u32 s5, s21, s5
	s_ashr_i32 s11, s81, 31
	s_add_u32 s64, s4, s81
	s_addc_u32 s65, s5, s11
	s_and_b64 s[4:5], s[8:9], exec
	s_cselect_b32 s71, s65, s13
	s_cselect_b32 s70, s64, s12
	s_ashr_i32 s61, s60, 31
	s_lshl_b64 s[4:5], s[60:61], 17
	s_add_u32 s66, s0, s4
	s_addc_u32 s67, s1, s5
	s_and_b64 s[4:5], s[8:9], exec
	s_cselect_b32 s69, s67, s15
	s_cselect_b32 s68, s66, s14
	s_add_u32 s4, s12, 0x80080
	s_addc_u32 s5, s13, 0
	s_add_i32 s88, s3, 0xc000
	v_lshl_add_u64 v[64:65], s[4:5], 0, v[138:139]
	s_mov_b32 m0, s88
	s_add_i32 s11, s3, 0xe000
	ds_read_b128 v[32:35], v170
	ds_read_b128 v[36:39], v170 offset:1024
	ds_read_b128 v[40:43], v170 offset:2048
	ds_read_b128 v[44:47], v170 offset:3072
	ds_read_b128 v[48:51], v170 offset:4096
	ds_read_b128 v[52:55], v170 offset:5120
	ds_read_b128 v[56:59], v170 offset:6144
	ds_read_b128 v[60:63], v170 offset:7168
	global_load_lds_dwordx4 v[64:65], off
	v_lshl_add_u64 v[64:65], s[4:5], 0, v[134:135]
	s_mov_b32 m0, s11
	s_nop 0
	global_load_lds_dwordx4 v[64:65], off
	s_waitcnt vmcnt(8)
	s_waitcnt lgkmcnt(0)
	s_barrier
	s_setprio 1
	s_waitcnt lgkmcnt(0)
	v_mfma_f32_16x16x32_bf16 v[64:67], v[0:3], v[32:35], 0
	v_mfma_f32_16x16x32_bf16 v[68:71], v[8:11], v[32:35], 0
	v_mfma_f32_16x16x32_bf16 v[72:75], v[0:3], v[40:43], 0
	v_mfma_f32_16x16x32_bf16 v[76:79], v[8:11], v[40:43], 0
	v_mfma_f32_16x16x32_bf16 v[80:83], v[0:3], v[48:51], 0
	v_mfma_f32_16x16x32_bf16 v[84:87], v[8:11], v[48:51], 0
	v_mfma_f32_16x16x32_bf16 v[88:91], v[0:3], v[56:59], 0
	v_mfma_f32_16x16x32_bf16 v[92:95], v[8:11], v[56:59], 0
	v_mfma_f32_16x16x32_bf16 v[64:67], v[4:7], v[36:39], v[64:67]
	v_mfma_f32_16x16x32_bf16 v[68:71], v[12:15], v[36:39], v[68:71]
	v_mfma_f32_16x16x32_bf16 v[72:75], v[4:7], v[44:47], v[72:75]
	v_mfma_f32_16x16x32_bf16 v[76:79], v[12:15], v[44:47], v[76:79]
	v_mfma_f32_16x16x32_bf16 v[80:83], v[4:7], v[52:55], v[80:83]
	v_mfma_f32_16x16x32_bf16 v[84:87], v[12:15], v[52:55], v[84:87]
	v_mfma_f32_16x16x32_bf16 v[88:91], v[4:7], v[60:63], v[88:91]
	v_mfma_f32_16x16x32_bf16 v[92:95], v[12:15], v[60:63], v[92:95]
	v_mfma_f32_16x16x32_bf16 v[96:99], v[16:19], v[32:35], 0
	v_mfma_f32_16x16x32_bf16 v[32:35], v[24:27], v[32:35], 0
	v_mfma_f32_16x16x32_bf16 v[96:99], v[20:23], v[36:39], v[96:99]
	v_mfma_f32_16x16x32_bf16 v[32:35], v[28:31], v[36:39], v[32:35]
	v_mfma_f32_16x16x32_bf16 v[36:39], v[16:19], v[40:43], 0
	v_mfma_f32_16x16x32_bf16 v[40:43], v[24:27], v[40:43], 0
	v_mfma_f32_16x16x32_bf16 v[36:39], v[20:23], v[44:47], v[36:39]
	v_mfma_f32_16x16x32_bf16 v[40:43], v[28:31], v[44:47], v[40:43]
	v_mfma_f32_16x16x32_bf16 v[44:47], v[16:19], v[48:51], 0
	v_mfma_f32_16x16x32_bf16 v[48:51], v[24:27], v[48:51], 0
	v_mfma_f32_16x16x32_bf16 v[44:47], v[20:23], v[52:55], v[44:47]
	v_mfma_f32_16x16x32_bf16 v[48:51], v[28:31], v[52:55], v[48:51]
	v_mfma_f32_16x16x32_bf16 v[52:55], v[16:19], v[56:59], 0
	v_mfma_f32_16x16x32_bf16 v[56:59], v[24:27], v[56:59], 0
	v_mfma_f32_16x16x32_bf16 v[52:55], v[20:23], v[60:63], v[52:55]
	v_mfma_f32_16x16x32_bf16 v[56:59], v[28:31], v[60:63], v[56:59]
	s_setprio 0
	s_barrier
	s_add_i32 s86, s45, s47
	v_lshl_add_u64 v[164:165], s[14:15], 0, v[136:137]
	s_add_i32 s61, s86, 0x2000
	v_lshl_add_u64 v[128:129], v[164:165], 0, s[36:37]
	s_mov_b32 m0, s86
	v_lshl_add_u64 v[212:213], s[14:15], 0, v[132:133]
	s_add_u32 s4, s14, 0x10100
	ds_read_b128 v[60:63], v170 offset:16384
	ds_read_b128 v[100:103], v170 offset:17408
	ds_read_b128 v[104:107], v170 offset:18432
	ds_read_b128 v[108:111], v170 offset:19456
	ds_read_b128 v[112:115], v170 offset:20480
	ds_read_b128 v[116:119], v170 offset:21504
	ds_read_b128 v[120:123], v170 offset:22528
	ds_read_b128 v[124:127], v170 offset:23552
	global_load_lds_dwordx4 v[128:129], off
	v_lshl_add_u64 v[128:129], v[212:213], 0, s[36:37]
	s_mov_b32 m0, s61
	s_addc_u32 s5, s15, 0
	s_add_i32 s63, s46, s47
	global_load_lds_dwordx4 v[128:129], off
	v_lshl_add_u64 v[128:129], s[4:5], 0, v[136:137]
	s_mov_b32 m0, s63
	s_add_i32 s85, s63, 0x2000
	global_load_lds_dwordx4 v[128:129], off
	v_lshl_add_u64 v[128:129], s[4:5], 0, v[132:133]
	s_mov_b32 m0, s85
	v_lshl_add_u64 v[214:215], s[12:13], 0, v[138:139]
	global_load_lds_dwordx4 v[128:129], off
	v_lshl_add_u64 v[128:129], v[214:215], 0, s[36:37]
	s_mov_b32 m0, s3
	v_lshl_add_u64 v[216:217], s[12:13], 0, v[134:135]
	global_load_lds_dwordx4 v[128:129], off
	v_lshl_add_u64 v[128:129], v[216:217], 0, s[36:37]
	s_mov_b32 m0, s24
	s_nop 0
	global_load_lds_dwordx4 v[128:129], off
	s_waitcnt vmcnt(8)
	s_waitcnt lgkmcnt(0)
	s_barrier
; #define PG8_STAGE(bufoff, gbase, voff) do { _Pragma("unroll") for (int _i = 0; _i < 2; ++_i) \
;         __builtin_amdgcn_global_load_lds((const unsigned*)((const char*)(gbase) + (voff)[_i]), (PG8_LAS unsigned*)(lds + (bufoff) + ldsw + _i * 8192), 16, 0, 0); } while (0)
; #define PG8_LDA(dst, b, h) do { _Pragma("unroll") for (int m = 0; m < 4; ++m) _Pragma("unroll") for (int k = 0; k < 2; ++k) dst[m][k] = *(const PG8_LAS bf16x8*)(lds + PG8_SA(b, h) + aoff + m * 2048 + k * 1024); } while (0)
; #define PG8_LDB(dst, b, h) do { _Pragma("unroll") for (int n = 0; n < 2; ++n) _Pragma("unroll") for (int k = 0; k < 2; ++k) dst[n][k] = *(const PG8_LAS bf16x8*)(lds + PG8_SB(b, h) + boff + n * 2048 + k * 1024); } while (0)
; #define PG8_MMA(ai, bj, At, Bt) do { __builtin_amdgcn_s_setprio(1); _Pragma("unroll") for (int m = 0; m < 4; ++m) _Pragma("unroll") for (int n = 0; n < 2; ++n) _Pragma("unroll") for (int k = 0; k < 2; ++k) \
;         acc[ai][bj][m][n] = __builtin_amdgcn_mfma_f32_16x16x32_bf16(Bt[n][k], At[m][k], acc[ai][bj][m][n], 0, 0, 0); __builtin_amdgcn_s_setprio(0); } while (0)
; #define PG8_WAIT_V(n) asm volatile("s_waitcnt vmcnt(" #n ")" ::: "memory")
; #define PG8_WAIT_L(n) asm volatile("s_waitcnt lgkmcnt(" #n ")" ::: "memory")
; #define PG8_BAR __builtin_amdgcn_s_barrier()
; #define PG8_SCHED __builtin_amdgcn_sched_barrier(0)
; template <class Epi, class Sched, bool ALIGN_EPI = false, bool SP2 = false>
; __device__ __forceinline__ void gemm_phase(PG8_LAS unsigned char* lds, const Gemm g, const Sched& S, const Epi& E) {
;     ...
;             PG8_WAIT_V(8); PG8_WAIT_L(0); PG8_BAR; PG8_MMA(1, 0, At, B0); PG8_MMA(1, 1, At, B1); PG8_BAR; PG8_SCHED;
;             PG8_LDB(B0, 1, 0); PG8_LDB(B1, 1, 1); PG8_SCHED; PG8_LDA(At, 1, 0); PG8_STAGE(PG8_SA(0, 1), a2 + hstepA, voffA);
;             PG8_WAIT_V(8); PG8_WAIT_L(0); PG8_BAR; PG8_MMA(0, 0, At, B0); PG8_MMA(0, 1, At, B1); PG8_BAR; PG8_SCHED;
	s_setprio 1
	s_waitcnt lgkmcnt(0)
	v_mfma_f32_16x16x32_bf16 v[128:131], v[0:3], v[60:63], 0
	v_mfma_f32_16x16x32_bf16 v[148:151], v[0:3], v[104:107], 0
	v_mfma_f32_16x16x32_bf16 v[156:159], v[0:3], v[112:115], 0
	v_mfma_f32_16x16x32_bf16 v[0:3], v[0:3], v[120:123], 0
	v_mfma_f32_16x16x32_bf16 v[128:131], v[4:7], v[100:103], v[128:131]
	v_mfma_f32_16x16x32_bf16 v[148:151], v[4:7], v[108:111], v[148:151]
	v_mfma_f32_16x16x32_bf16 v[156:159], v[4:7], v[116:119], v[156:159]
	v_mfma_f32_16x16x32_bf16 v[0:3], v[4:7], v[124:127], v[0:3]
	v_mfma_f32_16x16x32_bf16 v[4:7], v[8:11], v[120:123], 0
	v_mfma_f32_16x16x32_bf16 v[144:147], v[8:11], v[60:63], 0
	v_mfma_f32_16x16x32_bf16 v[152:155], v[8:11], v[104:107], 0
	v_mfma_f32_16x16x32_bf16 v[160:163], v[8:11], v[112:115], 0
	v_mfma_f32_16x16x32_bf16 v[4:7], v[12:15], v[124:127], v[4:7]
	v_mfma_f32_16x16x32_bf16 v[144:147], v[12:15], v[100:103], v[144:147]
	v_mfma_f32_16x16x32_bf16 v[152:155], v[12:15], v[108:111], v[152:155]
	v_mfma_f32_16x16x32_bf16 v[160:163], v[12:15], v[116:119], v[160:163]
	v_mfma_f32_16x16x32_bf16 v[8:11], v[16:19], v[60:63], 0
	v_mfma_f32_16x16x32_bf16 v[12:15], v[24:27], v[60:63], 0
	v_mfma_f32_16x16x32_bf16 v[8:11], v[20:23], v[100:103], v[8:11]
	v_mfma_f32_16x16x32_bf16 v[12:15], v[28:31], v[100:103], v[12:15]
	v_mfma_f32_16x16x32_bf16 v[60:63], v[16:19], v[104:107], 0
	v_mfma_f32_16x16x32_bf16 v[100:103], v[24:27], v[104:107], 0
	v_mfma_f32_16x16x32_bf16 v[104:107], v[16:19], v[112:115], 0
	v_mfma_f32_16x16x32_bf16 v[16:19], v[16:19], v[120:123], 0
	v_mfma_f32_16x16x32_bf16 v[60:63], v[20:23], v[108:111], v[60:63]
	v_mfma_f32_16x16x32_bf16 v[100:103], v[28:31], v[108:111], v[100:103]
	v_mfma_f32_16x16x32_bf16 v[104:107], v[20:23], v[116:119], v[104:107]
	v_mfma_f32_16x16x32_bf16 v[108:111], v[24:27], v[112:115], 0
	v_mfma_f32_16x16x32_bf16 v[16:19], v[20:23], v[124:127], v[16:19]
	v_mfma_f32_16x16x32_bf16 v[20:23], v[24:27], v[120:123], 0
	v_mfma_f32_16x16x32_bf16 v[108:111], v[28:31], v[116:119], v[108:111]
	v_mfma_f32_16x16x32_bf16 v[20:23], v[28:31], v[124:127], v[20:23]
	s_setprio 0
	s_barrier
	s_add_i32 s89, 0, 0x18000
	s_add_i32 s90, 0, 0x1c000
	v_add_u32_e32 v220, s89, v166
	v_add_u32_e32 v221, s90, v166
	ds_read_b128 v[24:27], v220
	ds_read_b128 v[28:31], v220 offset:1024
	ds_read_b128 v[112:115], v220 offset:2048
	ds_read_b128 v[116:119], v220 offset:3072
	ds_read_b128 v[120:123], v221
	ds_read_b128 v[124:127], v221 offset:1024
	ds_read_b128 v[172:175], v221 offset:2048
	ds_read_b128 v[176:179], v221 offset:3072
	s_add_u32 s4, s12, 0x80100
	s_addc_u32 s5, s13, 0
	s_mov_b32 m0, s25
	v_lshl_add_u64 v[218:219], s[4:5], 0, v[138:139]
	ds_read_b128 v[180:183], v170 offset:32768
	ds_read_b128 v[184:187], v170 offset:33792
	ds_read_b128 v[188:191], v170 offset:34816
	s_waitcnt vmcnt(0)
	ds_read_b128 v[192:195], v170 offset:35840
	ds_read_b128 v[196:199], v170 offset:36864
	ds_read_b128 v[200:203], v170 offset:37888
	ds_read_b128 v[204:207], v170 offset:38912
	ds_read_b128 v[208:211], v170 offset:39936
	global_load_lds_dwordx4 v[218:219], off
	v_lshl_add_u64 v[218:219], s[4:5], 0, v[134:135]
	s_mov_b32 m0, s33
	s_nop 0
	global_load_lds_dwordx4 v[218:219], off
	s_waitcnt vmcnt(8)
	s_waitcnt lgkmcnt(0)
	s_barrier
	s_setprio 1
	s_waitcnt lgkmcnt(0)
	v_mfma_f32_16x16x32_bf16 v[64:67], v[24:27], v[180:183], v[64:67]
	v_mfma_f32_16x16x32_bf16 v[68:71], v[112:115], v[180:183], v[68:71]
	v_mfma_f32_16x16x32_bf16 v[72:75], v[24:27], v[188:191], v[72:75]
	v_mfma_f32_16x16x32_bf16 v[76:79], v[112:115], v[188:191], v[76:79]
	v_mfma_f32_16x16x32_bf16 v[80:83], v[24:27], v[196:199], v[80:83]
	v_mfma_f32_16x16x32_bf16 v[84:87], v[112:115], v[196:199], v[84:87]
	v_mfma_f32_16x16x32_bf16 v[88:91], v[24:27], v[204:207], v[88:91]
	v_mfma_f32_16x16x32_bf16 v[92:95], v[112:115], v[204:207], v[92:95]
	v_mfma_f32_16x16x32_bf16 v[64:67], v[28:31], v[184:187], v[64:67]
	v_mfma_f32_16x16x32_bf16 v[68:71], v[116:119], v[184:187], v[68:71]
	v_mfma_f32_16x16x32_bf16 v[72:75], v[28:31], v[192:195], v[72:75]
	v_mfma_f32_16x16x32_bf16 v[76:79], v[116:119], v[192:195], v[76:79]
	v_mfma_f32_16x16x32_bf16 v[80:83], v[28:31], v[200:203], v[80:83]
	v_mfma_f32_16x16x32_bf16 v[84:87], v[116:119], v[200:203], v[84:87]
	v_mfma_f32_16x16x32_bf16 v[88:91], v[28:31], v[208:211], v[88:91]
	v_mfma_f32_16x16x32_bf16 v[92:95], v[116:119], v[208:211], v[92:95]
	v_mfma_f32_16x16x32_bf16 v[96:99], v[120:123], v[180:183], v[96:99]
	v_mfma_f32_16x16x32_bf16 v[32:35], v[172:175], v[180:183], v[32:35]
	v_mfma_f32_16x16x32_bf16 v[36:39], v[120:123], v[188:191], v[36:39]
	v_mfma_f32_16x16x32_bf16 v[40:43], v[172:175], v[188:191], v[40:43]
	v_mfma_f32_16x16x32_bf16 v[44:47], v[120:123], v[196:199], v[44:47]
	v_mfma_f32_16x16x32_bf16 v[48:51], v[172:175], v[196:199], v[48:51]
	v_mfma_f32_16x16x32_bf16 v[52:55], v[120:123], v[204:207], v[52:55]
	v_mfma_f32_16x16x32_bf16 v[56:59], v[172:175], v[204:207], v[56:59]
	v_mfma_f32_16x16x32_bf16 v[96:99], v[124:127], v[184:187], v[96:99]
	v_mfma_f32_16x16x32_bf16 v[32:35], v[176:179], v[184:187], v[32:35]
	v_mfma_f32_16x16x32_bf16 v[36:39], v[124:127], v[192:195], v[36:39]
	v_mfma_f32_16x16x32_bf16 v[40:43], v[176:179], v[192:195], v[40:43]
	v_mfma_f32_16x16x32_bf16 v[44:47], v[124:127], v[200:203], v[44:47]
	v_mfma_f32_16x16x32_bf16 v[48:51], v[176:179], v[200:203], v[48:51]
	v_mfma_f32_16x16x32_bf16 v[52:55], v[124:127], v[208:211], v[52:55]
	v_mfma_f32_16x16x32_bf16 v[56:59], v[176:179], v[208:211], v[56:59]
	s_setprio 0
	s_barrier
; #define PG8_STAGE(bufoff, gbase, voff) do { _Pragma("unroll") for (int _i = 0; _i < 2; ++_i) \
;         __builtin_amdgcn_global_load_lds((const unsigned*)((const char*)(gbase) + (voff)[_i]), (PG8_LAS unsigned*)(lds + (bufoff) + ldsw + _i * 8192), 16, 0, 0); } while (0)
; #define PG8_LDA(dst, b, h) do { _Pragma("unroll") for (int m = 0; m < 4; ++m) _Pragma("unroll") for (int k = 0; k < 2; ++k) dst[m][k] = *(const PG8_LAS bf16x8*)(lds + PG8_SA(b, h) + aoff + m * 2048 + k * 1024); } while (0)
; #define PG8_LDB(dst, b, h) do { _Pragma("unroll") for (int n = 0; n < 2; ++n) _Pragma("unroll") for (int k = 0; k < 2; ++k) dst[n][k] = *(const PG8_LAS bf16x8*)(lds + PG8_SB(b, h) + boff + n * 2048 + k * 1024); } while (0)
; #define PG8_MMA(ai, bj, At, Bt) do { __builtin_amdgcn_s_setprio(1); _Pragma("unroll") for (int m = 0; m < 4; ++m) _Pragma("unroll") for (int n = 0; n < 2; ++n) _Pragma("unroll") for (int k = 0; k < 2; ++k) \
;         acc[ai][bj][m][n] = __builtin_amdgcn_mfma_f32_16x16x32_bf16(Bt[n][k], At[m][k], acc[ai][bj][m][n], 0, 0, 0); __builtin_amdgcn_s_setprio(0); } while (0)
; #define PG8_WAIT_V(n) asm volatile("s_waitcnt vmcnt(" #n ")" ::: "memory")
; template <class Epi, class Sched, bool ALIGN_EPI = false, bool SP2 = false>
; __device__ __forceinline__ void gemm_phase(PG8_LAS unsigned char* lds, const Gemm g, const Sched& S, const Epi& E) {
;     ...
;             PG8_LDB(B0, 0, 0); PG8_LDB(B1, 0, 1); PG8_SCHED; PG8_LDA(At, 0, 0); PG8_STAGE(PG8_SA(1, 1), a1 + hstepA, voffA);
;             PG8_WAIT_V(8); PG8_WAIT_L(0); PG8_BAR; PG8_MMA(0, 0, At, B0); PG8_MMA(0, 1, At, B1); PG8_BAR; PG8_SCHED;
;             PG8_LDA(At, 0, 1); PG8_STAGE(PG8_SB(0, 0), b2, voffB); PG8_STAGE(PG8_SB(0, 1), b2 + hstepB, voffB); PG8_STAGE(PG8_SA(0, 0), a2, voffA);
;             PG8_WAIT_V(8); PG8_WAIT_L(0); PG8_BAR; PG8_MMA(1, 0, At, B0); PG8_MMA(1, 1, At, B1); PG8_BAR; PG8_SCHED;
;             PG8_LDB(B0, 1, 0); PG8_LDB(B1, 1, 1); PG8_SCHED; PG8_LDA(At, 1, 0); PG8_STAGE(PG8_SA(0, 1), a2 + hstepA, voffA);
;             PG8_WAIT_V(8); PG8_WAIT_L(0); PG8_BAR; PG8_MMA(0, 0, At, B0); PG8_MMA(0, 1, At, B1); PG8_BAR; PG8_SCHED;
;             PG8_LDA(At, 1, 1); PG8_STAGE(PG8_SB(1, 0), b3, voffB); PG8_STAGE(PG8_SB(1, 1), b3 + hstepB, voffB); PG8_STAGE(PG8_SA(1, 0), a3, voffA);
;             PG8_WAIT_V(8); PG8_WAIT_L(0); PG8_BAR; PG8_MMA(1, 0, At, B0); PG8_MMA(1, 1, At, B1); PG8_BAR; PG8_SCHED;
	s_add_i32 s89, s89, s47
	s_add_i32 s87, s89, 0x2000
	v_lshl_add_u64 v[164:165], v[164:165], 0, s[38:39]
	s_mov_b32 m0, s89
	s_add_u32 s4, s14, 0x10180
	ds_read_b128 v[180:183], v170 offset:49152
	ds_read_b128 v[184:187], v170 offset:50176
	ds_read_b128 v[188:191], v170 offset:51200
	ds_read_b128 v[192:195], v170 offset:52224
	ds_read_b128 v[196:199], v170 offset:53248
	ds_read_b128 v[200:203], v170 offset:54272
	ds_read_b128 v[204:207], v170 offset:55296
	ds_read_b128 v[208:211], v170 offset:56320
	global_load_lds_dwordx4 v[164:165], off
	v_lshl_add_u64 v[164:165], v[212:213], 0, s[38:39]
	s_mov_b32 m0, s87
	s_addc_u32 s5, s15, 0
	s_add_i32 s14, s90, s47
	global_load_lds_dwordx4 v[164:165], off
	v_lshl_add_u64 v[164:165], s[4:5], 0, v[136:137]
	s_mov_b32 m0, s14
	s_add_i32 s15, s14, 0x2000
	global_load_lds_dwordx4 v[164:165], off
	v_lshl_add_u64 v[164:165], s[4:5], 0, v[132:133]
	s_mov_b32 m0, s15
	s_nop 0
	global_load_lds_dwordx4 v[164:165], off
	v_lshl_add_u64 v[164:165], v[214:215], 0, s[38:39]
	s_mov_b32 m0, s41
	s_nop 0
	global_load_lds_dwordx4 v[164:165], off
	v_lshl_add_u64 v[164:165], v[216:217], 0, s[38:39]
	s_mov_b32 m0, s44
	s_nop 0
	global_load_lds_dwordx4 v[164:165], off
	s_waitcnt vmcnt(8)
	s_waitcnt lgkmcnt(0)
	s_barrier
	s_setprio 1
	s_waitcnt lgkmcnt(0)
	v_mfma_f32_16x16x32_bf16 v[0:3], v[24:27], v[204:207], v[0:3]
	v_mfma_f32_16x16x32_bf16 v[4:7], v[112:115], v[204:207], v[4:7]
	v_mfma_f32_16x16x32_bf16 v[128:131], v[24:27], v[180:183], v[128:131]
	v_mfma_f32_16x16x32_bf16 v[144:147], v[112:115], v[180:183], v[144:147]
	v_mfma_f32_16x16x32_bf16 v[148:151], v[24:27], v[188:191], v[148:151]
	v_mfma_f32_16x16x32_bf16 v[152:155], v[112:115], v[188:191], v[152:155]
	v_mfma_f32_16x16x32_bf16 v[156:159], v[24:27], v[196:199], v[156:159]
	v_mfma_f32_16x16x32_bf16 v[160:163], v[112:115], v[196:199], v[160:163]
	v_mfma_f32_16x16x32_bf16 v[0:3], v[28:31], v[208:211], v[0:3]
	v_mfma_f32_16x16x32_bf16 v[4:7], v[116:119], v[208:211], v[4:7]
	v_mfma_f32_16x16x32_bf16 v[128:131], v[28:31], v[184:187], v[128:131]
	v_mfma_f32_16x16x32_bf16 v[144:147], v[116:119], v[184:187], v[144:147]
	v_mfma_f32_16x16x32_bf16 v[148:151], v[28:31], v[192:195], v[148:151]
	v_mfma_f32_16x16x32_bf16 v[152:155], v[116:119], v[192:195], v[152:155]
	v_mfma_f32_16x16x32_bf16 v[156:159], v[28:31], v[200:203], v[156:159]
	v_mfma_f32_16x16x32_bf16 v[160:163], v[116:119], v[200:203], v[160:163]
	v_mfma_f32_16x16x32_bf16 v[8:11], v[120:123], v[180:183], v[8:11]
	v_mfma_f32_16x16x32_bf16 v[12:15], v[172:175], v[180:183], v[12:15]
	v_mfma_f32_16x16x32_bf16 v[24:27], v[120:123], v[188:191], v[60:63]
	v_mfma_f32_16x16x32_bf16 v[28:31], v[172:175], v[188:191], v[100:103]
	v_mfma_f32_16x16x32_bf16 v[60:63], v[120:123], v[196:199], v[104:107]
	v_mfma_f32_16x16x32_bf16 v[100:103], v[172:175], v[196:199], v[108:111]
	v_mfma_f32_16x16x32_bf16 v[16:19], v[120:123], v[204:207], v[16:19]
	v_mfma_f32_16x16x32_bf16 v[20:23], v[172:175], v[204:207], v[20:23]
	v_mfma_f32_16x16x32_bf16 v[8:11], v[124:127], v[184:187], v[8:11]
	v_mfma_f32_16x16x32_bf16 v[12:15], v[176:179], v[184:187], v[12:15]
	v_mfma_f32_16x16x32_bf16 v[24:27], v[124:127], v[192:195], v[24:27]
	v_mfma_f32_16x16x32_bf16 v[28:31], v[176:179], v[192:195], v[28:31]
	v_mfma_f32_16x16x32_bf16 v[60:63], v[124:127], v[200:203], v[60:63]
	v_mfma_f32_16x16x32_bf16 v[100:103], v[176:179], v[200:203], v[100:103]
	v_mfma_f32_16x16x32_bf16 v[16:19], v[124:127], v[208:211], v[16:19]
	v_mfma_f32_16x16x32_bf16 v[20:23], v[176:179], v[208:211], v[20:23]
	s_setprio 0
	s_barrier
	ds_read_b128 v[104:107], v168
	ds_read_b128 v[108:111], v168 offset:1024
	ds_read_b128 v[112:115], v168 offset:2048
	ds_read_b128 v[116:119], v168 offset:3072
	ds_read_b128 v[120:123], v169
	ds_read_b128 v[124:127], v169 offset:1024
	ds_read_b128 v[172:175], v169 offset:2048
	ds_read_b128 v[176:179], v169 offset:3072
	s_add_u32 s4, s12, 0x80180
	s_addc_u32 s5, s13, 0
	s_mov_b32 m0, s88
	v_lshl_add_u64 v[164:165], s[4:5], 0, v[138:139]
	ds_read_b128 v[180:183], v170
	ds_read_b128 v[184:187], v170 offset:1024
	ds_read_b128 v[188:191], v170 offset:2048
	ds_read_b128 v[192:195], v170 offset:3072
	ds_read_b128 v[196:199], v170 offset:4096
	ds_read_b128 v[200:203], v170 offset:5120
	ds_read_b128 v[204:207], v170 offset:6144
	ds_read_b128 v[208:211], v170 offset:7168
	global_load_lds_dwordx4 v[164:165], off
	v_lshl_add_u64 v[164:165], s[4:5], 0, v[134:135]
	s_mov_b32 m0, s11
	s_nop 0
	global_load_lds_dwordx4 v[164:165], off
	s_waitcnt vmcnt(8)
	s_waitcnt lgkmcnt(0)
	s_barrier
; #define PG8_STAGE(bufoff, gbase, voff) do { _Pragma("unroll") for (int _i = 0; _i < 2; ++_i) \
;         __builtin_amdgcn_global_load_lds((const unsigned*)((const char*)(gbase) + (voff)[_i]), (PG8_LAS unsigned*)(lds + (bufoff) + ldsw + _i * 8192), 16, 0, 0); } while (0)
; #define PG8_LDA(dst, b, h) do { _Pragma("unroll") for (int m = 0; m < 4; ++m) _Pragma("unroll") for (int k = 0; k < 2; ++k) dst[m][k] = *(const PG8_LAS bf16x8*)(lds + PG8_SA(b, h) + aoff + m * 2048 + k * 1024); } while (0)
; #define PG8_MMA(ai, bj, At, Bt) do { __builtin_amdgcn_s_setprio(1); _Pragma("unroll") for (int m = 0; m < 4; ++m) _Pragma("unroll") for (int n = 0; n < 2; ++n) _Pragma("unroll") for (int k = 0; k < 2; ++k) \
;         acc[ai][bj][m][n] = __builtin_amdgcn_mfma_f32_16x16x32_bf16(Bt[n][k], At[m][k], acc[ai][bj][m][n], 0, 0, 0); __builtin_amdgcn_s_setprio(0); } while (0)
; #define PG8_WAIT_V(n) asm volatile("s_waitcnt vmcnt(" #n ")" ::: "memory")
; #define PG8_WAIT_L(n) asm volatile("s_waitcnt lgkmcnt(" #n ")" ::: "memory")
; #define PG8_BAR __builtin_amdgcn_s_barrier()
; #define PG8_SCHED __builtin_amdgcn_sched_barrier(0)
; template <class Epi, class Sched, bool ALIGN_EPI = false, bool SP2 = false>
; __device__ __forceinline__ void gemm_phase(PG8_LAS unsigned char* lds, const Gemm g, const Sched& S, const Epi& E) {
;     ...
;             PG8_WAIT_V(8); PG8_WAIT_L(0); PG8_BAR; PG8_MMA(0, 0, At, B0); PG8_MMA(0, 1, At, B1); PG8_BAR; PG8_SCHED;
;             PG8_LDA(At, 0, 1); PG8_STAGE(PG8_SB(0, 0), b2, voffB); PG8_STAGE(PG8_SB(0, 1), b2 + hstepB, voffB); PG8_STAGE(PG8_SA(0, 0), a2, voffA);
;             PG8_WAIT_V(8); PG8_WAIT_L(0); PG8_BAR; PG8_MMA(1, 0, At, B0); PG8_MMA(1, 1, At, B1); PG8_BAR; PG8_SCHED;
	s_setprio 1
	s_waitcnt lgkmcnt(0)
	v_mfma_f32_16x16x32_bf16 v[88:91], v[104:107], v[204:207], v[88:91]
	v_mfma_f32_16x16x32_bf16 v[64:67], v[104:107], v[180:183], v[64:67]
	v_mfma_f32_16x16x32_bf16 v[68:71], v[112:115], v[180:183], v[68:71]
	v_mfma_f32_16x16x32_bf16 v[72:75], v[104:107], v[188:191], v[72:75]
	v_mfma_f32_16x16x32_bf16 v[76:79], v[112:115], v[188:191], v[76:79]
	v_mfma_f32_16x16x32_bf16 v[80:83], v[104:107], v[196:199], v[80:83]
	v_mfma_f32_16x16x32_bf16 v[84:87], v[112:115], v[196:199], v[84:87]
	v_mfma_f32_16x16x32_bf16 v[212:215], v[108:111], v[208:211], v[88:91]
	v_mfma_f32_16x16x32_bf16 v[88:91], v[112:115], v[204:207], v[92:95]
	v_mfma_f32_16x16x32_bf16 v[64:67], v[108:111], v[184:187], v[64:67]
	v_mfma_f32_16x16x32_bf16 v[68:71], v[116:119], v[184:187], v[68:71]
	v_mfma_f32_16x16x32_bf16 v[72:75], v[108:111], v[192:195], v[72:75]
	v_mfma_f32_16x16x32_bf16 v[76:79], v[116:119], v[192:195], v[76:79]
	v_mfma_f32_16x16x32_bf16 v[80:83], v[108:111], v[200:203], v[80:83]
	v_mfma_f32_16x16x32_bf16 v[84:87], v[116:119], v[200:203], v[84:87]
	v_mfma_f32_16x16x32_bf16 v[92:95], v[116:119], v[208:211], v[88:91]
	v_mfma_f32_16x16x32_bf16 v[32:35], v[172:175], v[180:183], v[32:35]
	v_mfma_f32_16x16x32_bf16 v[36:39], v[120:123], v[188:191], v[36:39]
	v_mfma_f32_16x16x32_bf16 v[40:43], v[172:175], v[188:191], v[40:43]
	v_mfma_f32_16x16x32_bf16 v[44:47], v[120:123], v[196:199], v[44:47]
	v_mfma_f32_16x16x32_bf16 v[48:51], v[172:175], v[196:199], v[48:51]
	v_mfma_f32_16x16x32_bf16 v[52:55], v[120:123], v[204:207], v[52:55]
	v_mfma_f32_16x16x32_bf16 v[56:59], v[172:175], v[204:207], v[56:59]
	v_mfma_f32_16x16x32_bf16 v[88:91], v[120:123], v[180:183], v[96:99]
	v_mfma_f32_16x16x32_bf16 v[32:35], v[176:179], v[184:187], v[32:35]
	v_mfma_f32_16x16x32_bf16 v[36:39], v[124:127], v[192:195], v[36:39]
	v_mfma_f32_16x16x32_bf16 v[40:43], v[176:179], v[192:195], v[40:43]
	v_mfma_f32_16x16x32_bf16 v[44:47], v[124:127], v[200:203], v[44:47]
	v_mfma_f32_16x16x32_bf16 v[48:51], v[176:179], v[200:203], v[48:51]
	v_mfma_f32_16x16x32_bf16 v[52:55], v[124:127], v[208:211], v[52:55]
	v_mfma_f32_16x16x32_bf16 v[56:59], v[176:179], v[208:211], v[56:59]
	v_mfma_f32_16x16x32_bf16 v[216:219], v[124:127], v[184:187], v[88:91]
	s_setprio 0
	s_barrier
	s_mov_b32 m0, s86
	v_lshl_add_u64 v[164:165], s[68:69], 0, v[136:137]
	s_add_u32 s4, s68, 0x10000
	ds_read_b128 v[88:91], v170 offset:16384
	ds_read_b128 v[96:99], v170 offset:17408
	ds_read_b128 v[180:183], v170 offset:18432
	ds_read_b128 v[184:187], v170 offset:19456
	ds_read_b128 v[188:191], v170 offset:20480
	ds_read_b128 v[192:195], v170 offset:21504
	ds_read_b128 v[196:199], v170 offset:22528
	ds_read_b128 v[200:203], v170 offset:23552
	global_load_lds_dwordx4 v[164:165], off
	v_lshl_add_u64 v[244:245], s[68:69], 0, v[132:133]
	s_mov_b32 m0, s61
	s_addc_u32 s5, s69, 0
	global_load_lds_dwordx4 v[244:245], off
	v_lshl_add_u64 v[204:205], s[4:5], 0, v[136:137]
	s_mov_b32 m0, s63
	v_lshl_add_u64 v[246:247], s[70:71], 0, v[138:139]
	global_load_lds_dwordx4 v[204:205], off
	v_lshl_add_u64 v[204:205], s[4:5], 0, v[132:133]
	s_mov_b32 m0, s85
	v_lshl_add_u64 v[248:249], s[70:71], 0, v[134:135]
	global_load_lds_dwordx4 v[204:205], off
	s_mov_b32 m0, s3
	s_nop 0
	global_load_lds_dwordx4 v[246:247], off
	s_mov_b32 m0, s24
	s_nop 0
	global_load_lds_dwordx4 v[248:249], off
	s_waitcnt vmcnt(8)
	s_waitcnt lgkmcnt(0)
	s_barrier
	s_setprio 1
	s_waitcnt lgkmcnt(0)
	v_mfma_f32_16x16x32_bf16 v[0:3], v[104:107], v[196:199], v[0:3]
	v_mfma_f32_16x16x32_bf16 v[4:7], v[112:115], v[196:199], v[4:7]
	v_mfma_f32_16x16x32_bf16 v[128:131], v[104:107], v[88:91], v[128:131]
	v_mfma_f32_16x16x32_bf16 v[144:147], v[112:115], v[88:91], v[144:147]
	v_mfma_f32_16x16x32_bf16 v[148:151], v[104:107], v[180:183], v[148:151]
	v_mfma_f32_16x16x32_bf16 v[152:155], v[112:115], v[180:183], v[152:155]
	v_mfma_f32_16x16x32_bf16 v[156:159], v[104:107], v[188:191], v[156:159]
	v_mfma_f32_16x16x32_bf16 v[160:163], v[112:115], v[188:191], v[160:163]
	v_mfma_f32_16x16x32_bf16 v[0:3], v[108:111], v[200:203], v[0:3]
	v_mfma_f32_16x16x32_bf16 v[4:7], v[116:119], v[200:203], v[4:7]
	v_mfma_f32_16x16x32_bf16 v[128:131], v[108:111], v[96:99], v[128:131]
	v_mfma_f32_16x16x32_bf16 v[144:147], v[116:119], v[96:99], v[144:147]
	v_mfma_f32_16x16x32_bf16 v[148:151], v[108:111], v[184:187], v[148:151]
	v_mfma_f32_16x16x32_bf16 v[152:155], v[116:119], v[184:187], v[152:155]
	v_mfma_f32_16x16x32_bf16 v[156:159], v[108:111], v[192:195], v[156:159]
	v_mfma_f32_16x16x32_bf16 v[160:163], v[116:119], v[192:195], v[160:163]
	v_mfma_f32_16x16x32_bf16 v[8:11], v[120:123], v[88:91], v[8:11]
	v_mfma_f32_16x16x32_bf16 v[204:207], v[124:127], v[96:99], v[8:11]
	v_mfma_f32_16x16x32_bf16 v[8:11], v[172:175], v[88:91], v[12:15]
	v_mfma_f32_16x16x32_bf16 v[12:15], v[176:179], v[96:99], v[8:11]
	v_mfma_f32_16x16x32_bf16 v[8:11], v[120:123], v[180:183], v[24:27]
	v_mfma_f32_16x16x32_bf16 v[208:211], v[124:127], v[184:187], v[8:11]
	v_mfma_f32_16x16x32_bf16 v[8:11], v[172:175], v[180:183], v[28:31]
	v_mfma_f32_16x16x32_bf16 v[28:31], v[176:179], v[184:187], v[8:11]
	v_mfma_f32_16x16x32_bf16 v[8:11], v[120:123], v[188:191], v[60:63]
	v_mfma_f32_16x16x32_bf16 v[180:183], v[124:127], v[192:195], v[8:11]
	v_mfma_f32_16x16x32_bf16 v[8:11], v[172:175], v[188:191], v[100:103]
	v_mfma_f32_16x16x32_bf16 v[184:187], v[176:179], v[192:195], v[8:11]
	v_mfma_f32_16x16x32_bf16 v[8:11], v[120:123], v[196:199], v[16:19]
	v_mfma_f32_16x16x32_bf16 v[188:191], v[124:127], v[200:203], v[8:11]
	v_mfma_f32_16x16x32_bf16 v[8:11], v[172:175], v[196:199], v[20:23]
	v_mfma_f32_16x16x32_bf16 v[172:175], v[176:179], v[200:203], v[8:11]
	s_setprio 0
	s_barrier
; #define PG8_STAGE(bufoff, gbase, voff) do { _Pragma("unroll") for (int _i = 0; _i < 2; ++_i) \
;         __builtin_amdgcn_global_load_lds((const unsigned*)((const char*)(gbase) + (voff)[_i]), (PG8_LAS unsigned*)(lds + (bufoff) + ldsw + _i * 8192), 16, 0, 0); } while (0)
; #define PG8_LDA(dst, b, h) do { _Pragma("unroll") for (int m = 0; m < 4; ++m) _Pragma("unroll") for (int k = 0; k < 2; ++k) dst[m][k] = *(const PG8_LAS bf16x8*)(lds + PG8_SA(b, h) + aoff + m * 2048 + k * 1024); } while (0)
; #define PG8_LDB(dst, b, h) do { _Pragma("unroll") for (int n = 0; n < 2; ++n) _Pragma("unroll") for (int k = 0; k < 2; ++k) dst[n][k] = *(const PG8_LAS bf16x8*)(lds + PG8_SB(b, h) + boff + n * 2048 + k * 1024); } while (0)
; #define PG8_MMA(ai, bj, At, Bt) do { __builtin_amdgcn_s_setprio(1); _Pragma("unroll") for (int m = 0; m < 4; ++m) _Pragma("unroll") for (int n = 0; n < 2; ++n) _Pragma("unroll") for (int k = 0; k < 2; ++k) \
;         acc[ai][bj][m][n] = __builtin_amdgcn_mfma_f32_16x16x32_bf16(Bt[n][k], At[m][k], acc[ai][bj][m][n], 0, 0, 0); __builtin_amdgcn_s_setprio(0); } while (0)
; #define PG8_WAIT_V(n) asm volatile("s_waitcnt vmcnt(" #n ")" ::: "memory")
; #define PG8_WAIT_L(n) asm volatile("s_waitcnt lgkmcnt(" #n ")" ::: "memory")
; #define PG8_BAR __builtin_amdgcn_s_barrier()
; #define PG8_SCHED __builtin_amdgcn_sched_barrier(0)
; template <class Epi, class Sched, bool ALIGN_EPI = false, bool SP2 = false>
; __device__ __forceinline__ void gemm_phase(PG8_LAS unsigned char* lds, const Gemm g, const Sched& S, const Epi& E) {
;     ...
;             PG8_LDB(B0, 1, 0); PG8_LDB(B1, 1, 1); PG8_SCHED; PG8_LDA(At, 1, 0); PG8_STAGE(PG8_SA(0, 1), a2 + hstepA, voffA);
;             PG8_WAIT_V(8); PG8_WAIT_L(0); PG8_BAR; PG8_MMA(0, 0, At, B0); PG8_MMA(0, 1, At, B1); PG8_BAR; PG8_SCHED;
;             PG8_LDA(At, 1, 1); PG8_STAGE(PG8_SB(1, 0), b3, voffB); PG8_STAGE(PG8_SB(1, 1), b3 + hstepB, voffB); PG8_STAGE(PG8_SA(1, 0), a3, voffA);
;             PG8_WAIT_V(8); PG8_WAIT_L(0); PG8_BAR; PG8_MMA(1, 0, At, B0); PG8_MMA(1, 1, At, B1); PG8_BAR; PG8_SCHED;
;     ...
;         if constexpr (ALIGN_EPI) { if (wr == 0) PG8_BAR; }
	s_nop 4
	ds_read_b128 v[8:11], v220
	ds_read_b128 v[20:23], v220 offset:1024
	ds_read_b128 v[60:63], v220 offset:2048
	ds_read_b128 v[176:179], v220 offset:3072
	ds_read_b128 v[192:195], v221
	ds_read_b128 v[196:199], v221 offset:1024
	ds_read_b128 v[200:203], v221 offset:2048
	ds_read_b128 v[220:223], v221 offset:3072
	s_add_u32 s4, s70, 0x80000
	s_addc_u32 s5, s71, 0
	s_mov_b32 m0, s25
	v_lshl_add_u64 v[88:89], s[4:5], 0, v[138:139]
	ds_read_b128 v[16:19], v170 offset:32768
	ds_read_b128 v[24:27], v170 offset:33792
	ds_read_b128 v[100:103], v170 offset:34816
	ds_read_b128 v[224:227], v170 offset:35840
	ds_read_b128 v[228:231], v170 offset:36864
	ds_read_b128 v[232:235], v170 offset:37888
	ds_read_b128 v[236:239], v170 offset:38912
	ds_read_b128 v[240:243], v170 offset:39936
	global_load_lds_dwordx4 v[88:89], off
	v_lshl_add_u64 v[88:89], s[4:5], 0, v[134:135]
	s_mov_b32 m0, s33
	s_nop 0
	global_load_lds_dwordx4 v[88:89], off
	s_waitcnt vmcnt(8)
	s_waitcnt lgkmcnt(0)
	s_barrier
	s_setprio 1
	s_waitcnt lgkmcnt(0)
	v_mfma_f32_16x16x32_bf16 v[64:67], v[8:11], v[16:19], v[64:67]
	v_mfma_f32_16x16x32_bf16 v[120:123], v[20:23], v[24:27], v[64:67]
	v_mfma_f32_16x16x32_bf16 v[64:67], v[60:63], v[16:19], v[68:71]
	v_mfma_f32_16x16x32_bf16 v[112:115], v[176:179], v[24:27], v[64:67]
	v_mfma_f32_16x16x32_bf16 v[64:67], v[8:11], v[100:103], v[72:75]
	v_mfma_f32_16x16x32_bf16 v[104:107], v[20:23], v[224:227], v[64:67]
	v_mfma_f32_16x16x32_bf16 v[64:67], v[60:63], v[100:103], v[76:79]
	v_mfma_f32_16x16x32_bf16 v[96:99], v[176:179], v[224:227], v[64:67]
	v_mfma_f32_16x16x32_bf16 v[64:67], v[8:11], v[228:231], v[80:83]
	v_mfma_f32_16x16x32_bf16 v[88:91], v[20:23], v[232:235], v[64:67]
	v_mfma_f32_16x16x32_bf16 v[64:67], v[60:63], v[228:231], v[84:87]
	v_mfma_f32_16x16x32_bf16 v[80:83], v[176:179], v[232:235], v[64:67]
	v_mfma_f32_16x16x32_bf16 v[64:67], v[8:11], v[236:239], v[212:215]
	v_mfma_f32_16x16x32_bf16 v[72:75], v[20:23], v[240:243], v[64:67]
	v_mfma_f32_16x16x32_bf16 v[64:67], v[60:63], v[236:239], v[92:95]
	v_mfma_f32_16x16x32_bf16 v[64:67], v[176:179], v[240:243], v[64:67]
	v_mfma_f32_16x16x32_bf16 v[68:71], v[192:195], v[16:19], v[216:219]
	v_mfma_f32_16x16x32_bf16 v[16:19], v[200:203], v[16:19], v[32:35]
	v_mfma_f32_16x16x32_bf16 v[116:119], v[220:223], v[24:27], v[16:19]
	v_mfma_f32_16x16x32_bf16 v[16:19], v[192:195], v[100:103], v[36:39]
	v_mfma_f32_16x16x32_bf16 v[108:111], v[196:199], v[224:227], v[16:19]
	v_mfma_f32_16x16x32_bf16 v[16:19], v[200:203], v[100:103], v[40:43]
	v_mfma_f32_16x16x32_bf16 v[100:103], v[220:223], v[224:227], v[16:19]
	v_mfma_f32_16x16x32_bf16 v[16:19], v[192:195], v[228:231], v[44:47]
	v_mfma_f32_16x16x32_bf16 v[92:95], v[196:199], v[232:235], v[16:19]
	v_mfma_f32_16x16x32_bf16 v[16:19], v[200:203], v[228:231], v[48:51]
	v_mfma_f32_16x16x32_bf16 v[84:87], v[220:223], v[232:235], v[16:19]
	v_mfma_f32_16x16x32_bf16 v[16:19], v[192:195], v[236:239], v[52:55]
	v_mfma_f32_16x16x32_bf16 v[76:79], v[196:199], v[240:243], v[16:19]
	v_mfma_f32_16x16x32_bf16 v[16:19], v[200:203], v[236:239], v[56:59]
	v_mfma_f32_16x16x32_bf16 v[124:127], v[196:199], v[24:27], v[68:71]
	v_mfma_f32_16x16x32_bf16 v[68:71], v[220:223], v[240:243], v[16:19]
	s_setprio 0
	s_barrier
	s_mov_b32 m0, s89
	s_nop 2
	v_lshl_add_u64 v[16:17], v[164:165], 0, s[30:31]
	s_add_u32 s4, s68, 0x10080
	ds_read_b128 v[36:39], v170 offset:49152
	ds_read_b128 v[44:47], v170 offset:50176
	ds_read_b128 v[212:215], v170 offset:51200
	ds_read_b128 v[216:219], v170 offset:52224
	ds_read_b128 v[224:227], v170 offset:53248
	ds_read_b128 v[228:231], v170 offset:54272
	ds_read_b128 v[232:235], v170 offset:55296
	ds_read_b128 v[236:239], v170 offset:56320
	global_load_lds_dwordx4 v[16:17], off
	v_lshl_add_u64 v[16:17], v[244:245], 0, s[30:31]
	s_mov_b32 m0, s87
	s_addc_u32 s5, s69, 0
	global_load_lds_dwordx4 v[16:17], off
	v_lshl_add_u64 v[16:17], s[4:5], 0, v[136:137]
	s_mov_b32 m0, s14
	s_nop 0
	global_load_lds_dwordx4 v[16:17], off
	v_lshl_add_u64 v[16:17], s[4:5], 0, v[132:133]
	s_mov_b32 m0, s15
	s_nop 0
	global_load_lds_dwordx4 v[16:17], off
	v_lshl_add_u64 v[16:17], v[246:247], 0, s[30:31]
	s_mov_b32 m0, s41
	s_nop 0
	global_load_lds_dwordx4 v[16:17], off
	v_lshl_add_u64 v[16:17], v[248:249], 0, s[30:31]
	s_mov_b32 m0, s44
	s_nop 0
	global_load_lds_dwordx4 v[16:17], off
	s_waitcnt vmcnt(8)
	s_waitcnt lgkmcnt(0)
	s_barrier
	s_setprio 1
	s_waitcnt lgkmcnt(0)
	v_mfma_f32_16x16x32_bf16 v[16:19], v[8:11], v[36:39], v[128:131]
	v_mfma_f32_16x16x32_bf16 v[56:59], v[20:23], v[44:47], v[16:19]
	v_mfma_f32_16x16x32_bf16 v[16:19], v[60:63], v[36:39], v[144:147]
	v_mfma_f32_16x16x32_bf16 v[48:51], v[176:179], v[44:47], v[16:19]
	v_mfma_f32_16x16x32_bf16 v[16:19], v[8:11], v[212:215], v[148:151]
	v_mfma_f32_16x16x32_bf16 v[40:43], v[20:23], v[216:219], v[16:19]
	v_mfma_f32_16x16x32_bf16 v[16:19], v[60:63], v[212:215], v[152:155]
	v_mfma_f32_16x16x32_bf16 v[32:35], v[176:179], v[216:219], v[16:19]
	v_mfma_f32_16x16x32_bf16 v[16:19], v[8:11], v[224:227], v[156:159]
	v_mfma_f32_16x16x32_bf16 v[0:3], v[8:11], v[232:235], v[0:3]
	v_mfma_f32_16x16x32_bf16 v[24:27], v[20:23], v[228:231], v[16:19]
	v_mfma_f32_16x16x32_bf16 v[16:19], v[60:63], v[224:227], v[160:163]
	v_mfma_f32_16x16x32_bf16 v[8:11], v[20:23], v[236:239], v[0:3]
	v_mfma_f32_16x16x32_bf16 v[0:3], v[60:63], v[232:235], v[4:7]
	v_mfma_f32_16x16x32_bf16 v[16:19], v[176:179], v[228:231], v[16:19]
	v_mfma_f32_16x16x32_bf16 v[0:3], v[176:179], v[236:239], v[0:3]
	v_mfma_f32_16x16x32_bf16 v[4:7], v[192:195], v[36:39], v[204:207]
	v_mfma_f32_16x16x32_bf16 v[60:63], v[196:199], v[44:47], v[4:7]
	v_mfma_f32_16x16x32_bf16 v[4:7], v[200:203], v[36:39], v[12:15]
	v_mfma_f32_16x16x32_bf16 v[52:55], v[220:223], v[44:47], v[4:7]
	v_mfma_f32_16x16x32_bf16 v[4:7], v[192:195], v[212:215], v[208:211]
	v_mfma_f32_16x16x32_bf16 v[44:47], v[196:199], v[216:219], v[4:7]
	v_mfma_f32_16x16x32_bf16 v[4:7], v[200:203], v[212:215], v[28:31]
	v_mfma_f32_16x16x32_bf16 v[36:39], v[220:223], v[216:219], v[4:7]
	v_mfma_f32_16x16x32_bf16 v[4:7], v[192:195], v[224:227], v[180:183]
	v_mfma_f32_16x16x32_bf16 v[28:31], v[196:199], v[228:231], v[4:7]
	v_mfma_f32_16x16x32_bf16 v[4:7], v[200:203], v[224:227], v[184:187]
	v_mfma_f32_16x16x32_bf16 v[20:23], v[220:223], v[228:231], v[4:7]
	v_mfma_f32_16x16x32_bf16 v[4:7], v[192:195], v[232:235], v[188:191]
	v_mfma_f32_16x16x32_bf16 v[12:15], v[196:199], v[236:239], v[4:7]
	v_mfma_f32_16x16x32_bf16 v[4:7], v[200:203], v[232:235], v[172:175]
	v_mfma_f32_16x16x32_bf16 v[4:7], v[220:223], v[236:239], v[4:7]
	s_setprio 0
	s_barrier
	s_andn2_b64 vcc, exec, s[48:49]
	s_cbranch_vccnz .LBB0_1043
	s_barrier

; #define PG8_STAGE(bufoff, gbase, voff) do { _Pragma("unroll") for (int _i = 0; _i < 2; ++_i) \
;         __builtin_amdgcn_global_load_lds((const unsigned*)((const char*)(gbase) + (voff)[_i]), (PG8_LAS unsigned*)(lds + (bufoff) + ldsw + _i * 8192), 16, 0, 0); } while (0)
; #define PG8_LDA(dst, b, h) do { _Pragma("unroll") for (int m = 0; m < 4; ++m) _Pragma("unroll") for (int k = 0; k < 2; ++k) dst[m][k] = *(const PG8_LAS bf16x8*)(lds + PG8_SA(b, h) + aoff + m * 2048 + k * 1024); } while (0)
; #define PG8_LDB(dst, b, h) do { _Pragma("unroll") for (int n = 0; n < 2; ++n) _Pragma("unroll") for (int k = 0; k < 2; ++k) dst[n][k] = *(const PG8_LAS bf16x8*)(lds + PG8_SB(b, h) + boff + n * 2048 + k * 1024); } while (0)
; #define PG8_MMA(ai, bj, At, Bt) do { __builtin_amdgcn_s_setprio(1); _Pragma("unroll") for (int m = 0; m < 4; ++m) _Pragma("unroll") for (int n = 0; n < 2; ++n) _Pragma("unroll") for (int k = 0; k < 2; ++k) \
;         acc[ai][bj][m][n] = __builtin_amdgcn_mfma_f32_16x16x32_bf16(Bt[n][k], At[m][k], acc[ai][bj][m][n], 0, 0, 0); __builtin_amdgcn_s_setprio(0); } while (0)
; #define PG8_WAIT_V(n) asm volatile("s_waitcnt vmcnt(" #n ")" ::: "memory")
; #define PG8_WAIT_L(n) asm volatile("s_waitcnt lgkmcnt(" #n ")" ::: "memory")
; #define PG8_BAR __builtin_amdgcn_s_barrier()
; #define PG8_SCHED __builtin_amdgcn_sched_barrier(0)
; template <class Epi, class Sched, bool ALIGN_EPI = false, bool SP2 = false>
; __device__ __forceinline__ void gemm_phase(PG8_LAS unsigned char* lds, const Gemm g, const Sched& S, const Epi& E) {
;     ...
;             const char* a1 = cA + (size_t)(t + 1) * kstep;
;             const char* a2 = last ? nA : cA + (size_t)(t + 2) * kstep; const char* b2 = last ? nB : cB + (size_t)(t + 2) * kstep;
;             const char* a3 = a2 + kstep; const char* b3 = b2 + kstep;
;             if (last && has_next) S.a_ready(nxt);
;             if constexpr (SP2) {
;             PG8_LDB(B0, 0, 0); PG8_LDB(B1, 0, 1); PG8_SCHED; PG8_LDA(At, 0, 0); PG8_STAGE(PG8_SA(1, 1), a1 + hstepA, voffA);
;             PG8_WAIT_V(8); PG8_WAIT_L(0); PG8_BAR; PG8_MMA(0, 0, At, B0); PG8_MMA(0, 1, At, B1); PG8_BAR; PG8_SCHED;
;             PG8_LDA(At, 0, 1); PG8_STAGE(PG8_SB(0, 0), b2, voffB); PG8_STAGE(PG8_SB(0, 1), b2 + hstepB, voffB); PG8_STAGE(PG8_SA(0, 0), a2, voffA);
.LBB0_1211:
	ds_read_b128 v[144:147], v149
	ds_read_b128 v[152:155], v149 offset:1024
	ds_read_b128 v[156:159], v149 offset:2048
	ds_read_b128 v[160:163], v149 offset:3072
	ds_read_b128 v[168:171], v150
	ds_read_b128 v[172:175], v150 offset:1024
	ds_read_b128 v[176:179], v150 offset:2048
	ds_read_b128 v[180:183], v150 offset:3072
	s_add_u32 s4, s30, 0xfff80080
	s_addc_u32 s5, s31, -1
	s_cmp_eq_u32 s58, 28
	s_cselect_b32 s37, s21, s5
	s_cselect_b32 s36, s29, s4
	s_cselect_b32 s35, s19, s57
	s_cselect_b32 s34, s55, s56
	v_lshl_add_u64 v[164:165], s[30:31], 0, v[136:137]
	s_add_i32 m0, s25, 0xc000
	ds_read_b128 v[184:187], v151
	ds_read_b128 v[188:191], v151 offset:1024
	ds_read_b128 v[192:195], v151 offset:2048
	ds_read_b128 v[196:199], v151 offset:3072
	ds_read_b128 v[200:203], v151 offset:4096
	ds_read_b128 v[204:207], v151 offset:5120
	ds_read_b128 v[208:211], v151 offset:6144
	ds_read_b128 v[212:215], v151 offset:7168
	global_load_lds_dwordx4 v[164:165], off
	v_lshl_add_u64 v[164:165], s[30:31], 0, v[138:139]
	s_add_i32 m0, s25, 0xe000
	s_nop 0
	global_load_lds_dwordx4 v[164:165], off
	s_waitcnt vmcnt(8)
	s_waitcnt lgkmcnt(0)
	s_barrier
	s_setprio 1
	s_waitcnt lgkmcnt(0)
	v_mfma_f32_16x16x32_bf16 v[124:127], v[144:147], v[184:187], v[124:127]
	v_mfma_f32_16x16x32_bf16 v[120:123], v[156:159], v[184:187], v[120:123]
	v_mfma_f32_16x16x32_bf16 v[108:111], v[144:147], v[192:195], v[108:111]
	v_mfma_f32_16x16x32_bf16 v[104:107], v[156:159], v[192:195], v[104:107]
	v_mfma_f32_16x16x32_bf16 v[92:95], v[144:147], v[200:203], v[92:95]
	v_mfma_f32_16x16x32_bf16 v[88:91], v[156:159], v[200:203], v[88:91]
	v_mfma_f32_16x16x32_bf16 v[76:79], v[144:147], v[208:211], v[76:79]
	v_mfma_f32_16x16x32_bf16 v[72:75], v[156:159], v[208:211], v[72:75]
	v_mfma_f32_16x16x32_bf16 v[124:127], v[152:155], v[188:191], v[124:127]
	v_mfma_f32_16x16x32_bf16 v[120:123], v[160:163], v[188:191], v[120:123]
	v_mfma_f32_16x16x32_bf16 v[108:111], v[152:155], v[196:199], v[108:111]
	v_mfma_f32_16x16x32_bf16 v[104:107], v[160:163], v[196:199], v[104:107]
	v_mfma_f32_16x16x32_bf16 v[92:95], v[152:155], v[204:207], v[92:95]
	v_mfma_f32_16x16x32_bf16 v[88:91], v[160:163], v[204:207], v[88:91]
	v_mfma_f32_16x16x32_bf16 v[76:79], v[152:155], v[212:215], v[76:79]
	v_mfma_f32_16x16x32_bf16 v[72:75], v[160:163], v[212:215], v[72:75]
	v_mfma_f32_16x16x32_bf16 v[116:119], v[168:171], v[184:187], v[116:119]
	v_mfma_f32_16x16x32_bf16 v[112:115], v[176:179], v[184:187], v[112:115]
	v_mfma_f32_16x16x32_bf16 v[100:103], v[168:171], v[192:195], v[100:103]
	v_mfma_f32_16x16x32_bf16 v[96:99], v[176:179], v[192:195], v[96:99]
	v_mfma_f32_16x16x32_bf16 v[84:87], v[168:171], v[200:203], v[84:87]
	v_mfma_f32_16x16x32_bf16 v[80:83], v[176:179], v[200:203], v[80:83]
	v_mfma_f32_16x16x32_bf16 v[68:71], v[168:171], v[208:211], v[68:71]
	v_mfma_f32_16x16x32_bf16 v[64:67], v[176:179], v[208:211], v[64:67]
	v_mfma_f32_16x16x32_bf16 v[116:119], v[172:175], v[188:191], v[116:119]
	v_mfma_f32_16x16x32_bf16 v[112:115], v[180:183], v[188:191], v[112:115]
	v_mfma_f32_16x16x32_bf16 v[100:103], v[172:175], v[196:199], v[100:103]
	v_mfma_f32_16x16x32_bf16 v[96:99], v[180:183], v[196:199], v[96:99]
	v_mfma_f32_16x16x32_bf16 v[84:87], v[172:175], v[204:207], v[84:87]
	v_mfma_f32_16x16x32_bf16 v[80:83], v[180:183], v[204:207], v[80:83]
	v_mfma_f32_16x16x32_bf16 v[68:71], v[172:175], v[212:215], v[68:71]
	v_mfma_f32_16x16x32_bf16 v[64:67], v[180:183], v[212:215], v[64:67]
	s_setprio 0
	s_barrier
	s_add_i32 s4, s44, s47
	v_lshl_add_u64 v[164:165], s[34:35], 0, v[130:131]
	s_mov_b32 m0, s4
	ds_read_b128 v[184:187], v151 offset:16384
	ds_read_b128 v[188:191], v151 offset:17408
	ds_read_b128 v[192:195], v151 offset:18432
	ds_read_b128 v[196:199], v151 offset:19456
	ds_read_b128 v[200:203], v151 offset:20480
	ds_read_b128 v[204:207], v151 offset:21504
	ds_read_b128 v[208:211], v151 offset:22528
	ds_read_b128 v[212:215], v151 offset:23552
	global_load_lds_dwordx4 v[164:165], off
	s_add_i32 m0, s4, 0x2000
	s_add_u32 s4, s34, 0x80000
	v_lshl_add_u64 v[216:217], s[34:35], 0, v[134:135]
	s_addc_u32 s5, s35, 0
	s_add_i32 s59, s45, s47
	global_load_lds_dwordx4 v[216:217], off
	v_lshl_add_u64 v[218:219], s[4:5], 0, v[130:131]
	s_mov_b32 m0, s59
	v_lshl_add_u64 v[220:221], s[36:37], 0, v[132:133]
	global_load_lds_dwordx4 v[218:219], off
	v_lshl_add_u64 v[218:219], s[4:5], 0, v[134:135]
	s_add_i32 m0, s59, 0x2000
	s_nop 0
	global_load_lds_dwordx4 v[218:219], off
	v_lshl_add_u64 v[218:219], s[36:37], 0, v[128:129]
	s_mov_b32 m0, s25
	s_nop 0
	global_load_lds_dwordx4 v[218:219], off
	s_mov_b32 m0, s33
	s_nop 0
	global_load_lds_dwordx4 v[220:221], off
	s_waitcnt vmcnt(8)
	s_waitcnt lgkmcnt(0)
	s_barrier
; #define PG8_STAGE(bufoff, gbase, voff) do { _Pragma("unroll") for (int _i = 0; _i < 2; ++_i) \
;         __builtin_amdgcn_global_load_lds((const unsigned*)((const char*)(gbase) + (voff)[_i]), (PG8_LAS unsigned*)(lds + (bufoff) + ldsw + _i * 8192), 16, 0, 0); } while (0)
; #define PG8_LDA(dst, b, h) do { _Pragma("unroll") for (int m = 0; m < 4; ++m) _Pragma("unroll") for (int k = 0; k < 2; ++k) dst[m][k] = *(const PG8_LAS bf16x8*)(lds + PG8_SA(b, h) + aoff + m * 2048 + k * 1024); } while (0)
; #define PG8_LDB(dst, b, h) do { _Pragma("unroll") for (int n = 0; n < 2; ++n) _Pragma("unroll") for (int k = 0; k < 2; ++k) dst[n][k] = *(const PG8_LAS bf16x8*)(lds + PG8_SB(b, h) + boff + n * 2048 + k * 1024); } while (0)
; #define PG8_MMA(ai, bj, At, Bt) do { __builtin_amdgcn_s_setprio(1); _Pragma("unroll") for (int m = 0; m < 4; ++m) _Pragma("unroll") for (int n = 0; n < 2; ++n) _Pragma("unroll") for (int k = 0; k < 2; ++k) \
;         acc[ai][bj][m][n] = __builtin_amdgcn_mfma_f32_16x16x32_bf16(Bt[n][k], At[m][k], acc[ai][bj][m][n], 0, 0, 0); __builtin_amdgcn_s_setprio(0); } while (0)
; #define PG8_WAIT_V(n) asm volatile("s_waitcnt vmcnt(" #n ")" ::: "memory")
; #define PG8_WAIT_L(n) asm volatile("s_waitcnt lgkmcnt(" #n ")" ::: "memory")
; #define PG8_BAR __builtin_amdgcn_s_barrier()
; #define PG8_SCHED __builtin_amdgcn_sched_barrier(0)
; template <class Epi, class Sched, bool ALIGN_EPI = false, bool SP2 = false>
; __device__ __forceinline__ void gemm_phase(PG8_LAS unsigned char* lds, const Gemm g, const Sched& S, const Epi& E) {
;     ...
;             PG8_WAIT_V(8); PG8_WAIT_L(0); PG8_BAR; PG8_MMA(1, 0, At, B0); PG8_MMA(1, 1, At, B1); PG8_BAR; PG8_SCHED;
;             PG8_LDB(B0, 1, 0); PG8_LDB(B1, 1, 1); PG8_SCHED; PG8_LDA(At, 1, 0); PG8_STAGE(PG8_SA(0, 1), a2 + hstepA, voffA);
;             PG8_WAIT_V(8); PG8_WAIT_L(0); PG8_BAR; PG8_MMA(0, 0, At, B0); PG8_MMA(0, 1, At, B1); PG8_BAR; PG8_SCHED;
	s_setprio 1
	s_waitcnt lgkmcnt(0)
	v_mfma_f32_16x16x32_bf16 v[60:63], v[144:147], v[184:187], v[60:63]
	v_mfma_f32_16x16x32_bf16 v[56:59], v[156:159], v[184:187], v[56:59]
	v_mfma_f32_16x16x32_bf16 v[44:47], v[144:147], v[192:195], v[44:47]
	v_mfma_f32_16x16x32_bf16 v[40:43], v[156:159], v[192:195], v[40:43]
	v_mfma_f32_16x16x32_bf16 v[28:31], v[144:147], v[200:203], v[28:31]
	v_mfma_f32_16x16x32_bf16 v[24:27], v[156:159], v[200:203], v[24:27]
	v_mfma_f32_16x16x32_bf16 v[12:15], v[144:147], v[208:211], v[12:15]
	v_mfma_f32_16x16x32_bf16 v[8:11], v[156:159], v[208:211], v[8:11]
	v_mfma_f32_16x16x32_bf16 v[60:63], v[152:155], v[188:191], v[60:63]
	v_mfma_f32_16x16x32_bf16 v[56:59], v[160:163], v[188:191], v[56:59]
	v_mfma_f32_16x16x32_bf16 v[44:47], v[152:155], v[196:199], v[44:47]
	v_mfma_f32_16x16x32_bf16 v[40:43], v[160:163], v[196:199], v[40:43]
	v_mfma_f32_16x16x32_bf16 v[28:31], v[152:155], v[204:207], v[28:31]
	v_mfma_f32_16x16x32_bf16 v[24:27], v[160:163], v[204:207], v[24:27]
	v_mfma_f32_16x16x32_bf16 v[12:15], v[152:155], v[212:215], v[12:15]
	v_mfma_f32_16x16x32_bf16 v[8:11], v[160:163], v[212:215], v[8:11]
	v_mfma_f32_16x16x32_bf16 v[52:55], v[168:171], v[184:187], v[52:55]
	v_mfma_f32_16x16x32_bf16 v[48:51], v[176:179], v[184:187], v[48:51]
	v_mfma_f32_16x16x32_bf16 v[36:39], v[168:171], v[192:195], v[36:39]
	v_mfma_f32_16x16x32_bf16 v[32:35], v[176:179], v[192:195], v[32:35]
	v_mfma_f32_16x16x32_bf16 v[20:23], v[168:171], v[200:203], v[20:23]
	v_mfma_f32_16x16x32_bf16 v[16:19], v[176:179], v[200:203], v[16:19]
	v_mfma_f32_16x16x32_bf16 v[4:7], v[168:171], v[208:211], v[4:7]
	v_mfma_f32_16x16x32_bf16 v[0:3], v[176:179], v[208:211], v[0:3]
	v_mfma_f32_16x16x32_bf16 v[52:55], v[172:175], v[188:191], v[52:55]
	v_mfma_f32_16x16x32_bf16 v[48:51], v[180:183], v[188:191], v[48:51]
	v_mfma_f32_16x16x32_bf16 v[36:39], v[172:175], v[196:199], v[36:39]
	v_mfma_f32_16x16x32_bf16 v[32:35], v[180:183], v[196:199], v[32:35]
	v_mfma_f32_16x16x32_bf16 v[20:23], v[172:175], v[204:207], v[20:23]
	v_mfma_f32_16x16x32_bf16 v[16:19], v[180:183], v[204:207], v[16:19]
	v_mfma_f32_16x16x32_bf16 v[4:7], v[172:175], v[212:215], v[4:7]
	v_mfma_f32_16x16x32_bf16 v[0:3], v[180:183], v[212:215], v[0:3]
	s_setprio 0
	s_barrier
	s_add_i32 s59, 0, 0x18000
	s_add_i32 s60, 0, 0x1c000
	v_add_u32_e32 v160, s59, v148
	v_add_u32_e32 v166, s60, v148
	ds_read_b128 v[144:147], v160
	ds_read_b128 v[152:155], v160 offset:1024
	ds_read_b128 v[156:159], v160 offset:2048
	ds_read_b128 v[160:163], v160 offset:3072
	ds_read_b128 v[168:171], v166
	ds_read_b128 v[172:175], v166 offset:1024
	ds_read_b128 v[176:179], v166 offset:2048
	ds_read_b128 v[180:183], v166 offset:3072
	s_add_u32 s4, s36, 0x80000
	s_addc_u32 s5, s37, 0
	s_mov_b32 m0, s38
	v_lshl_add_u64 v[222:223], s[4:5], 0, v[128:129]
	ds_read_b128 v[184:187], v151 offset:32768
	ds_read_b128 v[188:191], v151 offset:33792
	ds_read_b128 v[192:195], v151 offset:34816
	ds_read_b128 v[196:199], v151 offset:35840
	ds_read_b128 v[200:203], v151 offset:36864
	ds_read_b128 v[204:207], v151 offset:37888
	ds_read_b128 v[208:211], v151 offset:38912
	ds_read_b128 v[212:215], v151 offset:39936
	global_load_lds_dwordx4 v[222:223], off
	v_lshl_add_u64 v[222:223], s[4:5], 0, v[132:133]
	s_mov_b32 m0, s39
	s_nop 0
	global_load_lds_dwordx4 v[222:223], off
	s_waitcnt vmcnt(8)
	s_waitcnt lgkmcnt(0)
	s_barrier
	s_setprio 1
	s_waitcnt lgkmcnt(0)
	v_mfma_f32_16x16x32_bf16 v[124:127], v[144:147], v[184:187], v[124:127]
	v_mfma_f32_16x16x32_bf16 v[120:123], v[156:159], v[184:187], v[120:123]
	v_mfma_f32_16x16x32_bf16 v[108:111], v[144:147], v[192:195], v[108:111]
	v_mfma_f32_16x16x32_bf16 v[104:107], v[156:159], v[192:195], v[104:107]
	v_mfma_f32_16x16x32_bf16 v[92:95], v[144:147], v[200:203], v[92:95]
	v_mfma_f32_16x16x32_bf16 v[88:91], v[156:159], v[200:203], v[88:91]
	v_mfma_f32_16x16x32_bf16 v[76:79], v[144:147], v[208:211], v[76:79]
	v_mfma_f32_16x16x32_bf16 v[72:75], v[156:159], v[208:211], v[72:75]
	v_mfma_f32_16x16x32_bf16 v[124:127], v[152:155], v[188:191], v[124:127]
	v_mfma_f32_16x16x32_bf16 v[120:123], v[160:163], v[188:191], v[120:123]
	v_mfma_f32_16x16x32_bf16 v[108:111], v[152:155], v[196:199], v[108:111]
	v_mfma_f32_16x16x32_bf16 v[104:107], v[160:163], v[196:199], v[104:107]
	v_mfma_f32_16x16x32_bf16 v[92:95], v[152:155], v[204:207], v[92:95]
	v_mfma_f32_16x16x32_bf16 v[88:91], v[160:163], v[204:207], v[88:91]
	v_mfma_f32_16x16x32_bf16 v[76:79], v[152:155], v[212:215], v[76:79]
	v_mfma_f32_16x16x32_bf16 v[72:75], v[160:163], v[212:215], v[72:75]
	v_mfma_f32_16x16x32_bf16 v[116:119], v[168:171], v[184:187], v[116:119]
	v_mfma_f32_16x16x32_bf16 v[112:115], v[176:179], v[184:187], v[112:115]
	v_mfma_f32_16x16x32_bf16 v[100:103], v[168:171], v[192:195], v[100:103]
	v_mfma_f32_16x16x32_bf16 v[96:99], v[176:179], v[192:195], v[96:99]
	v_mfma_f32_16x16x32_bf16 v[84:87], v[168:171], v[200:203], v[84:87]
	v_mfma_f32_16x16x32_bf16 v[80:83], v[176:179], v[200:203], v[80:83]
	v_mfma_f32_16x16x32_bf16 v[68:71], v[168:171], v[208:211], v[68:71]
	v_mfma_f32_16x16x32_bf16 v[64:67], v[176:179], v[208:211], v[64:67]
	v_mfma_f32_16x16x32_bf16 v[116:119], v[172:175], v[188:191], v[116:119]
	v_mfma_f32_16x16x32_bf16 v[112:115], v[180:183], v[188:191], v[112:115]
	v_mfma_f32_16x16x32_bf16 v[100:103], v[172:175], v[196:199], v[100:103]
	v_mfma_f32_16x16x32_bf16 v[96:99], v[180:183], v[196:199], v[96:99]
	v_mfma_f32_16x16x32_bf16 v[84:87], v[172:175], v[204:207], v[84:87]
	v_mfma_f32_16x16x32_bf16 v[80:83], v[180:183], v[204:207], v[80:83]
	v_mfma_f32_16x16x32_bf16 v[68:71], v[172:175], v[212:215], v[68:71]
	v_mfma_f32_16x16x32_bf16 v[64:67], v[180:183], v[212:215], v[64:67]
	s_setprio 0
	s_barrier
; #define PG8_STAGE(bufoff, gbase, voff) do { _Pragma("unroll") for (int _i = 0; _i < 2; ++_i) \
;         __builtin_amdgcn_global_load_lds((const unsigned*)((const char*)(gbase) + (voff)[_i]), (PG8_LAS unsigned*)(lds + (bufoff) + ldsw + _i * 8192), 16, 0, 0); } while (0)
; #define PG8_LDA(dst, b, h) do { _Pragma("unroll") for (int m = 0; m < 4; ++m) _Pragma("unroll") for (int k = 0; k < 2; ++k) dst[m][k] = *(const PG8_LAS bf16x8*)(lds + PG8_SA(b, h) + aoff + m * 2048 + k * 1024); } while (0)
; #define PG8_LDB(dst, b, h) do { _Pragma("unroll") for (int n = 0; n < 2; ++n) _Pragma("unroll") for (int k = 0; k < 2; ++k) dst[n][k] = *(const PG8_LAS bf16x8*)(lds + PG8_SB(b, h) + boff + n * 2048 + k * 1024); } while (0)
; #define PG8_MMA(ai, bj, At, Bt) do { __builtin_amdgcn_s_setprio(1); _Pragma("unroll") for (int m = 0; m < 4; ++m) _Pragma("unroll") for (int n = 0; n < 2; ++n) _Pragma("unroll") for (int k = 0; k < 2; ++k) \
;         acc[ai][bj][m][n] = __builtin_amdgcn_mfma_f32_16x16x32_bf16(Bt[n][k], At[m][k], acc[ai][bj][m][n], 0, 0, 0); __builtin_amdgcn_s_setprio(0); } while (0)
; #define PG8_WAIT_V(n) asm volatile("s_waitcnt vmcnt(" #n ")" ::: "memory")
; template <class Epi, class Sched, bool ALIGN_EPI = false, bool SP2 = false>
; __device__ __forceinline__ void gemm_phase(PG8_LAS unsigned char* lds, const Gemm g, const Sched& S, const Epi& E) {
;     ...
;             PG8_LDB(B0, 0, 0); PG8_LDB(B1, 0, 1); PG8_SCHED; PG8_LDA(At, 0, 0); PG8_STAGE(PG8_SA(1, 1), a1 + hstepA, voffA);
;             PG8_WAIT_V(8); PG8_WAIT_L(0); PG8_BAR; PG8_MMA(0, 0, At, B0); PG8_MMA(0, 1, At, B1); PG8_BAR; PG8_SCHED;
;             PG8_LDA(At, 0, 1); PG8_STAGE(PG8_SB(0, 0), b2, voffB); PG8_STAGE(PG8_SB(0, 1), b2 + hstepB, voffB); PG8_STAGE(PG8_SA(0, 0), a2, voffA);
;             PG8_WAIT_V(8); PG8_WAIT_L(0); PG8_BAR; PG8_MMA(1, 0, At, B0); PG8_MMA(1, 1, At, B1); PG8_BAR; PG8_SCHED;
;             PG8_LDB(B0, 1, 0); PG8_LDB(B1, 1, 1); PG8_SCHED; PG8_LDA(At, 1, 0); PG8_STAGE(PG8_SA(0, 1), a2 + hstepA, voffA);
;             PG8_WAIT_V(8); PG8_WAIT_L(0); PG8_BAR; PG8_MMA(0, 0, At, B0); PG8_MMA(0, 1, At, B1); PG8_BAR; PG8_SCHED;
;             PG8_LDA(At, 1, 1); PG8_STAGE(PG8_SB(1, 0), b3, voffB); PG8_STAGE(PG8_SB(1, 1), b3 + hstepB, voffB); PG8_STAGE(PG8_SA(1, 0), a3, voffA);
;             PG8_WAIT_V(8); PG8_WAIT_L(0); PG8_BAR; PG8_MMA(1, 0, At, B0); PG8_MMA(1, 1, At, B1); PG8_BAR; PG8_SCHED;
	s_add_i32 s4, s59, s47
	v_lshl_add_u64 v[164:165], v[164:165], 0, s[16:17]
	s_mov_b32 m0, s4
	ds_read_b128 v[184:187], v151 offset:49152
	ds_read_b128 v[188:191], v151 offset:50176
	ds_read_b128 v[192:195], v151 offset:51200
	ds_read_b128 v[196:199], v151 offset:52224
	ds_read_b128 v[200:203], v151 offset:53248
	ds_read_b128 v[204:207], v151 offset:54272
	ds_read_b128 v[208:211], v151 offset:55296
	ds_read_b128 v[212:215], v151 offset:56320
	global_load_lds_dwordx4 v[164:165], off
	s_add_i32 m0, s4, 0x2000
	s_add_u32 s4, s34, 0x80080
	v_lshl_add_u64 v[164:165], v[216:217], 0, s[16:17]
	s_addc_u32 s5, s35, 0
	s_add_i32 s34, s60, s47
	global_load_lds_dwordx4 v[164:165], off
	v_lshl_add_u64 v[164:165], s[4:5], 0, v[130:131]
	s_mov_b32 m0, s34
	s_nop 0
	global_load_lds_dwordx4 v[164:165], off
	v_lshl_add_u64 v[164:165], s[4:5], 0, v[134:135]
	s_add_i32 m0, s34, 0x2000
	s_nop 0
	global_load_lds_dwordx4 v[164:165], off
	v_lshl_add_u64 v[164:165], v[218:219], 0, s[16:17]
	s_mov_b32 m0, s40
	s_nop 0
	global_load_lds_dwordx4 v[164:165], off
	v_lshl_add_u64 v[164:165], v[220:221], 0, s[16:17]
	s_mov_b32 m0, s41
	s_nop 0
	global_load_lds_dwordx4 v[164:165], off
	s_waitcnt vmcnt(8)
	s_waitcnt lgkmcnt(0)
	s_barrier
	s_setprio 1
	s_waitcnt lgkmcnt(0)
	v_mfma_f32_16x16x32_bf16 v[60:63], v[144:147], v[184:187], v[60:63]
	v_mfma_f32_16x16x32_bf16 v[56:59], v[156:159], v[184:187], v[56:59]
	v_mfma_f32_16x16x32_bf16 v[44:47], v[144:147], v[192:195], v[44:47]
	v_mfma_f32_16x16x32_bf16 v[40:43], v[156:159], v[192:195], v[40:43]
	v_mfma_f32_16x16x32_bf16 v[28:31], v[144:147], v[200:203], v[28:31]
	v_mfma_f32_16x16x32_bf16 v[24:27], v[156:159], v[200:203], v[24:27]
	v_mfma_f32_16x16x32_bf16 v[12:15], v[144:147], v[208:211], v[12:15]
	v_mfma_f32_16x16x32_bf16 v[8:11], v[156:159], v[208:211], v[8:11]
	v_mfma_f32_16x16x32_bf16 v[60:63], v[152:155], v[188:191], v[60:63]
	v_mfma_f32_16x16x32_bf16 v[56:59], v[160:163], v[188:191], v[56:59]
	v_mfma_f32_16x16x32_bf16 v[44:47], v[152:155], v[196:199], v[44:47]
	v_mfma_f32_16x16x32_bf16 v[40:43], v[160:163], v[196:199], v[40:43]
	v_mfma_f32_16x16x32_bf16 v[28:31], v[152:155], v[204:207], v[28:31]
	v_mfma_f32_16x16x32_bf16 v[24:27], v[160:163], v[204:207], v[24:27]
	v_mfma_f32_16x16x32_bf16 v[12:15], v[152:155], v[212:215], v[12:15]
	v_mfma_f32_16x16x32_bf16 v[8:11], v[160:163], v[212:215], v[8:11]
	v_mfma_f32_16x16x32_bf16 v[52:55], v[168:171], v[184:187], v[52:55]
	v_mfma_f32_16x16x32_bf16 v[48:51], v[176:179], v[184:187], v[48:51]
	v_mfma_f32_16x16x32_bf16 v[36:39], v[168:171], v[192:195], v[36:39]
	v_mfma_f32_16x16x32_bf16 v[32:35], v[176:179], v[192:195], v[32:35]
	v_mfma_f32_16x16x32_bf16 v[20:23], v[168:171], v[200:203], v[20:23]
	v_mfma_f32_16x16x32_bf16 v[16:19], v[176:179], v[200:203], v[16:19]
	v_mfma_f32_16x16x32_bf16 v[4:7], v[168:171], v[208:211], v[4:7]
	v_mfma_f32_16x16x32_bf16 v[0:3], v[176:179], v[208:211], v[0:3]
	v_mfma_f32_16x16x32_bf16 v[52:55], v[172:175], v[188:191], v[52:55]
	v_mfma_f32_16x16x32_bf16 v[48:51], v[180:183], v[188:191], v[48:51]
	v_mfma_f32_16x16x32_bf16 v[36:39], v[172:175], v[196:199], v[36:39]
	v_mfma_f32_16x16x32_bf16 v[32:35], v[180:183], v[196:199], v[32:35]
	v_mfma_f32_16x16x32_bf16 v[20:23], v[172:175], v[204:207], v[20:23]
	v_mfma_f32_16x16x32_bf16 v[16:19], v[180:183], v[204:207], v[16:19]
	v_mfma_f32_16x16x32_bf16 v[4:7], v[172:175], v[212:215], v[4:7]
	v_mfma_f32_16x16x32_bf16 v[0:3], v[180:183], v[212:215], v[0:3]
	s_setprio 0
	s_barrier
	s_add_i32 s58, s58, 2
	s_add_u32 s30, s30, 0x100
	s_addc_u32 s31, s31, 0
	s_add_u32 s56, s56, 0x100
	s_addc_u32 s57, s57, 0
	s_cmp_gt_u32 s58, 29
	s_cbranch_scc0 .LBB0_1211
	s_and_b64 vcc, exec, s[48:49]
	s_cbranch_vccz .LBB0_1214
	s_barrier

; #define PG8_STAGE(bufoff, gbase, voff) do { _Pragma("unroll") for (int _i = 0; _i < 2; ++_i) \
;         __builtin_amdgcn_global_load_lds((const unsigned*)((const char*)(gbase) + (voff)[_i]), (PG8_LAS unsigned*)(lds + (bufoff) + ldsw + _i * 8192), 16, 0, 0); } while (0)
; #define PG8_LDA(dst, b, h) do { _Pragma("unroll") for (int m = 0; m < 4; ++m) _Pragma("unroll") for (int k = 0; k < 2; ++k) dst[m][k] = *(const PG8_LAS bf16x8*)(lds + PG8_SA(b, h) + aoff + m * 2048 + k * 1024); } while (0)
; #define PG8_LDB(dst, b, h) do { _Pragma("unroll") for (int n = 0; n < 2; ++n) _Pragma("unroll") for (int k = 0; k < 2; ++k) dst[n][k] = *(const PG8_LAS bf16x8*)(lds + PG8_SB(b, h) + boff + n * 2048 + k * 1024); } while (0)
; #define PG8_MMA(ai, bj, At, Bt) do { __builtin_amdgcn_s_setprio(1); _Pragma("unroll") for (int m = 0; m < 4; ++m) _Pragma("unroll") for (int n = 0; n < 2; ++n) _Pragma("unroll") for (int k = 0; k < 2; ++k) \
;         acc[ai][bj][m][n] = __builtin_amdgcn_mfma_f32_16x16x32_bf16(Bt[n][k], At[m][k], acc[ai][bj][m][n], 0, 0, 0); __builtin_amdgcn_s_setprio(0); } while (0)
; #define PG8_WAIT_V(n) asm volatile("s_waitcnt vmcnt(" #n ")" ::: "memory")
; #define PG8_WAIT_L(n) asm volatile("s_waitcnt lgkmcnt(" #n ")" ::: "memory")
; #define PG8_BAR __builtin_amdgcn_s_barrier()
; #define PG8_SCHED __builtin_amdgcn_sched_barrier(0)
; template <class Epi, class Sched, bool ALIGN_EPI = false, bool SP2 = false>
; __device__ __forceinline__ void gemm_phase(PG8_LAS unsigned char* lds, const Gemm g, const Sched& S, const Epi& E) {
;     ...
;             const char* a1 = cA + (size_t)(t + 1) * kstep;
;             const char* a2 = last ? nA : cA + (size_t)(t + 2) * kstep; const char* b2 = last ? nB : cB + (size_t)(t + 2) * kstep;
;             const char* a3 = a2 + kstep; const char* b3 = b2 + kstep;
;             if (last && has_next) S.a_ready(nxt);
;             if constexpr (SP2) {
;             PG8_LDB(B0, 0, 0); PG8_LDB(B1, 0, 1); PG8_SCHED; PG8_LDA(At, 0, 0); PG8_STAGE(PG8_SA(1, 1), a1 + hstepA, voffA);
;             PG8_WAIT_V(8); PG8_WAIT_L(0); PG8_BAR; PG8_MMA(0, 0, At, B0); PG8_MMA(0, 1, At, B1); PG8_BAR; PG8_SCHED;
;             PG8_LDA(At, 0, 1); PG8_STAGE(PG8_SB(0, 0), b2, voffB); PG8_STAGE(PG8_SB(0, 1), b2 + hstepB, voffB); PG8_STAGE(PG8_SA(0, 0), a2, voffA);
.LBB0_1287:
	ds_read_b128 v[144:147], v149
	ds_read_b128 v[154:157], v149 offset:1024
	ds_read_b128 v[158:161], v149 offset:2048
	ds_read_b128 v[162:165], v149 offset:3072
	ds_read_b128 v[168:171], v150
	ds_read_b128 v[172:175], v150 offset:1024
	ds_read_b128 v[176:179], v150 offset:2048
	ds_read_b128 v[180:183], v150 offset:3072
	s_add_u32 s4, s28, 0xfff80080
	s_addc_u32 s5, s29, -1
	s_cmp_eq_u32 s58, 28
	s_cselect_b32 s35, s19, s5
	s_cselect_b32 s34, s54, s4
	s_cselect_b32 s31, s17, s57
	s_cselect_b32 s30, s55, s56
	v_lshl_add_u64 v[216:217], s[28:29], 0, v[136:137]
	s_add_i32 m0, s27, 0xc000
	ds_read_b128 v[184:187], v151
	ds_read_b128 v[188:191], v151 offset:1024
	ds_read_b128 v[192:195], v151 offset:2048
	ds_read_b128 v[196:199], v151 offset:3072
	ds_read_b128 v[200:203], v151 offset:4096
	ds_read_b128 v[204:207], v151 offset:5120
	ds_read_b128 v[208:211], v151 offset:6144
	ds_read_b128 v[212:215], v151 offset:7168
	global_load_lds_dwordx4 v[216:217], off
	v_lshl_add_u64 v[216:217], s[28:29], 0, v[138:139]
	s_add_i32 m0, s27, 0xe000
	s_nop 0
	global_load_lds_dwordx4 v[216:217], off
	s_waitcnt vmcnt(8)
	s_waitcnt lgkmcnt(0)
	s_barrier
	s_setprio 1
	s_waitcnt lgkmcnt(0)
	v_mfma_f32_16x16x32_bf16 v[116:119], v[144:147], v[184:187], v[116:119]
	v_mfma_f32_16x16x32_bf16 v[112:115], v[158:161], v[184:187], v[112:115]
	v_mfma_f32_16x16x32_bf16 v[100:103], v[144:147], v[192:195], v[100:103]
	v_mfma_f32_16x16x32_bf16 v[96:99], v[158:161], v[192:195], v[96:99]
	v_mfma_f32_16x16x32_bf16 v[84:87], v[144:147], v[200:203], v[84:87]
	v_mfma_f32_16x16x32_bf16 v[80:83], v[158:161], v[200:203], v[80:83]
	v_mfma_f32_16x16x32_bf16 v[68:71], v[144:147], v[208:211], v[68:71]
	v_mfma_f32_16x16x32_bf16 v[64:67], v[158:161], v[208:211], v[64:67]
	v_mfma_f32_16x16x32_bf16 v[116:119], v[154:157], v[188:191], v[116:119]
	v_mfma_f32_16x16x32_bf16 v[112:115], v[162:165], v[188:191], v[112:115]
	v_mfma_f32_16x16x32_bf16 v[100:103], v[154:157], v[196:199], v[100:103]
	v_mfma_f32_16x16x32_bf16 v[96:99], v[162:165], v[196:199], v[96:99]
	v_mfma_f32_16x16x32_bf16 v[84:87], v[154:157], v[204:207], v[84:87]
	v_mfma_f32_16x16x32_bf16 v[80:83], v[162:165], v[204:207], v[80:83]
	v_mfma_f32_16x16x32_bf16 v[68:71], v[154:157], v[212:215], v[68:71]
	v_mfma_f32_16x16x32_bf16 v[64:67], v[162:165], v[212:215], v[64:67]
	v_mfma_f32_16x16x32_bf16 v[124:127], v[168:171], v[184:187], v[124:127]
	v_mfma_f32_16x16x32_bf16 v[120:123], v[176:179], v[184:187], v[120:123]
	v_mfma_f32_16x16x32_bf16 v[108:111], v[168:171], v[192:195], v[108:111]
	v_mfma_f32_16x16x32_bf16 v[104:107], v[176:179], v[192:195], v[104:107]
	v_mfma_f32_16x16x32_bf16 v[92:95], v[168:171], v[200:203], v[92:95]
	v_mfma_f32_16x16x32_bf16 v[88:91], v[176:179], v[200:203], v[88:91]
	v_mfma_f32_16x16x32_bf16 v[76:79], v[168:171], v[208:211], v[76:79]
	v_mfma_f32_16x16x32_bf16 v[72:75], v[176:179], v[208:211], v[72:75]
	v_mfma_f32_16x16x32_bf16 v[124:127], v[172:175], v[188:191], v[124:127]
	v_mfma_f32_16x16x32_bf16 v[120:123], v[180:183], v[188:191], v[120:123]
	v_mfma_f32_16x16x32_bf16 v[108:111], v[172:175], v[196:199], v[108:111]
	v_mfma_f32_16x16x32_bf16 v[104:107], v[180:183], v[196:199], v[104:107]
	v_mfma_f32_16x16x32_bf16 v[92:95], v[172:175], v[204:207], v[92:95]
	v_mfma_f32_16x16x32_bf16 v[88:91], v[180:183], v[204:207], v[88:91]
	v_mfma_f32_16x16x32_bf16 v[76:79], v[172:175], v[212:215], v[76:79]
	v_mfma_f32_16x16x32_bf16 v[72:75], v[180:183], v[212:215], v[72:75]
	s_setprio 0
	s_barrier
	s_add_i32 s4, s41, s47
	v_lshl_add_u64 v[216:217], s[30:31], 0, v[132:133]
	s_mov_b32 m0, s4
	ds_read_b128 v[184:187], v151 offset:16384
	ds_read_b128 v[188:191], v151 offset:17408
	ds_read_b128 v[192:195], v151 offset:18432
	ds_read_b128 v[196:199], v151 offset:19456
	ds_read_b128 v[200:203], v151 offset:20480
	ds_read_b128 v[204:207], v151 offset:21504
	ds_read_b128 v[208:211], v151 offset:22528
	ds_read_b128 v[212:215], v151 offset:23552
	global_load_lds_dwordx4 v[216:217], off
	s_add_i32 m0, s4, 0x2000
	s_add_u32 s4, s30, 0x80000
	v_lshl_add_u64 v[218:219], s[30:31], 0, v[128:129]
	s_addc_u32 s5, s31, 0
	s_add_i32 s59, s44, s47
	global_load_lds_dwordx4 v[218:219], off
	v_lshl_add_u64 v[220:221], s[4:5], 0, v[132:133]
	s_mov_b32 m0, s59
	v_lshl_add_u64 v[222:223], s[34:35], 0, v[130:131]
	global_load_lds_dwordx4 v[220:221], off
	v_lshl_add_u64 v[220:221], s[4:5], 0, v[128:129]
	s_add_i32 m0, s59, 0x2000
	s_nop 0
	global_load_lds_dwordx4 v[220:221], off
	v_lshl_add_u64 v[220:221], s[34:35], 0, v[134:135]
	s_mov_b32 m0, s27
	s_nop 0
	global_load_lds_dwordx4 v[220:221], off
	s_mov_b32 m0, s33
	s_nop 0
	global_load_lds_dwordx4 v[222:223], off
	s_waitcnt vmcnt(8)
	s_waitcnt lgkmcnt(0)
	s_barrier
; #define PG8_STAGE(bufoff, gbase, voff) do { _Pragma("unroll") for (int _i = 0; _i < 2; ++_i) \
;         __builtin_amdgcn_global_load_lds((const unsigned*)((const char*)(gbase) + (voff)[_i]), (PG8_LAS unsigned*)(lds + (bufoff) + ldsw + _i * 8192), 16, 0, 0); } while (0)
; #define PG8_LDA(dst, b, h) do { _Pragma("unroll") for (int m = 0; m < 4; ++m) _Pragma("unroll") for (int k = 0; k < 2; ++k) dst[m][k] = *(const PG8_LAS bf16x8*)(lds + PG8_SA(b, h) + aoff + m * 2048 + k * 1024); } while (0)
; #define PG8_LDB(dst, b, h) do { _Pragma("unroll") for (int n = 0; n < 2; ++n) _Pragma("unroll") for (int k = 0; k < 2; ++k) dst[n][k] = *(const PG8_LAS bf16x8*)(lds + PG8_SB(b, h) + boff + n * 2048 + k * 1024); } while (0)
; #define PG8_MMA(ai, bj, At, Bt) do { __builtin_amdgcn_s_setprio(1); _Pragma("unroll") for (int m = 0; m < 4; ++m) _Pragma("unroll") for (int n = 0; n < 2; ++n) _Pragma("unroll") for (int k = 0; k < 2; ++k) \
;         acc[ai][bj][m][n] = __builtin_amdgcn_mfma_f32_16x16x32_bf16(Bt[n][k], At[m][k], acc[ai][bj][m][n], 0, 0, 0); __builtin_amdgcn_s_setprio(0); } while (0)
; #define PG8_WAIT_V(n) asm volatile("s_waitcnt vmcnt(" #n ")" ::: "memory")
; #define PG8_WAIT_L(n) asm volatile("s_waitcnt lgkmcnt(" #n ")" ::: "memory")
; #define PG8_BAR __builtin_amdgcn_s_barrier()
; #define PG8_SCHED __builtin_amdgcn_sched_barrier(0)
; template <class Epi, class Sched, bool ALIGN_EPI = false, bool SP2 = false>
; __device__ __forceinline__ void gemm_phase(PG8_LAS unsigned char* lds, const Gemm g, const Sched& S, const Epi& E) {
;     ...
;             PG8_WAIT_V(8); PG8_WAIT_L(0); PG8_BAR; PG8_MMA(1, 0, At, B0); PG8_MMA(1, 1, At, B1); PG8_BAR; PG8_SCHED;
;             PG8_LDB(B0, 1, 0); PG8_LDB(B1, 1, 1); PG8_SCHED; PG8_LDA(At, 1, 0); PG8_STAGE(PG8_SA(0, 1), a2 + hstepA, voffA);
;             PG8_WAIT_V(8); PG8_WAIT_L(0); PG8_BAR; PG8_MMA(0, 0, At, B0); PG8_MMA(0, 1, At, B1); PG8_BAR; PG8_SCHED;
	s_setprio 1
	s_waitcnt lgkmcnt(0)
	v_mfma_f32_16x16x32_bf16 v[52:55], v[144:147], v[184:187], v[52:55]
	v_mfma_f32_16x16x32_bf16 v[48:51], v[158:161], v[184:187], v[48:51]
	v_mfma_f32_16x16x32_bf16 v[36:39], v[144:147], v[192:195], v[36:39]
	v_mfma_f32_16x16x32_bf16 v[32:35], v[158:161], v[192:195], v[32:35]
	v_mfma_f32_16x16x32_bf16 v[20:23], v[144:147], v[200:203], v[20:23]
	v_mfma_f32_16x16x32_bf16 v[16:19], v[158:161], v[200:203], v[16:19]
	v_mfma_f32_16x16x32_bf16 v[8:11], v[144:147], v[208:211], v[8:11]
	v_mfma_f32_16x16x32_bf16 v[4:7], v[158:161], v[208:211], v[4:7]
	v_mfma_f32_16x16x32_bf16 v[52:55], v[154:157], v[188:191], v[52:55]
	v_mfma_f32_16x16x32_bf16 v[48:51], v[162:165], v[188:191], v[48:51]
	v_mfma_f32_16x16x32_bf16 v[36:39], v[154:157], v[196:199], v[36:39]
	v_mfma_f32_16x16x32_bf16 v[32:35], v[162:165], v[196:199], v[32:35]
	v_mfma_f32_16x16x32_bf16 v[20:23], v[154:157], v[204:207], v[20:23]
	v_mfma_f32_16x16x32_bf16 v[16:19], v[162:165], v[204:207], v[16:19]
	v_mfma_f32_16x16x32_bf16 v[8:11], v[154:157], v[212:215], v[8:11]
	v_mfma_f32_16x16x32_bf16 v[4:7], v[162:165], v[212:215], v[4:7]
	v_mfma_f32_16x16x32_bf16 v[60:63], v[168:171], v[184:187], v[60:63]
	v_mfma_f32_16x16x32_bf16 v[56:59], v[176:179], v[184:187], v[56:59]
	v_mfma_f32_16x16x32_bf16 v[44:47], v[168:171], v[192:195], v[44:47]
	v_mfma_f32_16x16x32_bf16 v[40:43], v[176:179], v[192:195], v[40:43]
	v_mfma_f32_16x16x32_bf16 v[28:31], v[168:171], v[200:203], v[28:31]
	v_mfma_f32_16x16x32_bf16 v[24:27], v[176:179], v[200:203], v[24:27]
	v_mfma_f32_16x16x32_bf16 v[12:15], v[168:171], v[208:211], v[12:15]
	v_mfma_f32_16x16x32_bf16 v[0:3], v[176:179], v[208:211], v[0:3]
	v_mfma_f32_16x16x32_bf16 v[60:63], v[172:175], v[188:191], v[60:63]
	v_mfma_f32_16x16x32_bf16 v[56:59], v[180:183], v[188:191], v[56:59]
	v_mfma_f32_16x16x32_bf16 v[44:47], v[172:175], v[196:199], v[44:47]
	v_mfma_f32_16x16x32_bf16 v[40:43], v[180:183], v[196:199], v[40:43]
	v_mfma_f32_16x16x32_bf16 v[28:31], v[172:175], v[204:207], v[28:31]
	v_mfma_f32_16x16x32_bf16 v[24:27], v[180:183], v[204:207], v[24:27]
	v_mfma_f32_16x16x32_bf16 v[12:15], v[172:175], v[212:215], v[12:15]
	v_mfma_f32_16x16x32_bf16 v[0:3], v[180:183], v[212:215], v[0:3]
	s_setprio 0
	s_barrier
	s_add_i32 s59, 0, 0x18000
	v_add_u32_e32 v153, s59, v148
	s_add_i32 s60, 0, 0x1c000
	ds_read_b128 v[144:147], v153
	ds_read_b128 v[154:157], v153 offset:1024
	ds_read_b128 v[158:161], v153 offset:2048
	ds_read_b128 v[162:165], v153 offset:3072
	v_add_u32_e32 v153, s60, v148
	ds_read_b128 v[168:171], v153
	ds_read_b128 v[172:175], v153 offset:1024
	ds_read_b128 v[176:179], v153 offset:2048
	ds_read_b128 v[180:183], v153 offset:3072
	s_add_u32 s4, s34, 0x80000
	s_addc_u32 s5, s35, 0
	s_mov_b32 m0, s36
	v_lshl_add_u64 v[224:225], s[4:5], 0, v[134:135]
	ds_read_b128 v[184:187], v151 offset:32768
	ds_read_b128 v[188:191], v151 offset:33792
	ds_read_b128 v[192:195], v151 offset:34816
	ds_read_b128 v[196:199], v151 offset:35840
	ds_read_b128 v[200:203], v151 offset:36864
	ds_read_b128 v[204:207], v151 offset:37888
	ds_read_b128 v[208:211], v151 offset:38912
	ds_read_b128 v[212:215], v151 offset:39936
	global_load_lds_dwordx4 v[224:225], off
	v_lshl_add_u64 v[224:225], s[4:5], 0, v[130:131]
	s_mov_b32 m0, s37
	s_nop 0
	global_load_lds_dwordx4 v[224:225], off
	s_waitcnt vmcnt(8)
	s_waitcnt lgkmcnt(0)
	s_barrier
	s_setprio 1
	s_waitcnt lgkmcnt(0)
	v_mfma_f32_16x16x32_bf16 v[116:119], v[144:147], v[184:187], v[116:119]
	v_mfma_f32_16x16x32_bf16 v[112:115], v[158:161], v[184:187], v[112:115]
	v_mfma_f32_16x16x32_bf16 v[100:103], v[144:147], v[192:195], v[100:103]
	v_mfma_f32_16x16x32_bf16 v[96:99], v[158:161], v[192:195], v[96:99]
	v_mfma_f32_16x16x32_bf16 v[84:87], v[144:147], v[200:203], v[84:87]
	v_mfma_f32_16x16x32_bf16 v[80:83], v[158:161], v[200:203], v[80:83]
	v_mfma_f32_16x16x32_bf16 v[68:71], v[144:147], v[208:211], v[68:71]
	v_mfma_f32_16x16x32_bf16 v[64:67], v[158:161], v[208:211], v[64:67]
	v_mfma_f32_16x16x32_bf16 v[116:119], v[154:157], v[188:191], v[116:119]
	v_mfma_f32_16x16x32_bf16 v[112:115], v[162:165], v[188:191], v[112:115]
	v_mfma_f32_16x16x32_bf16 v[100:103], v[154:157], v[196:199], v[100:103]
	v_mfma_f32_16x16x32_bf16 v[96:99], v[162:165], v[196:199], v[96:99]
	v_mfma_f32_16x16x32_bf16 v[84:87], v[154:157], v[204:207], v[84:87]
	v_mfma_f32_16x16x32_bf16 v[80:83], v[162:165], v[204:207], v[80:83]
	v_mfma_f32_16x16x32_bf16 v[68:71], v[154:157], v[212:215], v[68:71]
	v_mfma_f32_16x16x32_bf16 v[64:67], v[162:165], v[212:215], v[64:67]
	v_mfma_f32_16x16x32_bf16 v[124:127], v[168:171], v[184:187], v[124:127]
	v_mfma_f32_16x16x32_bf16 v[120:123], v[176:179], v[184:187], v[120:123]
	v_mfma_f32_16x16x32_bf16 v[108:111], v[168:171], v[192:195], v[108:111]
	v_mfma_f32_16x16x32_bf16 v[104:107], v[176:179], v[192:195], v[104:107]
	v_mfma_f32_16x16x32_bf16 v[92:95], v[168:171], v[200:203], v[92:95]
	v_mfma_f32_16x16x32_bf16 v[88:91], v[176:179], v[200:203], v[88:91]
	v_mfma_f32_16x16x32_bf16 v[76:79], v[168:171], v[208:211], v[76:79]
	v_mfma_f32_16x16x32_bf16 v[72:75], v[176:179], v[208:211], v[72:75]
	v_mfma_f32_16x16x32_bf16 v[124:127], v[172:175], v[188:191], v[124:127]
	v_mfma_f32_16x16x32_bf16 v[120:123], v[180:183], v[188:191], v[120:123]
	v_mfma_f32_16x16x32_bf16 v[108:111], v[172:175], v[196:199], v[108:111]
	v_mfma_f32_16x16x32_bf16 v[104:107], v[180:183], v[196:199], v[104:107]
	v_mfma_f32_16x16x32_bf16 v[92:95], v[172:175], v[204:207], v[92:95]
	v_mfma_f32_16x16x32_bf16 v[88:91], v[180:183], v[204:207], v[88:91]
	v_mfma_f32_16x16x32_bf16 v[76:79], v[172:175], v[212:215], v[76:79]
	v_mfma_f32_16x16x32_bf16 v[72:75], v[180:183], v[212:215], v[72:75]
	s_setprio 0
	s_barrier
; #define PG8_STAGE(bufoff, gbase, voff) do { _Pragma("unroll") for (int _i = 0; _i < 2; ++_i) \
;         __builtin_amdgcn_global_load_lds((const unsigned*)((const char*)(gbase) + (voff)[_i]), (PG8_LAS unsigned*)(lds + (bufoff) + ldsw + _i * 8192), 16, 0, 0); } while (0)
; #define PG8_LDA(dst, b, h) do { _Pragma("unroll") for (int m = 0; m < 4; ++m) _Pragma("unroll") for (int k = 0; k < 2; ++k) dst[m][k] = *(const PG8_LAS bf16x8*)(lds + PG8_SA(b, h) + aoff + m * 2048 + k * 1024); } while (0)
; #define PG8_LDB(dst, b, h) do { _Pragma("unroll") for (int n = 0; n < 2; ++n) _Pragma("unroll") for (int k = 0; k < 2; ++k) dst[n][k] = *(const PG8_LAS bf16x8*)(lds + PG8_SB(b, h) + boff + n * 2048 + k * 1024); } while (0)
; #define PG8_MMA(ai, bj, At, Bt) do { __builtin_amdgcn_s_setprio(1); _Pragma("unroll") for (int m = 0; m < 4; ++m) _Pragma("unroll") for (int n = 0; n < 2; ++n) _Pragma("unroll") for (int k = 0; k < 2; ++k) \
;         acc[ai][bj][m][n] = __builtin_amdgcn_mfma_f32_16x16x32_bf16(Bt[n][k], At[m][k], acc[ai][bj][m][n], 0, 0, 0); __builtin_amdgcn_s_setprio(0); } while (0)
; #define PG8_WAIT_V(n) asm volatile("s_waitcnt vmcnt(" #n ")" ::: "memory")
; template <class Epi, class Sched, bool ALIGN_EPI = false, bool SP2 = false>
; __device__ __forceinline__ void gemm_phase(PG8_LAS unsigned char* lds, const Gemm g, const Sched& S, const Epi& E) {
;     ...
;             PG8_LDB(B0, 0, 0); PG8_LDB(B1, 0, 1); PG8_SCHED; PG8_LDA(At, 0, 0); PG8_STAGE(PG8_SA(1, 1), a1 + hstepA, voffA);
;             PG8_WAIT_V(8); PG8_WAIT_L(0); PG8_BAR; PG8_MMA(0, 0, At, B0); PG8_MMA(0, 1, At, B1); PG8_BAR; PG8_SCHED;
;             PG8_LDA(At, 0, 1); PG8_STAGE(PG8_SB(0, 0), b2, voffB); PG8_STAGE(PG8_SB(0, 1), b2 + hstepB, voffB); PG8_STAGE(PG8_SA(0, 0), a2, voffA);
;             PG8_WAIT_V(8); PG8_WAIT_L(0); PG8_BAR; PG8_MMA(1, 0, At, B0); PG8_MMA(1, 1, At, B1); PG8_BAR; PG8_SCHED;
;             PG8_LDB(B0, 1, 0); PG8_LDB(B1, 1, 1); PG8_SCHED; PG8_LDA(At, 1, 0); PG8_STAGE(PG8_SA(0, 1), a2 + hstepA, voffA);
;             PG8_WAIT_V(8); PG8_WAIT_L(0); PG8_BAR; PG8_MMA(0, 0, At, B0); PG8_MMA(0, 1, At, B1); PG8_BAR; PG8_SCHED;
;             PG8_LDA(At, 1, 1); PG8_STAGE(PG8_SB(1, 0), b3, voffB); PG8_STAGE(PG8_SB(1, 1), b3 + hstepB, voffB); PG8_STAGE(PG8_SA(1, 0), a3, voffA);
;             PG8_WAIT_V(8); PG8_WAIT_L(0); PG8_BAR; PG8_MMA(1, 0, At, B0); PG8_MMA(1, 1, At, B1); PG8_BAR; PG8_SCHED;
	s_add_i32 s4, s59, s47
	v_lshl_add_u64 v[216:217], v[216:217], 0, s[14:15]
	s_mov_b32 m0, s4
	ds_read_b128 v[184:187], v151 offset:49152
	ds_read_b128 v[188:191], v151 offset:50176
	ds_read_b128 v[192:195], v151 offset:51200
	ds_read_b128 v[196:199], v151 offset:52224
	ds_read_b128 v[200:203], v151 offset:53248
	ds_read_b128 v[204:207], v151 offset:54272
	ds_read_b128 v[208:211], v151 offset:55296
	ds_read_b128 v[212:215], v151 offset:56320
	global_load_lds_dwordx4 v[216:217], off
	s_add_i32 m0, s4, 0x2000
	s_add_u32 s4, s30, 0x80080
	v_lshl_add_u64 v[216:217], v[218:219], 0, s[14:15]
	s_addc_u32 s5, s31, 0
	s_add_i32 s30, s60, s47
	global_load_lds_dwordx4 v[216:217], off
	v_lshl_add_u64 v[216:217], s[4:5], 0, v[132:133]
	s_mov_b32 m0, s30
	s_nop 0
	global_load_lds_dwordx4 v[216:217], off
	v_lshl_add_u64 v[216:217], s[4:5], 0, v[128:129]
	s_add_i32 m0, s30, 0x2000
	s_nop 0
	global_load_lds_dwordx4 v[216:217], off
	v_lshl_add_u64 v[216:217], v[220:221], 0, s[14:15]
	s_mov_b32 m0, s39
	s_nop 0
	global_load_lds_dwordx4 v[216:217], off
	v_lshl_add_u64 v[216:217], v[222:223], 0, s[14:15]
	s_mov_b32 m0, s40
	s_nop 0
	global_load_lds_dwordx4 v[216:217], off
	s_waitcnt vmcnt(8)
	s_waitcnt lgkmcnt(0)
	s_barrier
	s_setprio 1
	s_waitcnt lgkmcnt(0)
	v_mfma_f32_16x16x32_bf16 v[52:55], v[144:147], v[184:187], v[52:55]
	v_mfma_f32_16x16x32_bf16 v[48:51], v[158:161], v[184:187], v[48:51]
	v_mfma_f32_16x16x32_bf16 v[36:39], v[144:147], v[192:195], v[36:39]
	v_mfma_f32_16x16x32_bf16 v[32:35], v[158:161], v[192:195], v[32:35]
	v_mfma_f32_16x16x32_bf16 v[20:23], v[144:147], v[200:203], v[20:23]
	v_mfma_f32_16x16x32_bf16 v[16:19], v[158:161], v[200:203], v[16:19]
	v_mfma_f32_16x16x32_bf16 v[8:11], v[144:147], v[208:211], v[8:11]
	v_mfma_f32_16x16x32_bf16 v[4:7], v[158:161], v[208:211], v[4:7]
	v_mfma_f32_16x16x32_bf16 v[52:55], v[154:157], v[188:191], v[52:55]
	v_mfma_f32_16x16x32_bf16 v[48:51], v[162:165], v[188:191], v[48:51]
	v_mfma_f32_16x16x32_bf16 v[36:39], v[154:157], v[196:199], v[36:39]
	v_mfma_f32_16x16x32_bf16 v[32:35], v[162:165], v[196:199], v[32:35]
	v_mfma_f32_16x16x32_bf16 v[20:23], v[154:157], v[204:207], v[20:23]
	v_mfma_f32_16x16x32_bf16 v[16:19], v[162:165], v[204:207], v[16:19]
	v_mfma_f32_16x16x32_bf16 v[8:11], v[154:157], v[212:215], v[8:11]
	v_mfma_f32_16x16x32_bf16 v[4:7], v[162:165], v[212:215], v[4:7]
	v_mfma_f32_16x16x32_bf16 v[60:63], v[168:171], v[184:187], v[60:63]
	v_mfma_f32_16x16x32_bf16 v[56:59], v[176:179], v[184:187], v[56:59]
	v_mfma_f32_16x16x32_bf16 v[44:47], v[168:171], v[192:195], v[44:47]
	v_mfma_f32_16x16x32_bf16 v[40:43], v[176:179], v[192:195], v[40:43]
	v_mfma_f32_16x16x32_bf16 v[28:31], v[168:171], v[200:203], v[28:31]
	v_mfma_f32_16x16x32_bf16 v[24:27], v[176:179], v[200:203], v[24:27]
	v_mfma_f32_16x16x32_bf16 v[12:15], v[168:171], v[208:211], v[12:15]
	v_mfma_f32_16x16x32_bf16 v[0:3], v[176:179], v[208:211], v[0:3]
	v_mfma_f32_16x16x32_bf16 v[60:63], v[172:175], v[188:191], v[60:63]
	v_mfma_f32_16x16x32_bf16 v[56:59], v[180:183], v[188:191], v[56:59]
	v_mfma_f32_16x16x32_bf16 v[44:47], v[172:175], v[196:199], v[44:47]
	v_mfma_f32_16x16x32_bf16 v[40:43], v[180:183], v[196:199], v[40:43]
	v_mfma_f32_16x16x32_bf16 v[28:31], v[172:175], v[204:207], v[28:31]
	v_mfma_f32_16x16x32_bf16 v[24:27], v[180:183], v[204:207], v[24:27]
	v_mfma_f32_16x16x32_bf16 v[12:15], v[172:175], v[212:215], v[12:15]
	v_mfma_f32_16x16x32_bf16 v[0:3], v[180:183], v[212:215], v[0:3]
	s_setprio 0
	s_barrier
	s_add_i32 s58, s58, 2
	s_add_u32 s28, s28, 0x100
	s_addc_u32 s29, s29, 0
	s_add_u32 s56, s56, 0x100
	s_addc_u32 s57, s57, 0
	s_cmp_gt_u32 s58, 29
	s_cbranch_scc0 .LBB0_1287
	s_and_b64 vcc, exec, s[48:49]
	s_cbranch_vccz .LBB0_1290
	s_barrier

; #define PG8_STAGE(bufoff, gbase, voff) do { _Pragma("unroll") for (int _i = 0; _i < 2; ++_i) \
;         __builtin_amdgcn_global_load_lds((const unsigned*)((const char*)(gbase) + (voff)[_i]), (PG8_LAS unsigned*)(lds + (bufoff) + ldsw + _i * 8192), 16, 0, 0); } while (0)
; #define PG8_LDA(dst, b, h) do { _Pragma("unroll") for (int m = 0; m < 4; ++m) _Pragma("unroll") for (int k = 0; k < 2; ++k) dst[m][k] = *(const PG8_LAS bf16x8*)(lds + PG8_SA(b, h) + aoff + m * 2048 + k * 1024); } while (0)
; #define PG8_LDB(dst, b, h) do { _Pragma("unroll") for (int n = 0; n < 2; ++n) _Pragma("unroll") for (int k = 0; k < 2; ++k) dst[n][k] = *(const PG8_LAS bf16x8*)(lds + PG8_SB(b, h) + boff + n * 2048 + k * 1024); } while (0)
; #define PG8_MMA(ai, bj, At, Bt) do { __builtin_amdgcn_s_setprio(1); _Pragma("unroll") for (int m = 0; m < 4; ++m) _Pragma("unroll") for (int n = 0; n < 2; ++n) _Pragma("unroll") for (int k = 0; k < 2; ++k) \
;         acc[ai][bj][m][n] = __builtin_amdgcn_mfma_f32_16x16x32_bf16(Bt[n][k], At[m][k], acc[ai][bj][m][n], 0, 0, 0); __builtin_amdgcn_s_setprio(0); } while (0)
; #define PG8_WAIT_V(n) asm volatile("s_waitcnt vmcnt(" #n ")" ::: "memory")
; #define PG8_WAIT_L(n) asm volatile("s_waitcnt lgkmcnt(" #n ")" ::: "memory")
; #define PG8_BAR __builtin_amdgcn_s_barrier()
; #define PG8_SCHED __builtin_amdgcn_sched_barrier(0)
; template <class Epi, class Sched, bool ALIGN_EPI = false, bool SP2 = false>
; __device__ __forceinline__ void gemm_phase(PG8_LAS unsigned char* lds, const Gemm g, const Sched& S, const Epi& E) {
;     ...
;             const char* a1 = cA + (size_t)(t + 1) * kstep;
;             const char* a2 = last ? nA : cA + (size_t)(t + 2) * kstep; const char* b2 = last ? nB : cB + (size_t)(t + 2) * kstep;
;             const char* a3 = a2 + kstep; const char* b3 = b2 + kstep;
;             if (last && has_next) S.a_ready(nxt);
;             if constexpr (SP2) {
;             PG8_LDB(B0, 0, 0); PG8_LDB(B1, 0, 1); PG8_SCHED; PG8_LDA(At, 0, 0); PG8_STAGE(PG8_SA(1, 1), a1 + hstepA, voffA);
;             PG8_WAIT_V(8); PG8_WAIT_L(0); PG8_BAR; PG8_MMA(0, 0, At, B0); PG8_MMA(0, 1, At, B1); PG8_BAR; PG8_SCHED;
;             PG8_LDA(At, 0, 1); PG8_STAGE(PG8_SB(0, 0), b2, voffB); PG8_STAGE(PG8_SB(0, 1), b2 + hstepB, voffB); PG8_STAGE(PG8_SA(0, 0), a2, voffA);
.LBB0_1361:
	ds_read_b128 v[144:147], v149
	ds_read_b128 v[152:155], v149 offset:1024
	ds_read_b128 v[156:159], v149 offset:2048
	ds_read_b128 v[160:163], v149 offset:3072
	ds_read_b128 v[168:171], v150
	ds_read_b128 v[172:175], v150 offset:1024
	ds_read_b128 v[176:179], v150 offset:2048
	ds_read_b128 v[180:183], v150 offset:3072
	s_add_u32 s22, s20, 0x100
	s_addc_u32 s23, s21, 0
	s_cmpk_eq_i32 s50, 0x54
	s_cselect_b32 s29, s9, s23
	s_cselect_b32 s28, s8, s22
	s_cselect_b32 s27, s19, s46
	s_cselect_b32 s26, s18, s45
	v_lshl_add_u64 v[164:165], s[20:21], 0, v[136:137]
	s_add_i32 m0, s25, 0xc000
	ds_read_b128 v[184:187], v151
	ds_read_b128 v[188:191], v151 offset:1024
	ds_read_b128 v[192:195], v151 offset:2048
	ds_read_b128 v[196:199], v151 offset:3072
	ds_read_b128 v[200:203], v151 offset:4096
	ds_read_b128 v[204:207], v151 offset:5120
	ds_read_b128 v[208:211], v151 offset:6144
	ds_read_b128 v[212:215], v151 offset:7168
	global_load_lds_dwordx4 v[164:165], off
	v_lshl_add_u64 v[164:165], s[20:21], 0, v[138:139]
	s_add_i32 m0, s25, 0xe000
	s_nop 0
	global_load_lds_dwordx4 v[164:165], off
	s_waitcnt vmcnt(8)
	s_waitcnt lgkmcnt(0)
	s_barrier
	s_setprio 1
	s_waitcnt lgkmcnt(0)
	v_mfma_f32_16x16x32_bf16 v[124:127], v[144:147], v[184:187], v[124:127]
	v_mfma_f32_16x16x32_bf16 v[120:123], v[156:159], v[184:187], v[120:123]
	v_mfma_f32_16x16x32_bf16 v[108:111], v[144:147], v[192:195], v[108:111]
	v_mfma_f32_16x16x32_bf16 v[104:107], v[156:159], v[192:195], v[104:107]
	v_mfma_f32_16x16x32_bf16 v[92:95], v[144:147], v[200:203], v[92:95]
	v_mfma_f32_16x16x32_bf16 v[88:91], v[156:159], v[200:203], v[88:91]
	v_mfma_f32_16x16x32_bf16 v[76:79], v[144:147], v[208:211], v[76:79]
	v_mfma_f32_16x16x32_bf16 v[72:75], v[156:159], v[208:211], v[72:75]
	v_mfma_f32_16x16x32_bf16 v[124:127], v[152:155], v[188:191], v[124:127]
	v_mfma_f32_16x16x32_bf16 v[120:123], v[160:163], v[188:191], v[120:123]
	v_mfma_f32_16x16x32_bf16 v[108:111], v[152:155], v[196:199], v[108:111]
	v_mfma_f32_16x16x32_bf16 v[104:107], v[160:163], v[196:199], v[104:107]
	v_mfma_f32_16x16x32_bf16 v[92:95], v[152:155], v[204:207], v[92:95]
	v_mfma_f32_16x16x32_bf16 v[88:91], v[160:163], v[204:207], v[88:91]
	v_mfma_f32_16x16x32_bf16 v[76:79], v[152:155], v[212:215], v[76:79]
	v_mfma_f32_16x16x32_bf16 v[72:75], v[160:163], v[212:215], v[72:75]
	v_mfma_f32_16x16x32_bf16 v[116:119], v[168:171], v[184:187], v[116:119]
	v_mfma_f32_16x16x32_bf16 v[112:115], v[176:179], v[184:187], v[112:115]
	v_mfma_f32_16x16x32_bf16 v[100:103], v[168:171], v[192:195], v[100:103]
	v_mfma_f32_16x16x32_bf16 v[96:99], v[176:179], v[192:195], v[96:99]
	v_mfma_f32_16x16x32_bf16 v[84:87], v[168:171], v[200:203], v[84:87]
	v_mfma_f32_16x16x32_bf16 v[80:83], v[176:179], v[200:203], v[80:83]
	v_mfma_f32_16x16x32_bf16 v[68:71], v[168:171], v[208:211], v[68:71]
	v_mfma_f32_16x16x32_bf16 v[64:67], v[176:179], v[208:211], v[64:67]
	v_mfma_f32_16x16x32_bf16 v[116:119], v[172:175], v[188:191], v[116:119]
	v_mfma_f32_16x16x32_bf16 v[112:115], v[180:183], v[188:191], v[112:115]
	v_mfma_f32_16x16x32_bf16 v[100:103], v[172:175], v[196:199], v[100:103]
	v_mfma_f32_16x16x32_bf16 v[96:99], v[180:183], v[196:199], v[96:99]
	v_mfma_f32_16x16x32_bf16 v[84:87], v[172:175], v[204:207], v[84:87]
	v_mfma_f32_16x16x32_bf16 v[80:83], v[180:183], v[204:207], v[80:83]
	v_mfma_f32_16x16x32_bf16 v[68:71], v[172:175], v[212:215], v[68:71]
	v_mfma_f32_16x16x32_bf16 v[64:67], v[180:183], v[212:215], v[64:67]
	s_setprio 0
	s_barrier
	s_add_i32 s4, s36, s47
	v_lshl_add_u64 v[164:165], s[26:27], 0, v[130:131]
	s_mov_b32 m0, s4
	ds_read_b128 v[184:187], v151 offset:16384
	ds_read_b128 v[188:191], v151 offset:17408
	ds_read_b128 v[192:195], v151 offset:18432
	ds_read_b128 v[196:199], v151 offset:19456
	ds_read_b128 v[200:203], v151 offset:20480
	ds_read_b128 v[204:207], v151 offset:21504
	ds_read_b128 v[208:211], v151 offset:22528
	ds_read_b128 v[212:215], v151 offset:23552
	global_load_lds_dwordx4 v[164:165], off
	s_add_i32 m0, s4, 0x2000
	s_add_u32 s4, s26, 0x160000
	v_lshl_add_u64 v[216:217], s[26:27], 0, v[134:135]
	s_addc_u32 s5, s27, 0
	s_add_i32 s20, s37, s47
	global_load_lds_dwordx4 v[216:217], off
	v_lshl_add_u64 v[218:219], s[4:5], 0, v[130:131]
	s_mov_b32 m0, s20
	v_lshl_add_u64 v[220:221], s[28:29], 0, v[132:133]
	global_load_lds_dwordx4 v[218:219], off
	v_lshl_add_u64 v[218:219], s[4:5], 0, v[134:135]
	s_add_i32 m0, s20, 0x2000
	s_nop 0
	global_load_lds_dwordx4 v[218:219], off
	v_lshl_add_u64 v[218:219], s[28:29], 0, v[128:129]
	s_mov_b32 m0, s25
	s_nop 0
	global_load_lds_dwordx4 v[218:219], off
	s_mov_b32 m0, s30
	s_nop 0
	global_load_lds_dwordx4 v[220:221], off
	s_waitcnt vmcnt(8)
	s_waitcnt lgkmcnt(0)
	s_barrier
; #define PG8_STAGE(bufoff, gbase, voff) do { _Pragma("unroll") for (int _i = 0; _i < 2; ++_i) \
;         __builtin_amdgcn_global_load_lds((const unsigned*)((const char*)(gbase) + (voff)[_i]), (PG8_LAS unsigned*)(lds + (bufoff) + ldsw + _i * 8192), 16, 0, 0); } while (0)
; #define PG8_LDA(dst, b, h) do { _Pragma("unroll") for (int m = 0; m < 4; ++m) _Pragma("unroll") for (int k = 0; k < 2; ++k) dst[m][k] = *(const PG8_LAS bf16x8*)(lds + PG8_SA(b, h) + aoff + m * 2048 + k * 1024); } while (0)
; #define PG8_LDB(dst, b, h) do { _Pragma("unroll") for (int n = 0; n < 2; ++n) _Pragma("unroll") for (int k = 0; k < 2; ++k) dst[n][k] = *(const PG8_LAS bf16x8*)(lds + PG8_SB(b, h) + boff + n * 2048 + k * 1024); } while (0)
; #define PG8_MMA(ai, bj, At, Bt) do { __builtin_amdgcn_s_setprio(1); _Pragma("unroll") for (int m = 0; m < 4; ++m) _Pragma("unroll") for (int n = 0; n < 2; ++n) _Pragma("unroll") for (int k = 0; k < 2; ++k) \
;         acc[ai][bj][m][n] = __builtin_amdgcn_mfma_f32_16x16x32_bf16(Bt[n][k], At[m][k], acc[ai][bj][m][n], 0, 0, 0); __builtin_amdgcn_s_setprio(0); } while (0)
; #define PG8_WAIT_V(n) asm volatile("s_waitcnt vmcnt(" #n ")" ::: "memory")
; #define PG8_WAIT_L(n) asm volatile("s_waitcnt lgkmcnt(" #n ")" ::: "memory")
; #define PG8_BAR __builtin_amdgcn_s_barrier()
; #define PG8_SCHED __builtin_amdgcn_sched_barrier(0)
; template <class Epi, class Sched, bool ALIGN_EPI = false, bool SP2 = false>
; __device__ __forceinline__ void gemm_phase(PG8_LAS unsigned char* lds, const Gemm g, const Sched& S, const Epi& E) {
;     ...
;             PG8_WAIT_V(8); PG8_WAIT_L(0); PG8_BAR; PG8_MMA(1, 0, At, B0); PG8_MMA(1, 1, At, B1); PG8_BAR; PG8_SCHED;
;             PG8_LDB(B0, 1, 0); PG8_LDB(B1, 1, 1); PG8_SCHED; PG8_LDA(At, 1, 0); PG8_STAGE(PG8_SA(0, 1), a2 + hstepA, voffA);
;             PG8_WAIT_V(8); PG8_WAIT_L(0); PG8_BAR; PG8_MMA(0, 0, At, B0); PG8_MMA(0, 1, At, B1); PG8_BAR; PG8_SCHED;
	s_setprio 1
	s_waitcnt lgkmcnt(0)
	v_mfma_f32_16x16x32_bf16 v[60:63], v[144:147], v[184:187], v[60:63]
	v_mfma_f32_16x16x32_bf16 v[56:59], v[156:159], v[184:187], v[56:59]
	v_mfma_f32_16x16x32_bf16 v[44:47], v[144:147], v[192:195], v[44:47]
	v_mfma_f32_16x16x32_bf16 v[40:43], v[156:159], v[192:195], v[40:43]
	v_mfma_f32_16x16x32_bf16 v[28:31], v[144:147], v[200:203], v[28:31]
	v_mfma_f32_16x16x32_bf16 v[24:27], v[156:159], v[200:203], v[24:27]
	v_mfma_f32_16x16x32_bf16 v[12:15], v[144:147], v[208:211], v[12:15]
	v_mfma_f32_16x16x32_bf16 v[8:11], v[156:159], v[208:211], v[8:11]
	v_mfma_f32_16x16x32_bf16 v[60:63], v[152:155], v[188:191], v[60:63]
	v_mfma_f32_16x16x32_bf16 v[56:59], v[160:163], v[188:191], v[56:59]
	v_mfma_f32_16x16x32_bf16 v[44:47], v[152:155], v[196:199], v[44:47]
	v_mfma_f32_16x16x32_bf16 v[40:43], v[160:163], v[196:199], v[40:43]
	v_mfma_f32_16x16x32_bf16 v[28:31], v[152:155], v[204:207], v[28:31]
	v_mfma_f32_16x16x32_bf16 v[24:27], v[160:163], v[204:207], v[24:27]
	v_mfma_f32_16x16x32_bf16 v[12:15], v[152:155], v[212:215], v[12:15]
	v_mfma_f32_16x16x32_bf16 v[8:11], v[160:163], v[212:215], v[8:11]
	v_mfma_f32_16x16x32_bf16 v[52:55], v[168:171], v[184:187], v[52:55]
	v_mfma_f32_16x16x32_bf16 v[48:51], v[176:179], v[184:187], v[48:51]
	v_mfma_f32_16x16x32_bf16 v[36:39], v[168:171], v[192:195], v[36:39]
	v_mfma_f32_16x16x32_bf16 v[32:35], v[176:179], v[192:195], v[32:35]
	v_mfma_f32_16x16x32_bf16 v[20:23], v[168:171], v[200:203], v[20:23]
	v_mfma_f32_16x16x32_bf16 v[16:19], v[176:179], v[200:203], v[16:19]
	v_mfma_f32_16x16x32_bf16 v[4:7], v[168:171], v[208:211], v[4:7]
	v_mfma_f32_16x16x32_bf16 v[0:3], v[176:179], v[208:211], v[0:3]
	v_mfma_f32_16x16x32_bf16 v[52:55], v[172:175], v[188:191], v[52:55]
	v_mfma_f32_16x16x32_bf16 v[48:51], v[180:183], v[188:191], v[48:51]
	v_mfma_f32_16x16x32_bf16 v[36:39], v[172:175], v[196:199], v[36:39]
	v_mfma_f32_16x16x32_bf16 v[32:35], v[180:183], v[196:199], v[32:35]
	v_mfma_f32_16x16x32_bf16 v[20:23], v[172:175], v[204:207], v[20:23]
	v_mfma_f32_16x16x32_bf16 v[16:19], v[180:183], v[204:207], v[16:19]
	v_mfma_f32_16x16x32_bf16 v[4:7], v[172:175], v[212:215], v[4:7]
	v_mfma_f32_16x16x32_bf16 v[0:3], v[180:183], v[212:215], v[0:3]
	s_setprio 0
	s_barrier
	s_add_i32 s20, 0, 0x18000
	s_add_i32 s21, 0, 0x1c000
	v_add_u32_e32 v160, s20, v148
	v_add_u32_e32 v166, s21, v148
	ds_read_b128 v[144:147], v160
	ds_read_b128 v[152:155], v160 offset:1024
	ds_read_b128 v[156:159], v160 offset:2048
	ds_read_b128 v[160:163], v160 offset:3072
	ds_read_b128 v[168:171], v166
	ds_read_b128 v[172:175], v166 offset:1024
	ds_read_b128 v[176:179], v166 offset:2048
	ds_read_b128 v[180:183], v166 offset:3072
	s_add_u32 s4, s28, 0x160000
	s_addc_u32 s5, s29, 0
	s_mov_b32 m0, s31
	v_lshl_add_u64 v[222:223], s[4:5], 0, v[128:129]
	ds_read_b128 v[184:187], v151 offset:32768
	ds_read_b128 v[188:191], v151 offset:33792
	ds_read_b128 v[192:195], v151 offset:34816
	ds_read_b128 v[196:199], v151 offset:35840
	ds_read_b128 v[200:203], v151 offset:36864
	ds_read_b128 v[204:207], v151 offset:37888
	ds_read_b128 v[208:211], v151 offset:38912
	ds_read_b128 v[212:215], v151 offset:39936
	global_load_lds_dwordx4 v[222:223], off
	v_lshl_add_u64 v[222:223], s[4:5], 0, v[132:133]
	s_mov_b32 m0, s33
	s_nop 0
	global_load_lds_dwordx4 v[222:223], off
	s_waitcnt vmcnt(8)
	s_waitcnt lgkmcnt(0)
	s_barrier
	s_setprio 1
	s_waitcnt lgkmcnt(0)
	v_mfma_f32_16x16x32_bf16 v[124:127], v[144:147], v[184:187], v[124:127]
	v_mfma_f32_16x16x32_bf16 v[120:123], v[156:159], v[184:187], v[120:123]
	v_mfma_f32_16x16x32_bf16 v[108:111], v[144:147], v[192:195], v[108:111]
	v_mfma_f32_16x16x32_bf16 v[104:107], v[156:159], v[192:195], v[104:107]
	v_mfma_f32_16x16x32_bf16 v[92:95], v[144:147], v[200:203], v[92:95]
	v_mfma_f32_16x16x32_bf16 v[88:91], v[156:159], v[200:203], v[88:91]
	v_mfma_f32_16x16x32_bf16 v[76:79], v[144:147], v[208:211], v[76:79]
	v_mfma_f32_16x16x32_bf16 v[72:75], v[156:159], v[208:211], v[72:75]
	v_mfma_f32_16x16x32_bf16 v[124:127], v[152:155], v[188:191], v[124:127]
	v_mfma_f32_16x16x32_bf16 v[120:123], v[160:163], v[188:191], v[120:123]
	v_mfma_f32_16x16x32_bf16 v[108:111], v[152:155], v[196:199], v[108:111]
	v_mfma_f32_16x16x32_bf16 v[104:107], v[160:163], v[196:199], v[104:107]
	v_mfma_f32_16x16x32_bf16 v[92:95], v[152:155], v[204:207], v[92:95]
	v_mfma_f32_16x16x32_bf16 v[88:91], v[160:163], v[204:207], v[88:91]
	v_mfma_f32_16x16x32_bf16 v[76:79], v[152:155], v[212:215], v[76:79]
	v_mfma_f32_16x16x32_bf16 v[72:75], v[160:163], v[212:215], v[72:75]
	v_mfma_f32_16x16x32_bf16 v[116:119], v[168:171], v[184:187], v[116:119]
	v_mfma_f32_16x16x32_bf16 v[112:115], v[176:179], v[184:187], v[112:115]
	v_mfma_f32_16x16x32_bf16 v[100:103], v[168:171], v[192:195], v[100:103]
	v_mfma_f32_16x16x32_bf16 v[96:99], v[176:179], v[192:195], v[96:99]
	v_mfma_f32_16x16x32_bf16 v[84:87], v[168:171], v[200:203], v[84:87]
	v_mfma_f32_16x16x32_bf16 v[80:83], v[176:179], v[200:203], v[80:83]
	v_mfma_f32_16x16x32_bf16 v[68:71], v[168:171], v[208:211], v[68:71]
	v_mfma_f32_16x16x32_bf16 v[64:67], v[176:179], v[208:211], v[64:67]
	v_mfma_f32_16x16x32_bf16 v[116:119], v[172:175], v[188:191], v[116:119]
	v_mfma_f32_16x16x32_bf16 v[112:115], v[180:183], v[188:191], v[112:115]
	v_mfma_f32_16x16x32_bf16 v[100:103], v[172:175], v[196:199], v[100:103]
	v_mfma_f32_16x16x32_bf16 v[96:99], v[180:183], v[196:199], v[96:99]
	v_mfma_f32_16x16x32_bf16 v[84:87], v[172:175], v[204:207], v[84:87]
	v_mfma_f32_16x16x32_bf16 v[80:83], v[180:183], v[204:207], v[80:83]
	v_mfma_f32_16x16x32_bf16 v[68:71], v[172:175], v[212:215], v[68:71]
	v_mfma_f32_16x16x32_bf16 v[64:67], v[180:183], v[212:215], v[64:67]
	s_setprio 0
	s_barrier
; #define PG8_STAGE(bufoff, gbase, voff) do { _Pragma("unroll") for (int _i = 0; _i < 2; ++_i) \
;         __builtin_amdgcn_global_load_lds((const unsigned*)((const char*)(gbase) + (voff)[_i]), (PG8_LAS unsigned*)(lds + (bufoff) + ldsw + _i * 8192), 16, 0, 0); } while (0)
; #define PG8_LDA(dst, b, h) do { _Pragma("unroll") for (int m = 0; m < 4; ++m) _Pragma("unroll") for (int k = 0; k < 2; ++k) dst[m][k] = *(const PG8_LAS bf16x8*)(lds + PG8_SA(b, h) + aoff + m * 2048 + k * 1024); } while (0)
; #define PG8_LDB(dst, b, h) do { _Pragma("unroll") for (int n = 0; n < 2; ++n) _Pragma("unroll") for (int k = 0; k < 2; ++k) dst[n][k] = *(const PG8_LAS bf16x8*)(lds + PG8_SB(b, h) + boff + n * 2048 + k * 1024); } while (0)
; #define PG8_MMA(ai, bj, At, Bt) do { __builtin_amdgcn_s_setprio(1); _Pragma("unroll") for (int m = 0; m < 4; ++m) _Pragma("unroll") for (int n = 0; n < 2; ++n) _Pragma("unroll") for (int k = 0; k < 2; ++k) \
;         acc[ai][bj][m][n] = __builtin_amdgcn_mfma_f32_16x16x32_bf16(Bt[n][k], At[m][k], acc[ai][bj][m][n], 0, 0, 0); __builtin_amdgcn_s_setprio(0); } while (0)
; #define PG8_WAIT_V(n) asm volatile("s_waitcnt vmcnt(" #n ")" ::: "memory")
; template <class Epi, class Sched, bool ALIGN_EPI = false, bool SP2 = false>
; __device__ __forceinline__ void gemm_phase(PG8_LAS unsigned char* lds, const Gemm g, const Sched& S, const Epi& E) {
;     ...
;             PG8_LDB(B0, 0, 0); PG8_LDB(B1, 0, 1); PG8_SCHED; PG8_LDA(At, 0, 0); PG8_STAGE(PG8_SA(1, 1), a1 + hstepA, voffA);
;             PG8_WAIT_V(8); PG8_WAIT_L(0); PG8_BAR; PG8_MMA(0, 0, At, B0); PG8_MMA(0, 1, At, B1); PG8_BAR; PG8_SCHED;
;             PG8_LDA(At, 0, 1); PG8_STAGE(PG8_SB(0, 0), b2, voffB); PG8_STAGE(PG8_SB(0, 1), b2 + hstepB, voffB); PG8_STAGE(PG8_SA(0, 0), a2, voffA);
;             PG8_WAIT_V(8); PG8_WAIT_L(0); PG8_BAR; PG8_MMA(1, 0, At, B0); PG8_MMA(1, 1, At, B1); PG8_BAR; PG8_SCHED;
;             PG8_LDB(B0, 1, 0); PG8_LDB(B1, 1, 1); PG8_SCHED; PG8_LDA(At, 1, 0); PG8_STAGE(PG8_SA(0, 1), a2 + hstepA, voffA);
;             PG8_WAIT_V(8); PG8_WAIT_L(0); PG8_BAR; PG8_MMA(0, 0, At, B0); PG8_MMA(0, 1, At, B1); PG8_BAR; PG8_SCHED;
;             PG8_LDA(At, 1, 1); PG8_STAGE(PG8_SB(1, 0), b3, voffB); PG8_STAGE(PG8_SB(1, 1), b3 + hstepB, voffB); PG8_STAGE(PG8_SA(1, 0), a3, voffA);
;             PG8_WAIT_V(8); PG8_WAIT_L(0); PG8_BAR; PG8_MMA(1, 0, At, B0); PG8_MMA(1, 1, At, B1); PG8_BAR; PG8_SCHED;
	s_add_i32 s4, s20, s47
	v_lshl_add_u64 v[164:165], v[164:165], 0, s[16:17]
	s_mov_b32 m0, s4
	ds_read_b128 v[184:187], v151 offset:49152
	ds_read_b128 v[188:191], v151 offset:50176
	ds_read_b128 v[192:195], v151 offset:51200
	ds_read_b128 v[196:199], v151 offset:52224
	ds_read_b128 v[200:203], v151 offset:53248
	ds_read_b128 v[204:207], v151 offset:54272
	ds_read_b128 v[208:211], v151 offset:55296
	ds_read_b128 v[212:215], v151 offset:56320
	global_load_lds_dwordx4 v[164:165], off
	s_add_i32 m0, s4, 0x2000
	s_add_u32 s4, s26, 0x160080
	v_lshl_add_u64 v[164:165], v[216:217], 0, s[16:17]
	s_addc_u32 s5, s27, 0
	s_add_i32 s20, s21, s47
	global_load_lds_dwordx4 v[164:165], off
	v_lshl_add_u64 v[164:165], s[4:5], 0, v[130:131]
	s_mov_b32 m0, s20
	s_nop 0
	global_load_lds_dwordx4 v[164:165], off
	v_lshl_add_u64 v[164:165], s[4:5], 0, v[134:135]
	s_add_i32 m0, s20, 0x2000
	s_nop 0
	global_load_lds_dwordx4 v[164:165], off
	v_lshl_add_u64 v[164:165], v[218:219], 0, s[16:17]
	s_mov_b32 m0, s34
	s_nop 0
	global_load_lds_dwordx4 v[164:165], off
	v_lshl_add_u64 v[164:165], v[220:221], 0, s[16:17]
	s_mov_b32 m0, s35
	s_nop 0
	global_load_lds_dwordx4 v[164:165], off
	s_waitcnt vmcnt(8)
	s_waitcnt lgkmcnt(0)
	s_barrier
	s_setprio 1
	s_waitcnt lgkmcnt(0)
	v_mfma_f32_16x16x32_bf16 v[60:63], v[144:147], v[184:187], v[60:63]
	v_mfma_f32_16x16x32_bf16 v[56:59], v[156:159], v[184:187], v[56:59]
	v_mfma_f32_16x16x32_bf16 v[44:47], v[144:147], v[192:195], v[44:47]
	v_mfma_f32_16x16x32_bf16 v[40:43], v[156:159], v[192:195], v[40:43]
	v_mfma_f32_16x16x32_bf16 v[28:31], v[144:147], v[200:203], v[28:31]
	v_mfma_f32_16x16x32_bf16 v[24:27], v[156:159], v[200:203], v[24:27]
	v_mfma_f32_16x16x32_bf16 v[12:15], v[144:147], v[208:211], v[12:15]
	v_mfma_f32_16x16x32_bf16 v[8:11], v[156:159], v[208:211], v[8:11]
	v_mfma_f32_16x16x32_bf16 v[60:63], v[152:155], v[188:191], v[60:63]
	v_mfma_f32_16x16x32_bf16 v[56:59], v[160:163], v[188:191], v[56:59]
	v_mfma_f32_16x16x32_bf16 v[44:47], v[152:155], v[196:199], v[44:47]
	v_mfma_f32_16x16x32_bf16 v[40:43], v[160:163], v[196:199], v[40:43]
	v_mfma_f32_16x16x32_bf16 v[28:31], v[152:155], v[204:207], v[28:31]
	v_mfma_f32_16x16x32_bf16 v[24:27], v[160:163], v[204:207], v[24:27]
	v_mfma_f32_16x16x32_bf16 v[12:15], v[152:155], v[212:215], v[12:15]
	v_mfma_f32_16x16x32_bf16 v[8:11], v[160:163], v[212:215], v[8:11]
	v_mfma_f32_16x16x32_bf16 v[52:55], v[168:171], v[184:187], v[52:55]
	v_mfma_f32_16x16x32_bf16 v[48:51], v[176:179], v[184:187], v[48:51]
	v_mfma_f32_16x16x32_bf16 v[36:39], v[168:171], v[192:195], v[36:39]
	v_mfma_f32_16x16x32_bf16 v[32:35], v[176:179], v[192:195], v[32:35]
	v_mfma_f32_16x16x32_bf16 v[20:23], v[168:171], v[200:203], v[20:23]
	v_mfma_f32_16x16x32_bf16 v[16:19], v[176:179], v[200:203], v[16:19]
	v_mfma_f32_16x16x32_bf16 v[4:7], v[168:171], v[208:211], v[4:7]
	v_mfma_f32_16x16x32_bf16 v[0:3], v[176:179], v[208:211], v[0:3]
	v_mfma_f32_16x16x32_bf16 v[52:55], v[172:175], v[188:191], v[52:55]
	v_mfma_f32_16x16x32_bf16 v[48:51], v[180:183], v[188:191], v[48:51]
	v_mfma_f32_16x16x32_bf16 v[36:39], v[172:175], v[196:199], v[36:39]
	v_mfma_f32_16x16x32_bf16 v[32:35], v[180:183], v[196:199], v[32:35]
	v_mfma_f32_16x16x32_bf16 v[20:23], v[172:175], v[204:207], v[20:23]
	v_mfma_f32_16x16x32_bf16 v[16:19], v[180:183], v[204:207], v[16:19]
	v_mfma_f32_16x16x32_bf16 v[4:7], v[172:175], v[212:215], v[4:7]
	v_mfma_f32_16x16x32_bf16 v[0:3], v[180:183], v[212:215], v[0:3]
	s_setprio 0
	s_barrier
	s_add_i32 s50, s50, 2
	s_add_u32 s45, s45, 0x100
	s_addc_u32 s46, s46, 0
	s_cmpk_gt_u32 s50, 0x55
	s_mov_b64 s[20:21], s[22:23]
	s_cbranch_scc0 .LBB0_1361
	s_and_b64 vcc, exec, s[48:49]
	s_cbranch_vccz .LBB0_1364
	s_barrier
